# GEMM epilogues: flat_load/flat_store replaced by global_load/global_store (same addresses); on top of scalar-base LDS-DMA K-loops
# speedup vs baseline: 1.0230x; 1.0027x over previous
; __device__ __forceinline__ unsigned cvt_pk_bf16(float lo, float hi) { unsigned r; asm volatile("v_cvt_pk_bf16_f32 %0, %1, %2" : "=v"(r) : "v"(lo), "v"(hi)); return r; }
;     __device__ __forceinline__ void operator()(const f32x4 (&acc)[2][2][4][2], const Unit& u, int wr, int wc, int fr, int fq) const {
;     ...
;         const bool sg = u.pn >= 58, zs = u.pn >= 18 && u.pn < 34;
;         const int col0 = u.pn * BM + wc * 32 + 8 * fq;
; #pragma unroll
;         for (int ai = 0; ai < 2; ++ai)
; #pragma unroll
;             for (int m = 0; m < 4; ++m) { bf16_t* rowp = O + (size_t)(row0 + ai * HALF + m * 16) * NPROJ + col0;
; #pragma unroll
;                 for (int bj = 0; bj < 2; ++bj) { f32x4 v0 = acc[ai][bj][m][0], v1 = acc[ai][bj][m][1];
;                     if (sg || zs) { f32x4 t0, t1;
; #pragma unroll
;                         for (int j = 0; j < 4; ++j) { t0[j] = __expf(-v0[j]); t1[j] = __expf(-v1[j]); }
; #pragma unroll
;                         for (int j = 0; j < 4; ++j) { t0[j] = __builtin_amdgcn_rcpf(1.f + t0[j]); t1[j] = __builtin_amdgcn_rcpf(1.f + t1[j]); }
;                         if (sg) { v0 = t0; v1 = t1; } else { v0 = v0 * t0; v1 = v1 * t1; } }
;                     u32x4 w; w.x = cvt_pk_bf16(v0[0], v0[1]); w.y = cvt_pk_bf16(v0[2], v0[3]); w.z = cvt_pk_bf16(v1[0], v1[1]); w.w = cvt_pk_bf16(v1[2], v1[3]);
;                     *(u32x4*)(rowp + bj * HALF) = w; } }
.LBB0_199:
	v_lshl_or_b32 v144, s33, 8, v150
	v_mov_b64_e32 v[146:147], s[4:5]
	v_ashrrev_i32_e32 v145, 31, v144
	v_mad_i64_i32 v[146:147], s[18:19], v142, s69, v[146:147]
	v_lshl_add_u64 v[146:147], v[144:145], 1, v[146:147]
	s_and_b64 vcc, exec, s[38:39]
	v_cvt_pk_bf16_f32 v158, v158, v157
	v_cvt_pk_bf16_f32 v159, v156, v155
	v_cvt_pk_bf16_f32 v160, v154, v153
	v_cvt_pk_bf16_f32 v161, v152, v143
	global_store_dwordx4 v[146:147], v[158:161], off
	s_cbranch_vccnz .LBB0_201
	v_mul_f32_e32 v152, 0xbfb8aa3b, v124
	v_mul_f32_e32 v143, 0xbfb8aa3b, v128
	v_exp_f32_e32 v153, v152
	v_mul_f32_e32 v152, 0xbfb8aa3b, v129
	v_exp_f32_e32 v143, v143
	v_exp_f32_e32 v155, v152
	v_mul_f32_e32 v152, 0xbfb8aa3b, v125
	v_exp_f32_e32 v156, v152
	v_mul_f32_e32 v152, 0xbfb8aa3b, v130
	v_exp_f32_e32 v157, v152
	v_mul_f32_e32 v152, 0xbfb8aa3b, v126
	v_exp_f32_e32 v158, v152
	v_mul_f32_e32 v152, 0xbfb8aa3b, v131
	v_exp_f32_e32 v159, v152
	v_mul_f32_e32 v152, 0xbfb8aa3b, v127
	v_add_f32_e32 v143, 1.0, v143
	v_exp_f32_e32 v160, v152
	v_rcp_f32_e32 v152, v143
	v_add_f32_e32 v143, 1.0, v153
	v_rcp_f32_e32 v154, v143
	v_add_f32_e32 v143, 1.0, v155
	v_add_f32_e32 v155, 1.0, v157
	v_rcp_f32_e32 v153, v143
	v_add_f32_e32 v143, 1.0, v156
	v_rcp_f32_e32 v156, v155
	v_add_f32_e32 v155, 1.0, v158
	v_rcp_f32_e32 v158, v155
	v_add_f32_e32 v155, 1.0, v159
	v_rcp_f32_e32 v157, v155
	v_add_f32_e32 v155, 1.0, v160
	v_rcp_f32_e32 v159, v155
	v_rcp_f32_e32 v155, v143
	v_pk_mul_f32 v[130:131], v[130:131], v[156:157]
	v_pk_mul_f32 v[128:129], v[128:129], v[152:153]
	v_pk_mul_f32 v[126:127], v[126:127], v[158:159]
	v_pk_mul_f32 v[124:125], v[124:125], v[154:155]
	v_cndmask_b32_e64 v128, v128, v152, s[36:37]
	v_cndmask_b32_e64 v129, v129, v153, s[36:37]
	v_cndmask_b32_e64 v130, v130, v156, s[36:37]
	v_cndmask_b32_e64 v131, v131, v157, s[36:37]
	v_cndmask_b32_e64 v124, v124, v154, s[36:37]
	v_cndmask_b32_e64 v125, v125, v155, s[36:37]
	v_cndmask_b32_e64 v126, v126, v158, s[36:37]
	v_cndmask_b32_e64 v127, v127, v159, s[36:37]
.LBB0_201:
	v_cvt_pk_bf16_f32 v128, v128, v129
	v_cvt_pk_bf16_f32 v129, v130, v131
	v_cvt_pk_bf16_f32 v130, v124, v125
	v_cvt_pk_bf16_f32 v131, v126, v127
	global_store_dwordx4 v[146:147], v[128:131], off offset:256
	s_and_b64 vcc, exec, s[38:39]
	v_mov_b32_e32 v126, v63
	v_mov_b32_e32 v127, v62
	v_mov_b32_e32 v128, v61
	v_mov_b32_e32 v129, v60
	v_mov_b32_e32 v130, v67
	v_mov_b32_e32 v131, v66
	v_mov_b32_e32 v143, v65
	v_mov_b32_e32 v146, v64
	s_cbranch_vccnz .LBB0_203
	v_mul_f32_e32 v126, 0xbfb8aa3b, v65
	v_exp_f32_e32 v127, v126
	v_mul_f32_e32 v126, 0xbfb8aa3b, v61
	v_exp_f32_e32 v128, v126
	v_mul_f32_e32 v126, 0xbfb8aa3b, v66
	v_mul_f32_e32 v125, 0xbfb8aa3b, v60
	v_exp_f32_e32 v129, v126
	v_mul_f32_e32 v126, 0xbfb8aa3b, v62
	v_exp_f32_e32 v125, v125
	v_exp_f32_e32 v130, v126
	v_mul_f32_e32 v126, 0xbfb8aa3b, v67
	v_mul_f32_e32 v124, 0xbfb8aa3b, v64
	v_exp_f32_e32 v131, v126
	v_mul_f32_e32 v126, 0xbfb8aa3b, v63
	v_exp_f32_e32 v124, v124
	v_exp_f32_e32 v143, v126
	v_add_f32_e32 v125, 1.0, v125
	v_rcp_f32_e32 v126, v125
	v_add_f32_e32 v125, 1.0, v127
	v_add_f32_e32 v127, 1.0, v128
	v_add_f32_e32 v128, 1.0, v129
	v_add_f32_e32 v129, 1.0, v130
	v_add_f32_e32 v124, 1.0, v124
	v_rcp_f32_e32 v152, v129
	v_add_f32_e32 v129, 1.0, v131
	v_add_f32_e32 v130, 1.0, v143
	v_rcp_f32_e32 v124, v124
	v_rcp_f32_e32 v125, v125
	v_rcp_f32_e32 v128, v128
	v_rcp_f32_e32 v129, v129
	v_rcp_f32_e32 v153, v130
	v_rcp_f32_e32 v127, v127
	v_pk_mul_f32 v[130:131], v[64:65], v[124:125]
	v_pk_mul_f32 v[154:155], v[66:67], v[128:129]
	v_pk_mul_f32 v[156:157], v[62:63], v[152:153]
	v_pk_mul_f32 v[158:159], v[60:61], v[126:127]
	v_cndmask_b32_e64 v146, v130, v124, s[36:37]
	v_cndmask_b32_e64 v143, v131, v125, s[36:37]
	v_cndmask_b32_e64 v131, v154, v128, s[36:37]
	v_cndmask_b32_e64 v130, v155, v129, s[36:37]
	v_cndmask_b32_e64 v129, v158, v126, s[36:37]
	v_cndmask_b32_e64 v128, v159, v127, s[36:37]
	v_cndmask_b32_e64 v127, v156, v152, s[36:37]
	v_cndmask_b32_e64 v126, v157, v153, s[36:37]
.LBB0_203:
	v_or_b32_e32 v147, 16, v142
	v_mov_b64_e32 v[124:125], s[4:5]
	v_mad_i64_i32 v[124:125], s[18:19], v147, s69, v[124:125]
	v_lshl_add_u64 v[124:125], v[144:145], 1, v[124:125]
	s_and_b64 vcc, exec, s[38:39]
	v_cvt_pk_bf16_f32 v152, v146, v143
	v_cvt_pk_bf16_f32 v153, v131, v130
	v_cvt_pk_bf16_f32 v154, v129, v128
	v_cvt_pk_bf16_f32 v155, v127, v126
	global_store_dwordx4 v[124:125], v[152:155], off
	s_cbranch_vccnz .LBB0_205
	v_mul_f32_e32 v128, 0xbfb8aa3b, v121
	v_exp_f32_e32 v129, v128
	v_mul_f32_e32 v128, 0xbfb8aa3b, v117
	v_exp_f32_e32 v130, v128
	v_mul_f32_e32 v128, 0xbfb8aa3b, v122
	v_mul_f32_e32 v127, 0xbfb8aa3b, v116
	v_exp_f32_e32 v131, v128
	v_mul_f32_e32 v128, 0xbfb8aa3b, v118
	v_exp_f32_e32 v127, v127
	v_exp_f32_e32 v143, v128
	v_mul_f32_e32 v128, 0xbfb8aa3b, v123
	v_mul_f32_e32 v126, 0xbfb8aa3b, v120
	v_exp_f32_e32 v147, v128
	v_mul_f32_e32 v128, 0xbfb8aa3b, v119
	v_exp_f32_e32 v126, v126
	v_exp_f32_e32 v152, v128
	v_add_f32_e32 v127, 1.0, v127
	v_rcp_f32_e32 v128, v127
	v_add_f32_e32 v127, 1.0, v129
	v_add_f32_e32 v129, 1.0, v130
	v_add_f32_e32 v130, 1.0, v131
	v_add_f32_e32 v131, 1.0, v143
	v_add_f32_e32 v126, 1.0, v126
	v_rcp_f32_e32 v146, v131
	v_add_f32_e32 v131, 1.0, v147
	v_add_f32_e32 v143, 1.0, v152
	v_rcp_f32_e32 v126, v126
	v_rcp_f32_e32 v127, v127
	v_rcp_f32_e32 v130, v130
	v_rcp_f32_e32 v131, v131
	v_rcp_f32_e32 v147, v143
	v_rcp_f32_e32 v129, v129
	v_pk_mul_f32 v[120:121], v[120:121], v[126:127]
	v_pk_mul_f32 v[122:123], v[122:123], v[130:131]
	v_pk_mul_f32 v[118:119], v[118:119], v[146:147]
	v_pk_mul_f32 v[116:117], v[116:117], v[128:129]
	v_cndmask_b32_e64 v120, v120, v126, s[36:37]
	v_cndmask_b32_e64 v121, v121, v127, s[36:37]
	v_cndmask_b32_e64 v122, v122, v130, s[36:37]
	v_cndmask_b32_e64 v123, v123, v131, s[36:37]
	v_cndmask_b32_e64 v116, v116, v128, s[36:37]
	v_cndmask_b32_e64 v117, v117, v129, s[36:37]
	v_cndmask_b32_e64 v118, v118, v146, s[36:37]
	v_cndmask_b32_e64 v119, v119, v147, s[36:37]
; __device__ __forceinline__ unsigned cvt_pk_bf16(float lo, float hi) { unsigned r; asm volatile("v_cvt_pk_bf16_f32 %0, %1, %2" : "=v"(r) : "v"(lo), "v"(hi)); return r; }
;     __device__ __forceinline__ void operator()(const f32x4 (&acc)[2][2][4][2], const Unit& u, int wr, int wc, int fr, int fq) const {
;     ...
;             for (int m = 0; m < 4; ++m) { bf16_t* rowp = O + (size_t)(row0 + ai * HALF + m * 16) * NPROJ + col0;
; #pragma unroll
;                 for (int bj = 0; bj < 2; ++bj) { f32x4 v0 = acc[ai][bj][m][0], v1 = acc[ai][bj][m][1];
;                     if (sg || zs) { f32x4 t0, t1;
; #pragma unroll
;                         for (int j = 0; j < 4; ++j) { t0[j] = __expf(-v0[j]); t1[j] = __expf(-v1[j]); }
; #pragma unroll
;                         for (int j = 0; j < 4; ++j) { t0[j] = __builtin_amdgcn_rcpf(1.f + t0[j]); t1[j] = __builtin_amdgcn_rcpf(1.f + t1[j]); }
;                         if (sg) { v0 = t0; v1 = t1; } else { v0 = v0 * t0; v1 = v1 * t1; } }
;                     u32x4 w; w.x = cvt_pk_bf16(v0[0], v0[1]); w.y = cvt_pk_bf16(v0[2], v0[3]); w.z = cvt_pk_bf16(v1[0], v1[1]); w.w = cvt_pk_bf16(v1[2], v1[3]);
;                     *(u32x4*)(rowp + bj * HALF) = w; } }
.LBB0_205:
	v_cvt_pk_bf16_f32 v120, v120, v121
	v_cvt_pk_bf16_f32 v121, v122, v123
	v_cvt_pk_bf16_f32 v122, v116, v117
	v_cvt_pk_bf16_f32 v123, v118, v119
	global_store_dwordx4 v[124:125], v[120:123], off offset:256
	s_and_b64 vcc, exec, s[38:39]
	v_mov_b32_e32 v118, v55
	v_mov_b32_e32 v119, v54
	v_mov_b32_e32 v120, v53
	v_mov_b32_e32 v121, v52
	v_mov_b32_e32 v122, v59
	v_mov_b32_e32 v123, v58
	v_mov_b32_e32 v124, v57
	v_mov_b32_e32 v125, v56
	s_cbranch_vccnz .LBB0_207
	v_mul_f32_e32 v118, 0xbfb8aa3b, v57
	v_exp_f32_e32 v119, v118
	v_mul_f32_e32 v118, 0xbfb8aa3b, v53
	v_exp_f32_e32 v120, v118
	v_mul_f32_e32 v118, 0xbfb8aa3b, v58
	v_mul_f32_e32 v117, 0xbfb8aa3b, v52
	v_exp_f32_e32 v121, v118
	v_mul_f32_e32 v118, 0xbfb8aa3b, v54
	v_exp_f32_e32 v117, v117
	v_exp_f32_e32 v122, v118
	v_mul_f32_e32 v118, 0xbfb8aa3b, v59
	v_mul_f32_e32 v116, 0xbfb8aa3b, v56
	v_exp_f32_e32 v123, v118
	v_mul_f32_e32 v118, 0xbfb8aa3b, v55
	v_exp_f32_e32 v116, v116
	v_exp_f32_e32 v124, v118
	v_add_f32_e32 v117, 1.0, v117
	v_rcp_f32_e32 v118, v117
	v_add_f32_e32 v117, 1.0, v119
	v_add_f32_e32 v119, 1.0, v120
	v_add_f32_e32 v120, 1.0, v121
	v_add_f32_e32 v121, 1.0, v122
	v_add_f32_e32 v116, 1.0, v116
	v_rcp_f32_e32 v126, v121
	v_add_f32_e32 v121, 1.0, v123
	v_add_f32_e32 v122, 1.0, v124
	v_rcp_f32_e32 v116, v116
	v_rcp_f32_e32 v117, v117
	v_rcp_f32_e32 v120, v120
	v_rcp_f32_e32 v121, v121
	v_rcp_f32_e32 v127, v122
	v_rcp_f32_e32 v119, v119
	v_pk_mul_f32 v[122:123], v[56:57], v[116:117]
	v_pk_mul_f32 v[128:129], v[58:59], v[120:121]
	v_pk_mul_f32 v[130:131], v[54:55], v[126:127]
	v_pk_mul_f32 v[146:147], v[52:53], v[118:119]
	v_cndmask_b32_e64 v125, v122, v116, s[36:37]
	v_cndmask_b32_e64 v124, v123, v117, s[36:37]
	v_cndmask_b32_e64 v123, v128, v120, s[36:37]
	v_cndmask_b32_e64 v122, v129, v121, s[36:37]
	v_cndmask_b32_e64 v121, v146, v118, s[36:37]
	v_cndmask_b32_e64 v120, v147, v119, s[36:37]
	v_cndmask_b32_e64 v119, v130, v126, s[36:37]
	v_cndmask_b32_e64 v118, v131, v127, s[36:37]
.LBB0_207:
	v_or_b32_e32 v126, 32, v142
	v_mov_b64_e32 v[116:117], s[4:5]
	v_mad_i64_i32 v[116:117], s[18:19], v126, s69, v[116:117]
	v_lshl_add_u64 v[116:117], v[144:145], 1, v[116:117]
	s_and_b64 vcc, exec, s[38:39]
	v_cvt_pk_bf16_f32 v124, v125, v124
	v_cvt_pk_bf16_f32 v125, v123, v122
	v_cvt_pk_bf16_f32 v126, v121, v120
	v_cvt_pk_bf16_f32 v127, v119, v118
	global_store_dwordx4 v[116:117], v[124:127], off
	s_cbranch_vccnz .LBB0_209
	v_mul_f32_e32 v120, 0xbfb8aa3b, v113
	v_exp_f32_e32 v121, v120
	v_mul_f32_e32 v120, 0xbfb8aa3b, v109
	v_exp_f32_e32 v122, v120
	v_mul_f32_e32 v120, 0xbfb8aa3b, v114
	v_mul_f32_e32 v119, 0xbfb8aa3b, v108
	v_exp_f32_e32 v123, v120
	v_mul_f32_e32 v120, 0xbfb8aa3b, v110
	v_exp_f32_e32 v119, v119
	v_exp_f32_e32 v124, v120
	v_mul_f32_e32 v120, 0xbfb8aa3b, v115
	v_mul_f32_e32 v118, 0xbfb8aa3b, v112
	v_exp_f32_e32 v125, v120
	v_mul_f32_e32 v120, 0xbfb8aa3b, v111
	v_exp_f32_e32 v118, v118
	v_exp_f32_e32 v126, v120
	v_add_f32_e32 v119, 1.0, v119
	v_rcp_f32_e32 v120, v119
	v_add_f32_e32 v119, 1.0, v121
	v_add_f32_e32 v121, 1.0, v122
	v_add_f32_e32 v122, 1.0, v123
	v_add_f32_e32 v123, 1.0, v124
	v_add_f32_e32 v118, 1.0, v118
	v_rcp_f32_e32 v124, v123
	v_add_f32_e32 v123, 1.0, v125
	v_add_f32_e32 v125, 1.0, v126
	v_rcp_f32_e32 v118, v118
	v_rcp_f32_e32 v119, v119
	v_rcp_f32_e32 v122, v122
	v_rcp_f32_e32 v123, v123
	v_rcp_f32_e32 v125, v125
	v_rcp_f32_e32 v121, v121
	v_pk_mul_f32 v[112:113], v[112:113], v[118:119]
	v_pk_mul_f32 v[114:115], v[114:115], v[122:123]
	v_pk_mul_f32 v[110:111], v[110:111], v[124:125]
	v_pk_mul_f32 v[108:109], v[108:109], v[120:121]
	v_cndmask_b32_e64 v112, v112, v118, s[36:37]
	v_cndmask_b32_e64 v113, v113, v119, s[36:37]
	v_cndmask_b32_e64 v114, v114, v122, s[36:37]
	v_cndmask_b32_e64 v115, v115, v123, s[36:37]
	v_cndmask_b32_e64 v108, v108, v120, s[36:37]
	v_cndmask_b32_e64 v109, v109, v121, s[36:37]
	v_cndmask_b32_e64 v110, v110, v124, s[36:37]
	v_cndmask_b32_e64 v111, v111, v125, s[36:37]
.LBB0_209:
	v_cvt_pk_bf16_f32 v112, v112, v113
	v_cvt_pk_bf16_f32 v113, v114, v115
	v_cvt_pk_bf16_f32 v114, v108, v109
	v_cvt_pk_bf16_f32 v115, v110, v111
	global_store_dwordx4 v[116:117], v[112:115], off offset:256
	s_and_b64 vcc, exec, s[38:39]
	v_mov_b32_e32 v110, v47
	v_mov_b32_e32 v111, v46
	v_mov_b32_e32 v112, v45
	v_mov_b32_e32 v113, v44
	v_mov_b32_e32 v114, v51
	v_mov_b32_e32 v115, v50
	v_mov_b32_e32 v116, v49
	v_mov_b32_e32 v117, v48
	s_cbranch_vccnz .LBB0_211
	v_mul_f32_e32 v110, 0xbfb8aa3b, v49
	v_exp_f32_e32 v111, v110
	v_mul_f32_e32 v110, 0xbfb8aa3b, v45
	v_exp_f32_e32 v112, v110
	v_mul_f32_e32 v110, 0xbfb8aa3b, v50
	v_mul_f32_e32 v109, 0xbfb8aa3b, v44
	v_exp_f32_e32 v113, v110
	v_mul_f32_e32 v110, 0xbfb8aa3b, v46
	v_exp_f32_e32 v109, v109
	v_exp_f32_e32 v114, v110
	v_mul_f32_e32 v110, 0xbfb8aa3b, v51
	v_mul_f32_e32 v108, 0xbfb8aa3b, v48
	v_exp_f32_e32 v115, v110
	v_mul_f32_e32 v110, 0xbfb8aa3b, v47
	v_exp_f32_e32 v108, v108
	v_exp_f32_e32 v116, v110
	v_add_f32_e32 v109, 1.0, v109
	v_rcp_f32_e32 v110, v109
	v_add_f32_e32 v109, 1.0, v111
	v_add_f32_e32 v111, 1.0, v112
	v_add_f32_e32 v112, 1.0, v113
	v_add_f32_e32 v113, 1.0, v114
	v_add_f32_e32 v108, 1.0, v108
	v_rcp_f32_e32 v118, v113
	v_add_f32_e32 v113, 1.0, v115
	v_add_f32_e32 v114, 1.0, v116
	v_rcp_f32_e32 v108, v108
	v_rcp_f32_e32 v109, v109
	v_rcp_f32_e32 v112, v112
	v_rcp_f32_e32 v113, v113
	v_rcp_f32_e32 v119, v114
	v_rcp_f32_e32 v111, v111
	v_pk_mul_f32 v[114:115], v[48:49], v[108:109]
	v_pk_mul_f32 v[120:121], v[50:51], v[112:113]
	v_pk_mul_f32 v[122:123], v[46:47], v[118:119]
	v_pk_mul_f32 v[124:125], v[44:45], v[110:111]
	v_cndmask_b32_e64 v117, v114, v108, s[36:37]
	v_cndmask_b32_e64 v116, v115, v109, s[36:37]
	v_cndmask_b32_e64 v115, v120, v112, s[36:37]
	v_cndmask_b32_e64 v114, v121, v113, s[36:37]
	v_cndmask_b32_e64 v113, v124, v110, s[36:37]
	v_cndmask_b32_e64 v112, v125, v111, s[36:37]
	v_cndmask_b32_e64 v111, v122, v118, s[36:37]
	v_cndmask_b32_e64 v110, v123, v119, s[36:37]
; __device__ __forceinline__ unsigned cvt_pk_bf16(float lo, float hi) { unsigned r; asm volatile("v_cvt_pk_bf16_f32 %0, %1, %2" : "=v"(r) : "v"(lo), "v"(hi)); return r; }
;     __device__ __forceinline__ void operator()(const f32x4 (&acc)[2][2][4][2], const Unit& u, int wr, int wc, int fr, int fq) const {
;     ...
;             for (int m = 0; m < 4; ++m) { bf16_t* rowp = O + (size_t)(row0 + ai * HALF + m * 16) * NPROJ + col0;
; #pragma unroll
;                 for (int bj = 0; bj < 2; ++bj) { f32x4 v0 = acc[ai][bj][m][0], v1 = acc[ai][bj][m][1];
;                     if (sg || zs) { f32x4 t0, t1;
; #pragma unroll
;                         for (int j = 0; j < 4; ++j) { t0[j] = __expf(-v0[j]); t1[j] = __expf(-v1[j]); }
; #pragma unroll
;                         for (int j = 0; j < 4; ++j) { t0[j] = __builtin_amdgcn_rcpf(1.f + t0[j]); t1[j] = __builtin_amdgcn_rcpf(1.f + t1[j]); }
;                         if (sg) { v0 = t0; v1 = t1; } else { v0 = v0 * t0; v1 = v1 * t1; } }
;                     u32x4 w; w.x = cvt_pk_bf16(v0[0], v0[1]); w.y = cvt_pk_bf16(v0[2], v0[3]); w.z = cvt_pk_bf16(v1[0], v1[1]); w.w = cvt_pk_bf16(v1[2], v1[3]);
;                     *(u32x4*)(rowp + bj * HALF) = w; } }
.LBB0_211:
	v_or_b32_e32 v118, 48, v142
	v_mov_b64_e32 v[108:109], s[4:5]
	v_mad_i64_i32 v[108:109], s[18:19], v118, s69, v[108:109]
	v_lshl_add_u64 v[108:109], v[144:145], 1, v[108:109]
	s_and_b64 vcc, exec, s[38:39]
	v_cvt_pk_bf16_f32 v116, v117, v116
	v_cvt_pk_bf16_f32 v117, v115, v114
	v_cvt_pk_bf16_f32 v118, v113, v112
	v_cvt_pk_bf16_f32 v119, v111, v110
	global_store_dwordx4 v[108:109], v[116:119], off
	s_cbranch_vccnz .LBB0_213
	v_mul_f32_e32 v112, 0xbfb8aa3b, v105
	v_exp_f32_e32 v113, v112
	v_mul_f32_e32 v112, 0xbfb8aa3b, v101
	v_exp_f32_e32 v114, v112
	v_mul_f32_e32 v112, 0xbfb8aa3b, v106
	v_mul_f32_e32 v111, 0xbfb8aa3b, v100
	v_exp_f32_e32 v115, v112
	v_mul_f32_e32 v112, 0xbfb8aa3b, v102
	v_exp_f32_e32 v111, v111
	v_exp_f32_e32 v116, v112
	v_mul_f32_e32 v112, 0xbfb8aa3b, v107
	v_mul_f32_e32 v110, 0xbfb8aa3b, v104
	v_exp_f32_e32 v117, v112
	v_mul_f32_e32 v112, 0xbfb8aa3b, v103
	v_exp_f32_e32 v110, v110
	v_exp_f32_e32 v118, v112
	v_add_f32_e32 v111, 1.0, v111
	v_rcp_f32_e32 v112, v111
	v_add_f32_e32 v111, 1.0, v113
	v_add_f32_e32 v113, 1.0, v114
	v_add_f32_e32 v114, 1.0, v115
	v_add_f32_e32 v115, 1.0, v116
	v_add_f32_e32 v110, 1.0, v110
	v_rcp_f32_e32 v116, v115
	v_add_f32_e32 v115, 1.0, v117
	v_add_f32_e32 v117, 1.0, v118
	v_rcp_f32_e32 v110, v110
	v_rcp_f32_e32 v111, v111
	v_rcp_f32_e32 v114, v114
	v_rcp_f32_e32 v115, v115
	v_rcp_f32_e32 v117, v117
	v_rcp_f32_e32 v113, v113
	v_pk_mul_f32 v[104:105], v[104:105], v[110:111]
	v_pk_mul_f32 v[106:107], v[106:107], v[114:115]
	v_pk_mul_f32 v[102:103], v[102:103], v[116:117]
	v_pk_mul_f32 v[100:101], v[100:101], v[112:113]
	v_cndmask_b32_e64 v104, v104, v110, s[36:37]
	v_cndmask_b32_e64 v105, v105, v111, s[36:37]
	v_cndmask_b32_e64 v106, v106, v114, s[36:37]
	v_cndmask_b32_e64 v107, v107, v115, s[36:37]
	v_cndmask_b32_e64 v100, v100, v112, s[36:37]
	v_cndmask_b32_e64 v101, v101, v113, s[36:37]
	v_cndmask_b32_e64 v102, v102, v116, s[36:37]
	v_cndmask_b32_e64 v103, v103, v117, s[36:37]
.LBB0_213:
	v_cvt_pk_bf16_f32 v104, v104, v105
	v_cvt_pk_bf16_f32 v105, v106, v107
	v_cvt_pk_bf16_f32 v106, v100, v101
	v_cvt_pk_bf16_f32 v107, v102, v103
	global_store_dwordx4 v[108:109], v[104:107], off offset:256
	s_and_b64 vcc, exec, s[38:39]
	v_mov_b32_e32 v102, v31
	v_mov_b32_e32 v103, v30
	v_mov_b32_e32 v104, v29
	v_mov_b32_e32 v105, v28
	v_mov_b32_e32 v106, v35
	v_mov_b32_e32 v107, v34
	v_mov_b32_e32 v108, v33
	v_mov_b32_e32 v109, v32
	s_cbranch_vccnz .LBB0_215
	v_mul_f32_e32 v102, 0xbfb8aa3b, v33
	v_exp_f32_e32 v103, v102
	v_mul_f32_e32 v102, 0xbfb8aa3b, v29
	v_exp_f32_e32 v104, v102
	v_mul_f32_e32 v102, 0xbfb8aa3b, v34
	v_mul_f32_e32 v101, 0xbfb8aa3b, v28
	v_exp_f32_e32 v105, v102
	v_mul_f32_e32 v102, 0xbfb8aa3b, v30
	v_exp_f32_e32 v101, v101
	v_exp_f32_e32 v106, v102
	v_mul_f32_e32 v102, 0xbfb8aa3b, v35
	v_mul_f32_e32 v100, 0xbfb8aa3b, v32
	v_exp_f32_e32 v107, v102
	v_mul_f32_e32 v102, 0xbfb8aa3b, v31
	v_exp_f32_e32 v100, v100
	v_exp_f32_e32 v108, v102
	v_add_f32_e32 v101, 1.0, v101
	v_rcp_f32_e32 v102, v101
	v_add_f32_e32 v101, 1.0, v103
	v_add_f32_e32 v103, 1.0, v104
	v_add_f32_e32 v104, 1.0, v105
	v_add_f32_e32 v105, 1.0, v106
	v_add_f32_e32 v100, 1.0, v100
	v_rcp_f32_e32 v110, v105
	v_add_f32_e32 v105, 1.0, v107
	v_add_f32_e32 v106, 1.0, v108
	v_rcp_f32_e32 v100, v100
	v_rcp_f32_e32 v101, v101
	v_rcp_f32_e32 v104, v104
	v_rcp_f32_e32 v105, v105
	v_rcp_f32_e32 v111, v106
	v_rcp_f32_e32 v103, v103
	v_pk_mul_f32 v[106:107], v[32:33], v[100:101]
	v_pk_mul_f32 v[112:113], v[34:35], v[104:105]
	v_pk_mul_f32 v[114:115], v[30:31], v[110:111]
	v_pk_mul_f32 v[116:117], v[28:29], v[102:103]
	v_cndmask_b32_e64 v109, v106, v100, s[36:37]
	v_cndmask_b32_e64 v108, v107, v101, s[36:37]
	v_cndmask_b32_e64 v107, v112, v104, s[36:37]
	v_cndmask_b32_e64 v106, v113, v105, s[36:37]
	v_cndmask_b32_e64 v105, v116, v102, s[36:37]
	v_cndmask_b32_e64 v104, v117, v103, s[36:37]
	v_cndmask_b32_e64 v103, v114, v110, s[36:37]
	v_cndmask_b32_e64 v102, v115, v111, s[36:37]
.LBB0_215:
	v_add_u32_e32 v110, 0x80, v142
	v_mov_b64_e32 v[100:101], s[4:5]
	v_mad_i64_i32 v[100:101], s[18:19], v110, s69, v[100:101]
	v_lshl_add_u64 v[100:101], v[144:145], 1, v[100:101]
	s_and_b64 vcc, exec, s[38:39]
	v_cvt_pk_bf16_f32 v108, v109, v108
	v_cvt_pk_bf16_f32 v109, v107, v106
	v_cvt_pk_bf16_f32 v110, v105, v104
	v_cvt_pk_bf16_f32 v111, v103, v102
	global_store_dwordx4 v[100:101], v[108:111], off
	s_cbranch_vccnz .LBB0_217
	v_mul_f32_e32 v104, 0xbfb8aa3b, v97
	v_exp_f32_e32 v105, v104
	v_mul_f32_e32 v104, 0xbfb8aa3b, v93
	v_exp_f32_e32 v106, v104
	v_mul_f32_e32 v104, 0xbfb8aa3b, v98
	v_mul_f32_e32 v103, 0xbfb8aa3b, v92
	v_exp_f32_e32 v107, v104
	v_mul_f32_e32 v104, 0xbfb8aa3b, v94
	v_exp_f32_e32 v103, v103
	v_exp_f32_e32 v108, v104
	v_mul_f32_e32 v104, 0xbfb8aa3b, v99
	v_mul_f32_e32 v102, 0xbfb8aa3b, v96
	v_exp_f32_e32 v109, v104
	v_mul_f32_e32 v104, 0xbfb8aa3b, v95
	v_exp_f32_e32 v102, v102
	v_exp_f32_e32 v110, v104
	v_add_f32_e32 v103, 1.0, v103
	v_rcp_f32_e32 v104, v103
	v_add_f32_e32 v103, 1.0, v105
	v_add_f32_e32 v105, 1.0, v106
	v_add_f32_e32 v106, 1.0, v107
	v_add_f32_e32 v107, 1.0, v108
	v_add_f32_e32 v102, 1.0, v102
	v_rcp_f32_e32 v108, v107
	v_add_f32_e32 v107, 1.0, v109
	v_add_f32_e32 v109, 1.0, v110
	v_rcp_f32_e32 v102, v102
	v_rcp_f32_e32 v103, v103
	v_rcp_f32_e32 v106, v106
	v_rcp_f32_e32 v107, v107
	v_rcp_f32_e32 v109, v109
	v_rcp_f32_e32 v105, v105
	v_pk_mul_f32 v[96:97], v[96:97], v[102:103]
	v_pk_mul_f32 v[98:99], v[98:99], v[106:107]
	v_pk_mul_f32 v[94:95], v[94:95], v[108:109]
	v_pk_mul_f32 v[92:93], v[92:93], v[104:105]
	v_cndmask_b32_e64 v96, v96, v102, s[36:37]
	v_cndmask_b32_e64 v97, v97, v103, s[36:37]
	v_cndmask_b32_e64 v98, v98, v106, s[36:37]
	v_cndmask_b32_e64 v99, v99, v107, s[36:37]
	v_cndmask_b32_e64 v92, v92, v104, s[36:37]
	v_cndmask_b32_e64 v93, v93, v105, s[36:37]
	v_cndmask_b32_e64 v94, v94, v108, s[36:37]
	v_cndmask_b32_e64 v95, v95, v109, s[36:37]
; __device__ __forceinline__ unsigned cvt_pk_bf16(float lo, float hi) { unsigned r; asm volatile("v_cvt_pk_bf16_f32 %0, %1, %2" : "=v"(r) : "v"(lo), "v"(hi)); return r; }
;     __device__ __forceinline__ void operator()(const f32x4 (&acc)[2][2][4][2], const Unit& u, int wr, int wc, int fr, int fq) const {
;     ...
;             for (int m = 0; m < 4; ++m) { bf16_t* rowp = O + (size_t)(row0 + ai * HALF + m * 16) * NPROJ + col0;
; #pragma unroll
;                 for (int bj = 0; bj < 2; ++bj) { f32x4 v0 = acc[ai][bj][m][0], v1 = acc[ai][bj][m][1];
;                     if (sg || zs) { f32x4 t0, t1;
; #pragma unroll
;                         for (int j = 0; j < 4; ++j) { t0[j] = __expf(-v0[j]); t1[j] = __expf(-v1[j]); }
; #pragma unroll
;                         for (int j = 0; j < 4; ++j) { t0[j] = __builtin_amdgcn_rcpf(1.f + t0[j]); t1[j] = __builtin_amdgcn_rcpf(1.f + t1[j]); }
;                         if (sg) { v0 = t0; v1 = t1; } else { v0 = v0 * t0; v1 = v1 * t1; } }
;                     u32x4 w; w.x = cvt_pk_bf16(v0[0], v0[1]); w.y = cvt_pk_bf16(v0[2], v0[3]); w.z = cvt_pk_bf16(v1[0], v1[1]); w.w = cvt_pk_bf16(v1[2], v1[3]);
;                     *(u32x4*)(rowp + bj * HALF) = w; } }
.LBB0_217:
	v_cvt_pk_bf16_f32 v96, v96, v97
	v_cvt_pk_bf16_f32 v97, v98, v99
	v_cvt_pk_bf16_f32 v98, v92, v93
	v_cvt_pk_bf16_f32 v99, v94, v95
	global_store_dwordx4 v[100:101], v[96:99], off offset:256
	s_and_b64 vcc, exec, s[38:39]
	v_mov_b32_e32 v94, v23
	v_mov_b32_e32 v95, v22
	v_mov_b32_e32 v96, v21
	v_mov_b32_e32 v97, v20
	v_mov_b32_e32 v98, v27
	v_mov_b32_e32 v99, v26
	v_mov_b32_e32 v100, v25
	v_mov_b32_e32 v101, v24
	s_cbranch_vccnz .LBB0_219
	v_mul_f32_e32 v94, 0xbfb8aa3b, v25
	v_exp_f32_e32 v95, v94
	v_mul_f32_e32 v94, 0xbfb8aa3b, v21
	v_exp_f32_e32 v96, v94
	v_mul_f32_e32 v94, 0xbfb8aa3b, v26
	v_mul_f32_e32 v93, 0xbfb8aa3b, v20
	v_exp_f32_e32 v97, v94
	v_mul_f32_e32 v94, 0xbfb8aa3b, v22
	v_exp_f32_e32 v93, v93
	v_exp_f32_e32 v98, v94
	v_mul_f32_e32 v94, 0xbfb8aa3b, v27
	v_mul_f32_e32 v92, 0xbfb8aa3b, v24
	v_exp_f32_e32 v99, v94
	v_mul_f32_e32 v94, 0xbfb8aa3b, v23
	v_exp_f32_e32 v92, v92
	v_exp_f32_e32 v100, v94
	v_add_f32_e32 v93, 1.0, v93
	v_rcp_f32_e32 v94, v93
	v_add_f32_e32 v93, 1.0, v95
	v_add_f32_e32 v95, 1.0, v96
	v_add_f32_e32 v96, 1.0, v97
	v_add_f32_e32 v97, 1.0, v98
	v_add_f32_e32 v92, 1.0, v92
	v_rcp_f32_e32 v102, v97
	v_add_f32_e32 v97, 1.0, v99
	v_add_f32_e32 v98, 1.0, v100
	v_rcp_f32_e32 v92, v92
	v_rcp_f32_e32 v93, v93
	v_rcp_f32_e32 v96, v96
	v_rcp_f32_e32 v97, v97
	v_rcp_f32_e32 v103, v98
	v_rcp_f32_e32 v95, v95
	v_pk_mul_f32 v[98:99], v[24:25], v[92:93]
	v_pk_mul_f32 v[104:105], v[26:27], v[96:97]
	v_pk_mul_f32 v[106:107], v[22:23], v[102:103]
	v_pk_mul_f32 v[108:109], v[20:21], v[94:95]
	v_cndmask_b32_e64 v101, v98, v92, s[36:37]
	v_cndmask_b32_e64 v100, v99, v93, s[36:37]
	v_cndmask_b32_e64 v99, v104, v96, s[36:37]
	v_cndmask_b32_e64 v98, v105, v97, s[36:37]
	v_cndmask_b32_e64 v97, v108, v94, s[36:37]
	v_cndmask_b32_e64 v96, v109, v95, s[36:37]
	v_cndmask_b32_e64 v95, v106, v102, s[36:37]
	v_cndmask_b32_e64 v94, v107, v103, s[36:37]
.LBB0_219:
	v_add_u32_e32 v102, 0x90, v142
	v_mov_b64_e32 v[92:93], s[4:5]
	v_mad_i64_i32 v[92:93], s[18:19], v102, s69, v[92:93]
	v_lshl_add_u64 v[92:93], v[144:145], 1, v[92:93]
	s_and_b64 vcc, exec, s[38:39]
	v_cvt_pk_bf16_f32 v100, v101, v100
	v_cvt_pk_bf16_f32 v101, v99, v98
	v_cvt_pk_bf16_f32 v102, v97, v96
	v_cvt_pk_bf16_f32 v103, v95, v94
	global_store_dwordx4 v[92:93], v[100:103], off
	s_cbranch_vccnz .LBB0_221
	v_mul_f32_e32 v96, 0xbfb8aa3b, v89
	v_exp_f32_e32 v97, v96
	v_mul_f32_e32 v96, 0xbfb8aa3b, v85
	v_exp_f32_e32 v98, v96
	v_mul_f32_e32 v96, 0xbfb8aa3b, v90
	v_mul_f32_e32 v95, 0xbfb8aa3b, v84
	v_exp_f32_e32 v99, v96
	v_mul_f32_e32 v96, 0xbfb8aa3b, v86
	v_exp_f32_e32 v95, v95
	v_exp_f32_e32 v100, v96
	v_mul_f32_e32 v96, 0xbfb8aa3b, v91
	v_mul_f32_e32 v94, 0xbfb8aa3b, v88
	v_exp_f32_e32 v101, v96
	v_mul_f32_e32 v96, 0xbfb8aa3b, v87
	v_exp_f32_e32 v94, v94
	v_exp_f32_e32 v102, v96
	v_add_f32_e32 v95, 1.0, v95
	v_rcp_f32_e32 v96, v95
	v_add_f32_e32 v95, 1.0, v97
	v_add_f32_e32 v97, 1.0, v98
	v_add_f32_e32 v98, 1.0, v99
	v_add_f32_e32 v99, 1.0, v100
	v_add_f32_e32 v94, 1.0, v94
	v_rcp_f32_e32 v100, v99
	v_add_f32_e32 v99, 1.0, v101
	v_add_f32_e32 v101, 1.0, v102
	v_rcp_f32_e32 v94, v94
	v_rcp_f32_e32 v95, v95
	v_rcp_f32_e32 v98, v98
	v_rcp_f32_e32 v99, v99
	v_rcp_f32_e32 v101, v101
	v_rcp_f32_e32 v97, v97
	v_pk_mul_f32 v[88:89], v[88:89], v[94:95]
	v_pk_mul_f32 v[90:91], v[90:91], v[98:99]
	v_pk_mul_f32 v[86:87], v[86:87], v[100:101]
	v_pk_mul_f32 v[84:85], v[84:85], v[96:97]
	v_cndmask_b32_e64 v88, v88, v94, s[36:37]
	v_cndmask_b32_e64 v89, v89, v95, s[36:37]
	v_cndmask_b32_e64 v90, v90, v98, s[36:37]
	v_cndmask_b32_e64 v91, v91, v99, s[36:37]
	v_cndmask_b32_e64 v84, v84, v96, s[36:37]
	v_cndmask_b32_e64 v85, v85, v97, s[36:37]
	v_cndmask_b32_e64 v86, v86, v100, s[36:37]
	v_cndmask_b32_e64 v87, v87, v101, s[36:37]
.LBB0_221:
	v_cvt_pk_bf16_f32 v88, v88, v89
	v_cvt_pk_bf16_f32 v89, v90, v91
	v_cvt_pk_bf16_f32 v90, v84, v85
	v_cvt_pk_bf16_f32 v91, v86, v87
	global_store_dwordx4 v[92:93], v[88:91], off offset:256
	s_and_b64 vcc, exec, s[38:39]
	v_mov_b32_e32 v86, v15
	v_mov_b32_e32 v87, v14
	v_mov_b32_e32 v88, v13
	v_mov_b32_e32 v89, v12
	v_mov_b32_e32 v90, v19
	v_mov_b32_e32 v91, v18
	v_mov_b32_e32 v92, v17
	v_mov_b32_e32 v93, v16
	s_cbranch_vccnz .LBB0_223
	v_mul_f32_e32 v86, 0xbfb8aa3b, v17
	v_exp_f32_e32 v87, v86
	v_mul_f32_e32 v86, 0xbfb8aa3b, v13
	v_exp_f32_e32 v88, v86
	v_mul_f32_e32 v86, 0xbfb8aa3b, v18
	v_mul_f32_e32 v85, 0xbfb8aa3b, v12
	v_exp_f32_e32 v89, v86
	v_mul_f32_e32 v86, 0xbfb8aa3b, v14
	v_exp_f32_e32 v85, v85
	v_exp_f32_e32 v90, v86
	v_mul_f32_e32 v86, 0xbfb8aa3b, v19
	v_mul_f32_e32 v84, 0xbfb8aa3b, v16
	v_exp_f32_e32 v91, v86
	v_mul_f32_e32 v86, 0xbfb8aa3b, v15
	v_exp_f32_e32 v84, v84
	v_exp_f32_e32 v92, v86
	v_add_f32_e32 v85, 1.0, v85
	v_rcp_f32_e32 v86, v85
	v_add_f32_e32 v85, 1.0, v87
	v_add_f32_e32 v87, 1.0, v88
	v_add_f32_e32 v88, 1.0, v89
	v_add_f32_e32 v89, 1.0, v90
	v_add_f32_e32 v84, 1.0, v84
	v_rcp_f32_e32 v94, v89
	v_add_f32_e32 v89, 1.0, v91
	v_add_f32_e32 v90, 1.0, v92
	v_rcp_f32_e32 v84, v84
	v_rcp_f32_e32 v85, v85
	v_rcp_f32_e32 v88, v88
	v_rcp_f32_e32 v89, v89
	v_rcp_f32_e32 v95, v90
	v_rcp_f32_e32 v87, v87
	v_pk_mul_f32 v[90:91], v[16:17], v[84:85]
	v_pk_mul_f32 v[96:97], v[18:19], v[88:89]
	v_pk_mul_f32 v[98:99], v[14:15], v[94:95]
	v_pk_mul_f32 v[100:101], v[12:13], v[86:87]
	v_cndmask_b32_e64 v93, v90, v84, s[36:37]
	v_cndmask_b32_e64 v92, v91, v85, s[36:37]
	v_cndmask_b32_e64 v91, v96, v88, s[36:37]
	v_cndmask_b32_e64 v90, v97, v89, s[36:37]
	v_cndmask_b32_e64 v89, v100, v86, s[36:37]
	v_cndmask_b32_e64 v88, v101, v87, s[36:37]
	v_cndmask_b32_e64 v87, v98, v94, s[36:37]
	v_cndmask_b32_e64 v86, v99, v95, s[36:37]
; __device__ __forceinline__ unsigned cvt_pk_bf16(float lo, float hi) { unsigned r; asm volatile("v_cvt_pk_bf16_f32 %0, %1, %2" : "=v"(r) : "v"(lo), "v"(hi)); return r; }
;     __device__ __forceinline__ void operator()(const f32x4 (&acc)[2][2][4][2], const Unit& u, int wr, int wc, int fr, int fq) const {
;     ...
;             for (int m = 0; m < 4; ++m) { bf16_t* rowp = O + (size_t)(row0 + ai * HALF + m * 16) * NPROJ + col0;
; #pragma unroll
;                 for (int bj = 0; bj < 2; ++bj) { f32x4 v0 = acc[ai][bj][m][0], v1 = acc[ai][bj][m][1];
;                     if (sg || zs) { f32x4 t0, t1;
; #pragma unroll
;                         for (int j = 0; j < 4; ++j) { t0[j] = __expf(-v0[j]); t1[j] = __expf(-v1[j]); }
; #pragma unroll
;                         for (int j = 0; j < 4; ++j) { t0[j] = __builtin_amdgcn_rcpf(1.f + t0[j]); t1[j] = __builtin_amdgcn_rcpf(1.f + t1[j]); }
;                         if (sg) { v0 = t0; v1 = t1; } else { v0 = v0 * t0; v1 = v1 * t1; } }
;                     u32x4 w; w.x = cvt_pk_bf16(v0[0], v0[1]); w.y = cvt_pk_bf16(v0[2], v0[3]); w.z = cvt_pk_bf16(v1[0], v1[1]); w.w = cvt_pk_bf16(v1[2], v1[3]);
;                     *(u32x4*)(rowp + bj * HALF) = w; } }
.LBB0_223:
	v_add_u32_e32 v94, 0xa0, v142
	v_mov_b64_e32 v[84:85], s[4:5]
	v_mad_i64_i32 v[84:85], s[18:19], v94, s69, v[84:85]
	v_lshl_add_u64 v[84:85], v[144:145], 1, v[84:85]
	s_and_b64 vcc, exec, s[38:39]
	v_cvt_pk_bf16_f32 v92, v93, v92
	v_cvt_pk_bf16_f32 v93, v91, v90
	v_cvt_pk_bf16_f32 v94, v89, v88
	v_cvt_pk_bf16_f32 v95, v87, v86
	global_store_dwordx4 v[84:85], v[92:95], off
	s_cbranch_vccnz .LBB0_225
	v_mul_f32_e32 v88, 0xbfb8aa3b, v81
	v_exp_f32_e32 v89, v88
	v_mul_f32_e32 v88, 0xbfb8aa3b, v77
	v_exp_f32_e32 v90, v88
	v_mul_f32_e32 v88, 0xbfb8aa3b, v82
	v_mul_f32_e32 v87, 0xbfb8aa3b, v76
	v_exp_f32_e32 v91, v88
	v_mul_f32_e32 v88, 0xbfb8aa3b, v78
	v_exp_f32_e32 v87, v87
	v_exp_f32_e32 v92, v88
	v_mul_f32_e32 v88, 0xbfb8aa3b, v83
	v_mul_f32_e32 v86, 0xbfb8aa3b, v80
	v_exp_f32_e32 v93, v88
	v_mul_f32_e32 v88, 0xbfb8aa3b, v79
	v_exp_f32_e32 v86, v86
	v_exp_f32_e32 v94, v88
	v_add_f32_e32 v87, 1.0, v87
	v_rcp_f32_e32 v88, v87
	v_add_f32_e32 v87, 1.0, v89
	v_add_f32_e32 v89, 1.0, v90
	v_add_f32_e32 v90, 1.0, v91
	v_add_f32_e32 v91, 1.0, v92
	v_add_f32_e32 v86, 1.0, v86
	v_rcp_f32_e32 v92, v91
	v_add_f32_e32 v91, 1.0, v93
	v_add_f32_e32 v93, 1.0, v94
	v_rcp_f32_e32 v86, v86
	v_rcp_f32_e32 v87, v87
	v_rcp_f32_e32 v90, v90
	v_rcp_f32_e32 v91, v91
	v_rcp_f32_e32 v93, v93
	v_rcp_f32_e32 v89, v89
	v_pk_mul_f32 v[80:81], v[80:81], v[86:87]
	v_pk_mul_f32 v[82:83], v[82:83], v[90:91]
	v_pk_mul_f32 v[78:79], v[78:79], v[92:93]
	v_pk_mul_f32 v[76:77], v[76:77], v[88:89]
	v_cndmask_b32_e64 v80, v80, v86, s[36:37]
	v_cndmask_b32_e64 v81, v81, v87, s[36:37]
	v_cndmask_b32_e64 v82, v82, v90, s[36:37]
	v_cndmask_b32_e64 v83, v83, v91, s[36:37]
	v_cndmask_b32_e64 v76, v76, v88, s[36:37]
	v_cndmask_b32_e64 v77, v77, v89, s[36:37]
	v_cndmask_b32_e64 v78, v78, v92, s[36:37]
	v_cndmask_b32_e64 v79, v79, v93, s[36:37]
.LBB0_225:
	v_cvt_pk_bf16_f32 v80, v80, v81
	v_cvt_pk_bf16_f32 v81, v82, v83
	v_cvt_pk_bf16_f32 v82, v76, v77
	v_cvt_pk_bf16_f32 v83, v78, v79
	global_store_dwordx4 v[84:85], v[80:83], off offset:256
	s_and_b64 vcc, exec, s[38:39]
	v_mov_b32_e32 v78, v7
	v_mov_b32_e32 v79, v6
	v_mov_b32_e32 v80, v5
	v_mov_b32_e32 v81, v4
	v_mov_b32_e32 v82, v11
	v_mov_b32_e32 v83, v10
	v_mov_b32_e32 v84, v9
	v_mov_b32_e32 v85, v8
	s_cbranch_vccnz .LBB0_227
	v_mul_f32_e32 v78, 0xbfb8aa3b, v9
	v_exp_f32_e32 v79, v78
	v_mul_f32_e32 v78, 0xbfb8aa3b, v5
	v_exp_f32_e32 v80, v78
	v_mul_f32_e32 v78, 0xbfb8aa3b, v10
	v_mul_f32_e32 v77, 0xbfb8aa3b, v4
	v_exp_f32_e32 v81, v78
	v_mul_f32_e32 v78, 0xbfb8aa3b, v6
	v_exp_f32_e32 v77, v77
	v_exp_f32_e32 v82, v78
	v_mul_f32_e32 v78, 0xbfb8aa3b, v11
	v_mul_f32_e32 v76, 0xbfb8aa3b, v8
	v_exp_f32_e32 v83, v78
	v_mul_f32_e32 v78, 0xbfb8aa3b, v7
	v_exp_f32_e32 v76, v76
	v_exp_f32_e32 v84, v78
	v_add_f32_e32 v77, 1.0, v77
	v_rcp_f32_e32 v78, v77
	v_add_f32_e32 v77, 1.0, v79
	v_add_f32_e32 v79, 1.0, v80
	v_add_f32_e32 v80, 1.0, v81
	v_add_f32_e32 v81, 1.0, v82
	v_add_f32_e32 v76, 1.0, v76
	v_rcp_f32_e32 v86, v81
	v_add_f32_e32 v81, 1.0, v83
	v_add_f32_e32 v82, 1.0, v84
	v_rcp_f32_e32 v76, v76
	v_rcp_f32_e32 v77, v77
	v_rcp_f32_e32 v80, v80
	v_rcp_f32_e32 v81, v81
	v_rcp_f32_e32 v87, v82
	v_rcp_f32_e32 v79, v79
	v_pk_mul_f32 v[82:83], v[8:9], v[76:77]
	v_pk_mul_f32 v[88:89], v[10:11], v[80:81]
	v_pk_mul_f32 v[90:91], v[6:7], v[86:87]
	v_pk_mul_f32 v[92:93], v[4:5], v[78:79]
	v_cndmask_b32_e64 v85, v82, v76, s[36:37]
	v_cndmask_b32_e64 v84, v83, v77, s[36:37]
	v_cndmask_b32_e64 v83, v88, v80, s[36:37]
	v_cndmask_b32_e64 v82, v89, v81, s[36:37]
	v_cndmask_b32_e64 v81, v92, v78, s[36:37]
	v_cndmask_b32_e64 v80, v93, v79, s[36:37]
	v_cndmask_b32_e64 v79, v90, v86, s[36:37]
	v_cndmask_b32_e64 v78, v91, v87, s[36:37]
; __device__ __forceinline__ unsigned cvt_pk_bf16(float lo, float hi) { unsigned r; asm volatile("v_cvt_pk_bf16_f32 %0, %1, %2" : "=v"(r) : "v"(lo), "v"(hi)); return r; }
;     __device__ __forceinline__ void operator()(const f32x4 (&acc)[2][2][4][2], const Unit& u, int wr, int wc, int fr, int fq) const {
;     ...
;         if (u.pn == 74) {
;             if (wc < 2) {
; #pragma unroll
;                 for (int ai = 0; ai < 2; ++ai)
; #pragma unroll
;                     for (int m = 0; m < 4; ++m) { float* p = DT + (size_t)(row0 + ai * HALF + m * 16) * 64 + wc * 32 + 8 * fq;
;                         *(f32x4*)p = acc[ai][0][m][0]; *(f32x4*)(p + 4) = acc[ai][0][m][1]; }
;             }
;     ...
;                 for (int bj = 0; bj < 2; ++bj) { f32x4 v0 = acc[ai][bj][m][0], v1 = acc[ai][bj][m][1];
;                     if (sg || zs) { f32x4 t0, t1;
; #pragma unroll
;                         for (int j = 0; j < 4; ++j) { t0[j] = __expf(-v0[j]); t1[j] = __expf(-v1[j]); }
; #pragma unroll
;                         for (int j = 0; j < 4; ++j) { t0[j] = __builtin_amdgcn_rcpf(1.f + t0[j]); t1[j] = __builtin_amdgcn_rcpf(1.f + t1[j]); }
;                         if (sg) { v0 = t0; v1 = t1; } else { v0 = v0 * t0; v1 = v1 * t1; } }
;                     u32x4 w; w.x = cvt_pk_bf16(v0[0], v0[1]); w.y = cvt_pk_bf16(v0[2], v0[3]); w.z = cvt_pk_bf16(v1[0], v1[1]); w.w = cvt_pk_bf16(v1[2], v1[3]);
;                     *(u32x4*)(rowp + bj * HALF) = w; } }
.LBB0_227:
	v_add_u32_e32 v86, 0xb0, v142
	v_mov_b64_e32 v[76:77], s[4:5]
	v_mad_i64_i32 v[76:77], s[18:19], v86, s69, v[76:77]
	v_lshl_add_u64 v[76:77], v[144:145], 1, v[76:77]
	s_and_b64 vcc, exec, s[38:39]
	v_cvt_pk_bf16_f32 v84, v85, v84
	v_cvt_pk_bf16_f32 v85, v83, v82
	v_cvt_pk_bf16_f32 v86, v81, v80
	v_cvt_pk_bf16_f32 v87, v79, v78
	global_store_dwordx4 v[76:77], v[84:87], off
	s_cbranch_vccnz .LBB0_229
	v_mul_f32_e32 v80, 0xbfb8aa3b, v41
	v_exp_f32_e32 v81, v80
	v_mul_f32_e32 v80, 0xbfb8aa3b, v37
	v_exp_f32_e32 v82, v80
	v_mul_f32_e32 v80, 0xbfb8aa3b, v42
	v_mul_f32_e32 v79, 0xbfb8aa3b, v36
	v_exp_f32_e32 v83, v80
	v_mul_f32_e32 v80, 0xbfb8aa3b, v38
	v_exp_f32_e32 v79, v79
	v_exp_f32_e32 v84, v80
	v_mul_f32_e32 v80, 0xbfb8aa3b, v43
	v_mul_f32_e32 v78, 0xbfb8aa3b, v40
	v_exp_f32_e32 v85, v80
	v_mul_f32_e32 v80, 0xbfb8aa3b, v39
	v_exp_f32_e32 v78, v78
	v_exp_f32_e32 v86, v80
	v_add_f32_e32 v79, 1.0, v79
	v_rcp_f32_e32 v80, v79
	v_add_f32_e32 v79, 1.0, v81
	v_add_f32_e32 v81, 1.0, v82
	v_add_f32_e32 v82, 1.0, v83
	v_add_f32_e32 v83, 1.0, v84
	v_add_f32_e32 v78, 1.0, v78
	v_rcp_f32_e32 v84, v83
	v_add_f32_e32 v83, 1.0, v85
	v_add_f32_e32 v85, 1.0, v86
	v_rcp_f32_e32 v78, v78
	v_rcp_f32_e32 v79, v79
	v_rcp_f32_e32 v82, v82
	v_rcp_f32_e32 v83, v83
	v_rcp_f32_e32 v85, v85
	v_rcp_f32_e32 v81, v81
	v_pk_mul_f32 v[40:41], v[40:41], v[78:79]
	v_pk_mul_f32 v[42:43], v[42:43], v[82:83]
	v_pk_mul_f32 v[38:39], v[38:39], v[84:85]
	v_pk_mul_f32 v[36:37], v[36:37], v[80:81]
	v_cndmask_b32_e64 v40, v40, v78, s[36:37]
	v_cndmask_b32_e64 v41, v41, v79, s[36:37]
	v_cndmask_b32_e64 v42, v42, v82, s[36:37]
	v_cndmask_b32_e64 v43, v43, v83, s[36:37]
	v_cndmask_b32_e64 v36, v36, v80, s[36:37]
	v_cndmask_b32_e64 v37, v37, v81, s[36:37]
	v_cndmask_b32_e64 v38, v38, v84, s[36:37]
	v_cndmask_b32_e64 v39, v39, v85, s[36:37]
.LBB0_229:
	v_cvt_pk_bf16_f32 v40, v40, v41
	v_cvt_pk_bf16_f32 v41, v42, v43
	v_cvt_pk_bf16_f32 v42, v36, v37
	v_cvt_pk_bf16_f32 v43, v38, v39
	global_store_dwordx4 v[76:77], v[40:43], off offset:256
	s_branch .LBB0_232
.LBB0_230:
	s_andn2_b64 vcc, exec, s[16:17]
	s_cbranch_vccnz .LBB0_232
	v_or_b32_e32 v38, 16, v142
	v_ashrrev_i32_e32 v143, 31, v142
	v_ashrrev_i32_e32 v39, 31, v38
	v_lshlrev_b64 v[36:37], 8, v[142:143]
	v_lshlrev_b64 v[38:39], 8, v[38:39]
	v_lshl_add_u64 v[36:37], v[136:137], 0, v[36:37]
	v_lshl_add_u64 v[38:39], v[136:137], 0, v[38:39]
	global_store_dwordx4 v[36:37], v[72:75], off
	global_store_dwordx4 v[36:37], v[68:71], off offset:16
	global_store_dwordx4 v[38:39], v[64:67], off
	global_store_dwordx4 v[38:39], v[60:63], off offset:16
	v_or_b32_e32 v38, 32, v142
	v_ashrrev_i32_e32 v39, 31, v38
	v_lshlrev_b64 v[38:39], 8, v[38:39]
	v_lshl_add_u64 v[38:39], v[136:137], 0, v[38:39]
	global_store_dwordx4 v[38:39], v[56:59], off
	global_store_dwordx4 v[38:39], v[52:55], off offset:16
	v_or_b32_e32 v38, 48, v142
	v_ashrrev_i32_e32 v39, 31, v38
	v_lshlrev_b64 v[38:39], 8, v[38:39]
	v_lshl_add_u64 v[38:39], v[136:137], 0, v[38:39]
	s_mov_b64 s[18:19], 0x8000
	global_store_dwordx4 v[38:39], v[48:51], off
	global_store_dwordx4 v[38:39], v[44:47], off offset:16
	v_lshl_add_u64 v[38:39], v[36:37], 0, s[18:19]
	s_mov_b32 s18, 0x8000
	v_add_co_u32_e32 v40, vcc, s18, v36
	s_mov_b64 s[18:19], 0x9000
	s_nop 0
	v_addc_co_u32_e32 v41, vcc, 0, v37, vcc
	global_store_dwordx4 v[40:41], v[32:35], off
	global_store_dwordx4 v[38:39], v[28:31], off offset:16
	s_nop 1
	v_add_co_u32_e32 v30, vcc, 0x9000, v36
	v_lshl_add_u64 v[28:29], v[36:37], 0, s[18:19]
	s_nop 0
	v_addc_co_u32_e32 v31, vcc, 0, v37, vcc
	global_store_dwordx4 v[30:31], v[24:27], off
	global_store_dwordx4 v[28:29], v[20:23], off offset:16
	s_mov_b64 s[18:19], 0xa000
	s_nop 0
	v_add_co_u32_e32 v22, vcc, 0xa000, v36
	v_lshl_add_u64 v[20:21], v[36:37], 0, s[18:19]
	s_nop 0
	v_addc_co_u32_e32 v23, vcc, 0, v37, vcc
	global_store_dwordx4 v[22:23], v[16:19], off
	global_store_dwordx4 v[20:21], v[12:15], off offset:16
	s_mov_b64 s[18:19], 0xb000
	s_nop 0
	v_add_co_u32_e32 v14, vcc, 0xb000, v36
	v_lshl_add_u64 v[12:13], v[36:37], 0, s[18:19]
	s_nop 0
	v_addc_co_u32_e32 v15, vcc, 0, v37, vcc
	global_store_dwordx4 v[14:15], v[8:11], off
	global_store_dwordx4 v[12:13], v[4:7], off offset:16

; __device__ __forceinline__ unsigned cvt_pk_bf16(float lo, float hi) { unsigned r; asm volatile("v_cvt_pk_bf16_f32 %0, %1, %2" : "=v"(r) : "v"(lo), "v"(hi)); return r; }
; __device__ __forceinline__ float bflo(unsigned u) { return __uint_as_float(u << 16); }
; __device__ __forceinline__ float bfhi(unsigned u) { return __uint_as_float(u & 0xffff0000u); }
;     __device__ __forceinline__ void operator()(const f32x4 (&acc)[2][2][4][2], const Unit& u, int wr, int wc, int fr, int fq) const {
;     ...
;         for (int ai = 0; ai < 2; ++ai) { u32x4 gall[4][2];
; #pragma unroll
;             for (int m = 0; m < 4; ++m)
; #pragma unroll
;                 for (int bj = 0; bj < 2; ++bj) gall[m][bj] = *(const u32x4*)(G + (size_t)(row0 + ai * HALF + m * 16) * ldg + col0 + bj * HALF);
; #pragma unroll
;             for (int m = 0; m < 4; ++m) { const size_t row = (size_t)(row0 + ai * HALF + m * 16);
; #pragma unroll
;                 for (int bj = 0; bj < 2; ++bj) { const int col = col0 + bj * HALF;
;                     const u32x4 gv = gall[m][bj];
;                     f32x4 v0 = acc[ai][bj][m][0], v1 = acc[ai][bj][m][1];
;                     v0[0] *= bflo(gv.x); v0[1] *= bfhi(gv.x); v0[2] *= bflo(gv.y); v0[3] *= bfhi(gv.y);
;                     v1[0] *= bflo(gv.z); v1[1] *= bfhi(gv.z); v1[2] *= bflo(gv.w); v1[3] *= bfhi(gv.w);
;                     bf16_t* op = O + row * ldc + col;
;                     if (MODE == 1) { const u32x4 ov = *(const u32x4*)op;
;                         v0[0] += bflo(ov.x); v0[1] += bfhi(ov.x); v0[2] += bflo(ov.y); v0[3] += bfhi(ov.y);
;                         v1[0] += bflo(ov.z); v1[1] += bfhi(ov.z); v1[2] += bflo(ov.w); v1[3] += bfhi(ov.w); }
;                     u32x4 w; w.x = cvt_pk_bf16(v0[0], v0[1]); w.y = cvt_pk_bf16(v0[2], v0[3]); w.z = cvt_pk_bf16(v1[0], v1[1]); w.w = cvt_pk_bf16(v1[2], v1[3]);
;                     *(u32x4*)op = w; } } }
.LBB0_571:
	v_lshl_or_b32 v132, s33, 8, v187
	v_ashrrev_i32_e32 v133, 31, v132
	v_lshlrev_b64 v[160:161], 1, v[132:133]
	v_lshl_add_u32 v162, s57, 8, v173
	v_lshl_add_u64 v[164:165], s[6:7], 0, v[160:161]
	v_mad_i64_i32 v[132:133], s[24:25], v162, s69, v[164:165]
	global_load_dwordx4 v[190:193], v[132:133], off
	global_load_dwordx4 v[194:197], v[132:133], off offset:256
	v_or_b32_e32 v184, 16, v162
	v_mad_i64_i32 v[132:133], s[24:25], v184, s69, v[164:165]
	global_load_dwordx4 v[198:201], v[132:133], off
	global_load_dwordx4 v[148:151], v[132:133], off offset:256
	v_or_b32_e32 v182, 32, v162
	v_mad_i64_i32 v[132:133], s[24:25], v182, s69, v[164:165]
	global_load_dwordx4 v[144:147], v[132:133], off
	global_load_dwordx4 v[136:139], v[132:133], off offset:256
	v_or_b32_e32 v166, 48, v162
	v_mad_i64_i32 v[132:133], s[24:25], v166, s69, v[164:165]
	global_load_dwordx4 v[140:143], v[132:133], off
	s_nop 0
	global_load_dwordx4 v[132:135], v[132:133], off offset:256
	v_ashrrev_i32_e32 v163, 31, v162
	v_ashrrev_i32_e32 v185, 31, v184
	v_ashrrev_i32_e32 v183, 31, v182
	v_ashrrev_i32_e32 v167, 31, v166
	v_readlane_b32 s66, v252, 18
	s_and_b64 vcc, exec, s[36:37]
	v_readlane_b32 s67, v252, 19
	s_waitcnt vmcnt(0) lgkmcnt(0)
	v_lshlrev_b32_e32 v189, 16, v190
	v_mul_f32_e32 v189, v128, v189
	v_and_b32_e32 v128, 0xffff0000, v190
	v_mul_f32_e32 v190, v129, v128
	v_lshlrev_b32_e32 v128, 16, v191
	v_mul_f32_e32 v130, v130, v128
	v_and_b32_e32 v128, 0xffff0000, v191
	v_mul_f32_e32 v131, v131, v128
	v_lshlrev_b32_e32 v128, 16, v192
	v_mul_f32_e32 v191, v124, v128
	v_and_b32_e32 v124, 0xffff0000, v192
	v_mul_f32_e32 v192, v125, v124
	v_lshlrev_b32_e32 v124, 16, v193
	v_mul_f32_e32 v211, v126, v124
	v_and_b32_e32 v124, 0xffff0000, v193
	v_mul_f32_e32 v127, v127, v124
	v_lshlrev_b64 v[124:125], 12, v[162:163]
	v_lshl_add_u64 v[124:125], s[40:41], 0, v[124:125]
	v_lshl_add_u64 v[128:129], v[124:125], 0, v[160:161]
	v_cvt_pk_bf16_f32 v124, v189, v190
	v_cvt_pk_bf16_f32 v125, v130, v131
	v_cvt_pk_bf16_f32 v126, v191, v192
	v_cvt_pk_bf16_f32 v127, v211, v127
	global_store_dwordx4 v[128:129], v[124:127], off
	s_nop 1
	v_lshlrev_b32_e32 v124, 16, v194
	v_mul_f32_e32 v116, v116, v124
	v_and_b32_e32 v124, 0xffff0000, v194
	v_mul_f32_e32 v117, v117, v124
	v_lshlrev_b32_e32 v124, 16, v195
	v_mul_f32_e32 v118, v118, v124
	v_and_b32_e32 v124, 0xffff0000, v195
	v_mul_f32_e32 v119, v119, v124
	v_lshlrev_b32_e32 v124, 16, v196
	v_mul_f32_e32 v124, v108, v124
	v_and_b32_e32 v108, 0xffff0000, v196
	v_mul_f32_e32 v125, v109, v108
	v_lshlrev_b32_e32 v108, 16, v197
	v_mul_f32_e32 v126, v110, v108
	v_and_b32_e32 v108, 0xffff0000, v197
	v_mul_f32_e32 v111, v111, v108
	v_cvt_pk_bf16_f32 v108, v116, v117
	v_cvt_pk_bf16_f32 v109, v118, v119
	v_cvt_pk_bf16_f32 v110, v124, v125
	v_cvt_pk_bf16_f32 v111, v126, v111
	global_store_dwordx4 v[128:129], v[108:111], off offset:256
	s_nop 1
	v_lshlrev_b32_e32 v108, 16, v198
	v_mul_f32_e32 v110, v120, v108
	v_and_b32_e32 v108, 0xffff0000, v198
	v_mul_f32_e32 v111, v121, v108
	v_lshlrev_b32_e32 v108, 16, v199
	v_mul_f32_e32 v116, v122, v108
	v_and_b32_e32 v108, 0xffff0000, v199
	v_mul_f32_e32 v117, v123, v108
	v_lshlrev_b32_e32 v108, 16, v200
	v_mul_f32_e32 v118, v112, v108
	v_and_b32_e32 v108, 0xffff0000, v200
	v_mul_f32_e32 v119, v113, v108
	v_lshlrev_b32_e32 v108, 16, v201
	v_mul_f32_e32 v114, v114, v108
	v_and_b32_e32 v108, 0xffff0000, v201
	v_mul_f32_e32 v115, v115, v108
	v_lshlrev_b64 v[108:109], 12, v[184:185]
	v_lshl_add_u64 v[108:109], s[40:41], 0, v[108:109]
	v_lshl_add_u64 v[112:113], v[108:109], 0, v[160:161]
	v_cvt_pk_bf16_f32 v108, v110, v111
	v_cvt_pk_bf16_f32 v109, v116, v117
	v_cvt_pk_bf16_f32 v110, v118, v119
	v_cvt_pk_bf16_f32 v111, v114, v115
	global_store_dwordx4 v[112:113], v[108:111], off
	s_nop 1
	v_lshlrev_b32_e32 v108, 16, v148
	v_mul_f32_e32 v104, v104, v108
	v_and_b32_e32 v108, 0xffff0000, v148
	v_mul_f32_e32 v105, v105, v108
	v_lshlrev_b32_e32 v108, 16, v149
	v_mul_f32_e32 v106, v106, v108
	v_and_b32_e32 v108, 0xffff0000, v149
	v_mul_f32_e32 v107, v107, v108
	v_lshlrev_b32_e32 v108, 16, v150
	v_mul_f32_e32 v108, v96, v108
	v_and_b32_e32 v96, 0xffff0000, v150
	v_mul_f32_e32 v109, v97, v96
	v_lshlrev_b32_e32 v96, 16, v151
	v_mul_f32_e32 v110, v98, v96
	v_and_b32_e32 v96, 0xffff0000, v151
	v_mul_f32_e32 v99, v99, v96
	v_cvt_pk_bf16_f32 v96, v104, v105
	v_cvt_pk_bf16_f32 v97, v106, v107
	v_cvt_pk_bf16_f32 v98, v108, v109
	v_cvt_pk_bf16_f32 v99, v110, v99
	global_store_dwordx4 v[112:113], v[96:99], off offset:256
	v_add_u32_e32 v106, 0xb0, v162
	v_ashrrev_i32_e32 v107, 31, v106
	v_lshlrev_b32_e32 v96, 16, v144
	v_mul_f32_e32 v98, v100, v96
	v_and_b32_e32 v96, 0xffff0000, v144
	v_mul_f32_e32 v99, v101, v96
	v_lshlrev_b32_e32 v96, 16, v145
	v_mul_f32_e32 v100, v102, v96
	v_and_b32_e32 v96, 0xffff0000, v145
	v_mul_f32_e32 v101, v103, v96
	v_lshlrev_b32_e32 v96, 16, v146
	v_mul_f32_e32 v102, v92, v96
	v_and_b32_e32 v92, 0xffff0000, v146
	v_mul_f32_e32 v103, v93, v92
	v_lshlrev_b32_e32 v92, 16, v147
	v_mul_f32_e32 v104, v94, v92
	v_and_b32_e32 v92, 0xffff0000, v147
	v_mul_f32_e32 v95, v95, v92
	v_lshlrev_b64 v[92:93], 12, v[182:183]
	v_lshl_add_u64 v[92:93], s[40:41], 0, v[92:93]
	v_lshl_add_u64 v[96:97], v[92:93], 0, v[160:161]
	v_cvt_pk_bf16_f32 v92, v98, v99
	v_cvt_pk_bf16_f32 v93, v100, v101
	v_cvt_pk_bf16_f32 v94, v102, v103
	v_cvt_pk_bf16_f32 v95, v104, v95
	global_store_dwordx4 v[96:97], v[92:95], off
	v_add_u32_e32 v100, 0x80, v162
	v_add_u32_e32 v102, 0x90, v162
	v_lshlrev_b32_e32 v92, 16, v136
	v_mul_f32_e32 v88, v88, v92
	v_and_b32_e32 v92, 0xffff0000, v136
	v_mul_f32_e32 v89, v89, v92
	v_lshlrev_b32_e32 v92, 16, v137
; __device__ __forceinline__ unsigned cvt_pk_bf16(float lo, float hi) { unsigned r; asm volatile("v_cvt_pk_bf16_f32 %0, %1, %2" : "=v"(r) : "v"(lo), "v"(hi)); return r; }
; __device__ __forceinline__ float bflo(unsigned u) { return __uint_as_float(u << 16); }
; __device__ __forceinline__ float bfhi(unsigned u) { return __uint_as_float(u & 0xffff0000u); }
;     __device__ __forceinline__ void operator()(const f32x4 (&acc)[2][2][4][2], const Unit& u, int wr, int wc, int fr, int fq) const {
;     ...
;                 for (int bj = 0; bj < 2; ++bj) gall[m][bj] = *(const u32x4*)(G + (size_t)(row0 + ai * HALF + m * 16) * ldg + col0 + bj * HALF);
; #pragma unroll
;             for (int m = 0; m < 4; ++m) { const size_t row = (size_t)(row0 + ai * HALF + m * 16);
; #pragma unroll
;                 for (int bj = 0; bj < 2; ++bj) { const int col = col0 + bj * HALF;
;                     const u32x4 gv = gall[m][bj];
;                     f32x4 v0 = acc[ai][bj][m][0], v1 = acc[ai][bj][m][1];
;                     v0[0] *= bflo(gv.x); v0[1] *= bfhi(gv.x); v0[2] *= bflo(gv.y); v0[3] *= bfhi(gv.y);
;                     v1[0] *= bflo(gv.z); v1[1] *= bfhi(gv.z); v1[2] *= bflo(gv.w); v1[3] *= bfhi(gv.w);
;                     bf16_t* op = O + row * ldc + col;
;                     if (MODE == 1) { const u32x4 ov = *(const u32x4*)op;
;                         v0[0] += bflo(ov.x); v0[1] += bfhi(ov.x); v0[2] += bflo(ov.y); v0[3] += bfhi(ov.y);
;                         v1[0] += bflo(ov.z); v1[1] += bfhi(ov.z); v1[2] += bflo(ov.w); v1[3] += bfhi(ov.w); }
;                     u32x4 w; w.x = cvt_pk_bf16(v0[0], v0[1]); w.y = cvt_pk_bf16(v0[2], v0[3]); w.z = cvt_pk_bf16(v1[0], v1[1]); w.w = cvt_pk_bf16(v1[2], v1[3]);
;                     *(u32x4*)op = w; } } }
	v_mul_f32_e32 v90, v90, v92
	v_and_b32_e32 v92, 0xffff0000, v137
	v_mul_f32_e32 v91, v91, v92
	v_lshlrev_b32_e32 v92, 16, v138
	v_mul_f32_e32 v92, v80, v92
	v_and_b32_e32 v80, 0xffff0000, v138
	v_mul_f32_e32 v93, v81, v80
	v_lshlrev_b32_e32 v80, 16, v139
	v_mul_f32_e32 v94, v82, v80
	v_and_b32_e32 v80, 0xffff0000, v139
	v_mul_f32_e32 v83, v83, v80
	v_cvt_pk_bf16_f32 v80, v88, v89
	v_cvt_pk_bf16_f32 v81, v90, v91
	v_cvt_pk_bf16_f32 v82, v92, v93
	v_cvt_pk_bf16_f32 v83, v94, v83
	global_store_dwordx4 v[96:97], v[80:83], off offset:256
	v_add_u32_e32 v104, 0xa0, v162
	v_mad_i64_i32 v[96:97], s[24:25], v106, s69, v[164:165]
	v_lshlrev_b32_e32 v80, 16, v140
	v_mul_f32_e32 v82, v84, v80
	v_and_b32_e32 v80, 0xffff0000, v140
	v_mul_f32_e32 v83, v85, v80
	v_lshlrev_b32_e32 v80, 16, v141
	v_mul_f32_e32 v84, v86, v80
	v_and_b32_e32 v80, 0xffff0000, v141
	v_mul_f32_e32 v85, v87, v80
	v_lshlrev_b32_e32 v80, 16, v142
	v_mul_f32_e32 v86, v76, v80
	v_and_b32_e32 v76, 0xffff0000, v142
	v_mul_f32_e32 v87, v77, v76
	v_lshlrev_b32_e32 v76, 16, v143
	v_mul_f32_e32 v88, v78, v76
	v_and_b32_e32 v76, 0xffff0000, v143
	v_mul_f32_e32 v79, v79, v76
	v_lshlrev_b64 v[76:77], 12, v[166:167]
	v_lshl_add_u64 v[76:77], s[40:41], 0, v[76:77]
	v_lshl_add_u64 v[80:81], v[76:77], 0, v[160:161]
	v_cvt_pk_bf16_f32 v76, v82, v83
	v_cvt_pk_bf16_f32 v77, v84, v85
	v_cvt_pk_bf16_f32 v78, v86, v87
	v_cvt_pk_bf16_f32 v79, v88, v79
	global_store_dwordx4 v[80:81], v[76:79], off
	v_mad_i64_i32 v[88:89], s[24:25], v104, s69, v[164:165]
	s_nop 0
	v_lshlrev_b32_e32 v76, 16, v132
	v_mul_f32_e32 v72, v72, v76
	v_and_b32_e32 v76, 0xffff0000, v132
	v_mul_f32_e32 v73, v73, v76
	v_lshlrev_b32_e32 v76, 16, v133
	v_mul_f32_e32 v74, v74, v76
	v_and_b32_e32 v76, 0xffff0000, v133
	v_mul_f32_e32 v75, v75, v76
	v_lshlrev_b32_e32 v76, 16, v134
	v_mul_f32_e32 v76, v68, v76
	v_and_b32_e32 v68, 0xffff0000, v134
	v_mul_f32_e32 v77, v69, v68
	v_lshlrev_b32_e32 v68, 16, v135
	v_mul_f32_e32 v78, v70, v68
	v_and_b32_e32 v68, 0xffff0000, v135
	v_mul_f32_e32 v71, v71, v68
	v_cvt_pk_bf16_f32 v68, v72, v73
	v_cvt_pk_bf16_f32 v69, v74, v75
	v_cvt_pk_bf16_f32 v70, v76, v77
	v_cvt_pk_bf16_f32 v71, v78, v71
	global_store_dwordx4 v[80:81], v[68:71], off offset:256
	v_mad_i64_i32 v[72:73], s[24:25], v100, s69, v[164:165]
	global_load_dwordx4 v[68:71], v[72:73], off
	s_nop 0
	global_load_dwordx4 v[72:75], v[72:73], off offset:256
	v_mad_i64_i32 v[80:81], s[24:25], v102, s69, v[164:165]
	global_load_dwordx4 v[76:79], v[80:81], off
	s_nop 0
	global_load_dwordx4 v[80:83], v[80:81], off offset:256
	s_nop 0
	global_load_dwordx4 v[84:87], v[88:89], off
	s_nop 0
	global_load_dwordx4 v[88:91], v[88:89], off offset:256
	s_nop 0
	global_load_dwordx4 v[92:95], v[96:97], off
	s_nop 0
	global_load_dwordx4 v[96:99], v[96:97], off offset:256
	v_ashrrev_i32_e32 v101, 31, v100
	v_ashrrev_i32_e32 v103, 31, v102
	v_ashrrev_i32_e32 v105, 31, v104
	s_mov_b64 s[24:25], -1
	s_waitcnt vmcnt(0) lgkmcnt(0)
; __device__ __forceinline__ unsigned cvt_pk_bf16(float lo, float hi) { unsigned r; asm volatile("v_cvt_pk_bf16_f32 %0, %1, %2" : "=v"(r) : "v"(lo), "v"(hi)); return r; }
; __device__ __forceinline__ float bflo(unsigned u) { return __uint_as_float(u << 16); }
; __device__ __forceinline__ float bfhi(unsigned u) { return __uint_as_float(u & 0xffff0000u); }
; #define PG8_BAR __builtin_amdgcn_s_barrier()
;     __device__ __forceinline__ void operator()(const f32x4 (&acc)[2][2][4][2], const Unit& u, int wr, int wc, int fr, int fq) const {
;     ...
;             for (int m = 0; m < 4; ++m) { const size_t row = (size_t)(row0 + ai * HALF + m * 16);
; #pragma unroll
;                 for (int bj = 0; bj < 2; ++bj) { const int col = col0 + bj * HALF;
;                     const u32x4 gv = gall[m][bj];
;                     f32x4 v0 = acc[ai][bj][m][0], v1 = acc[ai][bj][m][1];
;                     v0[0] *= bflo(gv.x); v0[1] *= bfhi(gv.x); v0[2] *= bflo(gv.y); v0[3] *= bfhi(gv.y);
;                     v1[0] *= bflo(gv.z); v1[1] *= bfhi(gv.z); v1[2] *= bflo(gv.w); v1[3] *= bfhi(gv.w);
;                     bf16_t* op = O + row * ldc + col;
;                     if (MODE == 1) { const u32x4 ov = *(const u32x4*)op;
;                         v0[0] += bflo(ov.x); v0[1] += bfhi(ov.x); v0[2] += bflo(ov.y); v0[3] += bfhi(ov.y);
;                         v1[0] += bflo(ov.z); v1[1] += bfhi(ov.z); v1[2] += bflo(ov.w); v1[3] += bfhi(ov.w); }
;                     u32x4 w; w.x = cvt_pk_bf16(v0[0], v0[1]); w.y = cvt_pk_bf16(v0[2], v0[3]); w.z = cvt_pk_bf16(v1[0], v1[1]); w.w = cvt_pk_bf16(v1[2], v1[3]);
;                     *(u32x4*)op = w; } } }
; template <class Epi, class Sched, bool ALIGN_EPI = false, bool SP2 = false>
; __device__ __forceinline__ void gemm_phase(PG8_LAS unsigned char* lds, const Gemm g, const Sched& S, const Epi& E, int wave_s) {
;     ...
;         if (!has_next) break;
; #pragma unroll
;         for (int a = 0; a < 2; ++a)
; #pragma unroll
;             for (int b = 0; b < 2; ++b)
; #pragma unroll
;                 for (int m = 0; m < 4; ++m)
; #pragma unroll
;                     for (int n = 0; n < 2; ++n) acc[a][b][m][n] = (f32x4){0.f, 0.f, 0.f, 0.f};
;         cur = nxt; cA = nA; cB = nB; ++ui;
;         if constexpr (ALIGN_EPI) { if (wr == 1) PG8_BAR; }
	v_lshlrev_b32_e32 v108, 16, v68
	v_mul_f32_e32 v108, v64, v108
	v_and_b32_e32 v64, 0xffff0000, v68
	v_mul_f32_e32 v68, v65, v64
	v_lshlrev_b32_e32 v64, 16, v69
	v_mul_f32_e32 v66, v66, v64
	v_and_b32_e32 v64, 0xffff0000, v69
	v_mul_f32_e32 v67, v67, v64
	v_lshlrev_b32_e32 v64, 16, v70
	v_mul_f32_e32 v69, v60, v64
	v_and_b32_e32 v60, 0xffff0000, v70
	v_mul_f32_e32 v70, v61, v60
	v_lshlrev_b32_e32 v60, 16, v71
	v_mul_f32_e32 v109, v62, v60
	v_and_b32_e32 v60, 0xffff0000, v71
	v_mul_f32_e32 v63, v63, v60
	v_lshlrev_b64 v[60:61], 12, v[100:101]
	v_lshl_add_u64 v[60:61], s[40:41], 0, v[60:61]
	v_lshl_add_u64 v[64:65], v[60:61], 0, v[160:161]
	v_cvt_pk_bf16_f32 v60, v108, v68
	v_cvt_pk_bf16_f32 v61, v66, v67
	v_cvt_pk_bf16_f32 v62, v69, v70
	v_cvt_pk_bf16_f32 v63, v109, v63
	global_store_dwordx4 v[64:65], v[60:63], off
	s_nop 1
	v_lshlrev_b32_e32 v60, 16, v72
	v_mul_f32_e32 v56, v56, v60
	v_and_b32_e32 v60, 0xffff0000, v72
	v_mul_f32_e32 v57, v57, v60
	v_lshlrev_b32_e32 v60, 16, v73
	v_mul_f32_e32 v58, v58, v60
	v_and_b32_e32 v60, 0xffff0000, v73
	v_mul_f32_e32 v59, v59, v60
	v_lshlrev_b32_e32 v60, 16, v74
	v_mul_f32_e32 v60, v48, v60
	v_and_b32_e32 v48, 0xffff0000, v74
	v_mul_f32_e32 v61, v49, v48
	v_lshlrev_b32_e32 v48, 16, v75
	v_mul_f32_e32 v62, v50, v48
	v_and_b32_e32 v48, 0xffff0000, v75
	v_mul_f32_e32 v51, v51, v48
	v_cvt_pk_bf16_f32 v48, v56, v57
	v_cvt_pk_bf16_f32 v49, v58, v59
	v_cvt_pk_bf16_f32 v50, v60, v61
	v_cvt_pk_bf16_f32 v51, v62, v51
	global_store_dwordx4 v[64:65], v[48:51], off offset:256
	s_nop 1
	v_lshlrev_b32_e32 v48, 16, v76
	v_mul_f32_e32 v50, v52, v48
	v_and_b32_e32 v48, 0xffff0000, v76
	v_mul_f32_e32 v51, v53, v48
	v_lshlrev_b32_e32 v48, 16, v77
	v_mul_f32_e32 v52, v54, v48
	v_and_b32_e32 v48, 0xffff0000, v77
	v_mul_f32_e32 v53, v55, v48
	v_lshlrev_b32_e32 v48, 16, v78
	v_mul_f32_e32 v54, v44, v48
	v_and_b32_e32 v44, 0xffff0000, v78
	v_mul_f32_e32 v55, v45, v44
	v_lshlrev_b32_e32 v44, 16, v79
	v_mul_f32_e32 v56, v46, v44
	v_and_b32_e32 v44, 0xffff0000, v79
	v_mul_f32_e32 v47, v47, v44
	v_lshlrev_b64 v[44:45], 12, v[102:103]
	v_lshl_add_u64 v[44:45], s[40:41], 0, v[44:45]
	v_lshl_add_u64 v[48:49], v[44:45], 0, v[160:161]
	v_cvt_pk_bf16_f32 v44, v50, v51
	v_cvt_pk_bf16_f32 v45, v52, v53
	v_cvt_pk_bf16_f32 v46, v54, v55
	v_cvt_pk_bf16_f32 v47, v56, v47
	global_store_dwordx4 v[48:49], v[44:47], off
	s_nop 1
	v_lshlrev_b32_e32 v44, 16, v80
	v_mul_f32_e32 v40, v40, v44
	v_and_b32_e32 v44, 0xffff0000, v80
	v_mul_f32_e32 v41, v41, v44
	v_lshlrev_b32_e32 v44, 16, v81
	v_mul_f32_e32 v42, v42, v44
	v_and_b32_e32 v44, 0xffff0000, v81
	v_mul_f32_e32 v43, v43, v44
	v_lshlrev_b32_e32 v44, 16, v82
	v_mul_f32_e32 v44, v32, v44
	v_and_b32_e32 v32, 0xffff0000, v82
	v_mul_f32_e32 v45, v33, v32
	v_lshlrev_b32_e32 v32, 16, v83
	v_mul_f32_e32 v46, v34, v32
	v_and_b32_e32 v32, 0xffff0000, v83
	v_mul_f32_e32 v35, v35, v32
	v_cvt_pk_bf16_f32 v32, v40, v41
	v_cvt_pk_bf16_f32 v33, v42, v43
	v_cvt_pk_bf16_f32 v34, v44, v45
	v_cvt_pk_bf16_f32 v35, v46, v35
	global_store_dwordx4 v[48:49], v[32:35], off offset:256
	s_nop 1
	v_lshlrev_b32_e32 v32, 16, v84
	v_mul_f32_e32 v34, v36, v32
	v_and_b32_e32 v32, 0xffff0000, v84
	v_mul_f32_e32 v35, v37, v32
	v_lshlrev_b32_e32 v32, 16, v85
	v_mul_f32_e32 v36, v38, v32
	v_and_b32_e32 v32, 0xffff0000, v85
	v_mul_f32_e32 v37, v39, v32
	v_lshlrev_b32_e32 v32, 16, v86
	v_mul_f32_e32 v38, v28, v32
	v_and_b32_e32 v28, 0xffff0000, v86
	v_mul_f32_e32 v39, v29, v28
	v_lshlrev_b32_e32 v28, 16, v87
	v_mul_f32_e32 v40, v30, v28
	v_and_b32_e32 v28, 0xffff0000, v87
	v_mul_f32_e32 v31, v31, v28
	v_lshlrev_b64 v[28:29], 12, v[104:105]
	v_lshl_add_u64 v[28:29], s[40:41], 0, v[28:29]
	v_lshl_add_u64 v[32:33], v[28:29], 0, v[160:161]
	v_cvt_pk_bf16_f32 v28, v34, v35
	v_cvt_pk_bf16_f32 v29, v36, v37
	v_cvt_pk_bf16_f32 v30, v38, v39
	v_cvt_pk_bf16_f32 v31, v40, v31
	global_store_dwordx4 v[32:33], v[28:31], off
	s_nop 1
	v_lshlrev_b32_e32 v28, 16, v88
	v_mul_f32_e32 v24, v24, v28
	v_and_b32_e32 v28, 0xffff0000, v88
	v_mul_f32_e32 v25, v25, v28
	v_lshlrev_b32_e32 v28, 16, v89
	v_mul_f32_e32 v26, v26, v28
	v_and_b32_e32 v28, 0xffff0000, v89
	v_mul_f32_e32 v27, v27, v28
	v_lshlrev_b32_e32 v28, 16, v90
	v_mul_f32_e32 v28, v16, v28
	v_and_b32_e32 v16, 0xffff0000, v90
	v_mul_f32_e32 v29, v17, v16
	v_lshlrev_b32_e32 v16, 16, v91
	v_mul_f32_e32 v30, v18, v16
	v_and_b32_e32 v16, 0xffff0000, v91
	v_mul_f32_e32 v19, v19, v16
	v_cvt_pk_bf16_f32 v16, v24, v25
	v_cvt_pk_bf16_f32 v17, v26, v27
	v_cvt_pk_bf16_f32 v18, v28, v29
	v_cvt_pk_bf16_f32 v19, v30, v19
	global_store_dwordx4 v[32:33], v[16:19], off offset:256
	s_nop 1
	v_lshlrev_b32_e32 v16, 16, v92
	v_mul_f32_e32 v18, v20, v16
	v_and_b32_e32 v16, 0xffff0000, v92
	v_mul_f32_e32 v19, v21, v16
	v_lshlrev_b32_e32 v16, 16, v93
	v_mul_f32_e32 v20, v22, v16
	v_and_b32_e32 v16, 0xffff0000, v93
	v_mul_f32_e32 v21, v23, v16
	v_lshlrev_b32_e32 v16, 16, v94
	v_mul_f32_e32 v22, v12, v16
	v_and_b32_e32 v12, 0xffff0000, v94
	v_mul_f32_e32 v23, v13, v12
	v_lshlrev_b32_e32 v12, 16, v95
	v_mul_f32_e32 v24, v14, v12
	v_and_b32_e32 v12, 0xffff0000, v95
	v_mul_f32_e32 v15, v15, v12
	v_lshlrev_b64 v[12:13], 12, v[106:107]
	v_lshl_add_u64 v[12:13], s[40:41], 0, v[12:13]
	v_lshl_add_u64 v[16:17], v[12:13], 0, v[160:161]
	v_cvt_pk_bf16_f32 v12, v18, v19
	v_cvt_pk_bf16_f32 v13, v20, v21
	v_cvt_pk_bf16_f32 v14, v22, v23
	v_cvt_pk_bf16_f32 v15, v24, v15
	global_store_dwordx4 v[16:17], v[12:15], off
	s_nop 1
	v_lshlrev_b32_e32 v12, 16, v96
	v_mul_f32_e32 v8, v8, v12
	v_and_b32_e32 v12, 0xffff0000, v96
	v_mul_f32_e32 v9, v9, v12
	v_lshlrev_b32_e32 v12, 16, v97
	v_mul_f32_e32 v10, v10, v12
	v_and_b32_e32 v12, 0xffff0000, v97
	v_mul_f32_e32 v11, v11, v12
	v_lshlrev_b32_e32 v12, 16, v98
	v_mul_f32_e32 v12, v4, v12
	v_and_b32_e32 v4, 0xffff0000, v98
	v_mul_f32_e32 v13, v5, v4
	v_lshlrev_b32_e32 v4, 16, v99
	v_mul_f32_e32 v14, v6, v4
	v_and_b32_e32 v4, 0xffff0000, v99
	v_mul_f32_e32 v7, v7, v4
	v_cvt_pk_bf16_f32 v4, v8, v9
	v_cvt_pk_bf16_f32 v5, v10, v11
	v_cvt_pk_bf16_f32 v6, v12, v13
	v_cvt_pk_bf16_f32 v7, v14, v7
	global_store_dwordx4 v[16:17], v[4:7], off offset:256
	s_cbranch_vccnz .LBB0_558
	s_andn2_b64 vcc, exec, s[4:5]
	s_cbranch_vccnz .LBB0_557
	s_barrier
	s_branch .LBB0_557

; __device__ __forceinline__ unsigned cvt_pk_bf16(float lo, float hi) { unsigned r; asm volatile("v_cvt_pk_bf16_f32 %0, %1, %2" : "=v"(r) : "v"(lo), "v"(hi)); return r; }
; __device__ __forceinline__ float bflo(unsigned u) { return __uint_as_float(u << 16); }
; __device__ __forceinline__ float bfhi(unsigned u) { return __uint_as_float(u & 0xffff0000u); }
;     __device__ __forceinline__ void operator()(const f32x4 (&acc)[2][2][4][2], const Unit& u, int wr, int wc, int fr, int fq) const {
;     ...
;                 for (int bj = 0; bj < 2; ++bj) gall[m][bj] = *(const u32x4*)(G + (size_t)(row0 + ai * HALF + m * 16) * ldg + col0 + bj * HALF);
; #pragma unroll
;             for (int m = 0; m < 4; ++m) { const size_t row = (size_t)(row0 + ai * HALF + m * 16);
; #pragma unroll
;                 for (int bj = 0; bj < 2; ++bj) { const int col = col0 + bj * HALF;
;                     const u32x4 gv = gall[m][bj];
;                     f32x4 v0 = acc[ai][bj][m][0], v1 = acc[ai][bj][m][1];
;                     v0[0] *= bflo(gv.x); v0[1] *= bfhi(gv.x); v0[2] *= bflo(gv.y); v0[3] *= bfhi(gv.y);
;                     v1[0] *= bflo(gv.z); v1[1] *= bfhi(gv.z); v1[2] *= bflo(gv.w); v1[3] *= bfhi(gv.w);
;                     bf16_t* op = O + row * ldc + col;
;                     if (MODE == 1) { const u32x4 ov = *(const u32x4*)op;
;                         v0[0] += bflo(ov.x); v0[1] += bfhi(ov.x); v0[2] += bflo(ov.y); v0[3] += bfhi(ov.y);
;                         v1[0] += bflo(ov.z); v1[1] += bfhi(ov.z); v1[2] += bflo(ov.w); v1[3] += bfhi(ov.w); }
;                     u32x4 w; w.x = cvt_pk_bf16(v0[0], v0[1]); w.y = cvt_pk_bf16(v0[2], v0[3]); w.z = cvt_pk_bf16(v1[0], v1[1]); w.w = cvt_pk_bf16(v1[2], v1[3]);
;                     *(u32x4*)op = w; } } }
.LBB0_593:
	v_lshl_or_b32 v100, s33, 8, v195
	v_ashrrev_i32_e32 v101, 31, v100
	v_lshlrev_b64 v[182:183], 1, v[100:101]
	v_lshl_add_u32 v184, s55, 8, v173
	v_lshl_add_u64 v[186:187], s[44:45], 0, v[182:183]
	v_mad_i64_i32 v[100:101], s[0:1], v184, s69, v[186:187]
	global_load_dwordx4 v[198:201], v[100:101], off
	global_load_dwordx4 v[156:159], v[100:101], off offset:256
	v_ashrrev_i32_e32 v185, 31, v184
	v_or_b32_e32 v192, 16, v184
	v_mad_i64_i32 v[100:101], s[0:1], v192, s69, v[186:187]
	v_or_b32_e32 v190, 32, v184
	global_load_dwordx4 v[152:155], v[100:101], off
	global_load_dwordx4 v[148:151], v[100:101], off offset:256
	v_mad_i64_i32 v[100:101], s[0:1], v190, s69, v[186:187]
	v_or_b32_e32 v188, 48, v184
	global_load_dwordx4 v[144:147], v[100:101], off
	global_load_dwordx4 v[124:127], v[100:101], off offset:256
	v_mad_i64_i32 v[100:101], s[0:1], v188, s69, v[186:187]
	global_load_dwordx4 v[120:123], v[100:101], off
	s_nop 0
	global_load_dwordx4 v[100:103], v[100:101], off offset:256
	v_ashrrev_i32_e32 v193, 31, v192
	v_ashrrev_i32_e32 v191, 31, v190
	v_ashrrev_i32_e32 v189, 31, v188
	s_and_b64 vcc, exec, s[36:37]
	s_waitcnt vmcnt(0) lgkmcnt(0)
	v_lshlrev_b32_e32 v197, 16, v198
	v_and_b32_e32 v211, 0xffff0000, v198
	v_lshlrev_b32_e32 v214, 16, v199
	v_and_b32_e32 v215, 0xffff0000, v199
	v_lshlrev_b64 v[198:199], 12, v[184:185]
	v_lshl_add_u64 v[198:199], s[40:41], 0, v[198:199]
	v_lshl_add_u64 v[212:213], v[198:199], 0, v[182:183]
	v_lshlrev_b32_e32 v216, 16, v200
	v_and_b32_e32 v217, 0xffff0000, v200
	v_lshlrev_b32_e32 v218, 16, v201
	v_and_b32_e32 v219, 0xffff0000, v201
	global_load_dwordx4 v[198:201], v[212:213], off
	s_waitcnt vmcnt(0) lgkmcnt(0)
	v_lshlrev_b32_e32 v185, 16, v198
	v_fmac_f32_e32 v185, v140, v197
	v_and_b32_e32 v140, 0xffff0000, v198
	v_fmac_f32_e32 v140, v141, v211
	v_lshlrev_b32_e32 v141, 16, v199
	v_fmac_f32_e32 v141, v142, v214
	v_and_b32_e32 v142, 0xffff0000, v199
	v_fmac_f32_e32 v142, v143, v215
	v_lshlrev_b32_e32 v143, 16, v200
	v_and_b32_e32 v197, 0xffff0000, v200
	v_lshlrev_b32_e32 v198, 16, v201
	v_and_b32_e32 v199, 0xffff0000, v201
	v_fmac_f32_e32 v143, v136, v216
	v_fmac_f32_e32 v197, v137, v217
	v_fmac_f32_e32 v198, v138, v218
	v_fmac_f32_e32 v199, v139, v219
	v_cvt_pk_bf16_f32 v136, v185, v140
	v_cvt_pk_bf16_f32 v137, v141, v142
	v_cvt_pk_bf16_f32 v138, v143, v197
	v_cvt_pk_bf16_f32 v139, v198, v199
	global_store_dwordx4 v[212:213], v[136:139], off
	global_load_dwordx4 v[136:139], v[212:213], off offset:256
	v_lshlrev_b32_e32 v140, 16, v156
	v_and_b32_e32 v141, 0xffff0000, v156
	v_lshlrev_b32_e32 v142, 16, v157
	v_and_b32_e32 v143, 0xffff0000, v157
	v_lshlrev_b32_e32 v156, 16, v158
	v_and_b32_e32 v157, 0xffff0000, v158
	v_lshlrev_b32_e32 v158, 16, v159
	v_and_b32_e32 v159, 0xffff0000, v159
	s_waitcnt vmcnt(0) lgkmcnt(0)
	v_lshlrev_b32_e32 v185, 16, v136
	v_fmac_f32_e32 v185, v132, v140
	v_and_b32_e32 v132, 0xffff0000, v136
	v_fmac_f32_e32 v132, v133, v141
	v_lshlrev_b32_e32 v133, 16, v137
	v_fmac_f32_e32 v133, v134, v142
	v_and_b32_e32 v134, 0xffff0000, v137
	v_fmac_f32_e32 v134, v135, v143
	v_lshlrev_b32_e32 v135, 16, v138
	v_and_b32_e32 v136, 0xffff0000, v138
	v_fmac_f32_e32 v135, v128, v156
	v_fmac_f32_e32 v136, v129, v157
	v_lshlrev_b32_e32 v137, 16, v139
	v_and_b32_e32 v138, 0xffff0000, v139
	v_cvt_pk_bf16_f32 v128, v185, v132
	v_cvt_pk_bf16_f32 v129, v133, v134
	v_fmac_f32_e32 v137, v130, v158
	v_fmac_f32_e32 v138, v131, v159
	v_cvt_pk_bf16_f32 v130, v135, v136
	v_cvt_pk_bf16_f32 v131, v137, v138
	global_store_dwordx4 v[212:213], v[128:131], off offset:256
	v_lshlrev_b32_e32 v134, 16, v152
	v_and_b32_e32 v135, 0xffff0000, v152
	v_lshlrev_b64 v[128:129], 12, v[192:193]
	v_lshl_add_u64 v[128:129], s[40:41], 0, v[128:129]
	v_lshl_add_u64 v[128:129], v[128:129], 0, v[182:183]
	global_load_dwordx4 v[130:133], v[128:129], off
	v_lshlrev_b32_e32 v136, 16, v153
	v_and_b32_e32 v137, 0xffff0000, v153
	v_lshlrev_b32_e32 v138, 16, v154
	v_and_b32_e32 v139, 0xffff0000, v154
	v_lshlrev_b32_e32 v140, 16, v155
	v_and_b32_e32 v141, 0xffff0000, v155
	s_waitcnt vmcnt(0) lgkmcnt(0)
	v_lshlrev_b32_e32 v142, 16, v130
	v_fmac_f32_e32 v142, v116, v134
	v_and_b32_e32 v116, 0xffff0000, v130
	v_fmac_f32_e32 v116, v117, v135
	v_lshlrev_b32_e32 v117, 16, v131
	v_fmac_f32_e32 v117, v118, v136
	v_and_b32_e32 v118, 0xffff0000, v131
	v_fmac_f32_e32 v118, v119, v137
	v_lshlrev_b32_e32 v119, 16, v132
	v_and_b32_e32 v130, 0xffff0000, v132
	v_lshlrev_b32_e32 v131, 16, v133
	v_and_b32_e32 v132, 0xffff0000, v133
	v_fmac_f32_e32 v119, v112, v138
	v_fmac_f32_e32 v130, v113, v139
	v_fmac_f32_e32 v131, v114, v140
	v_fmac_f32_e32 v132, v115, v141
	v_cvt_pk_bf16_f32 v112, v142, v116
	v_cvt_pk_bf16_f32 v113, v117, v118
	v_cvt_pk_bf16_f32 v114, v119, v130
	v_cvt_pk_bf16_f32 v115, v131, v132
	global_store_dwordx4 v[128:129], v[112:115], off
	global_load_dwordx4 v[112:115], v[128:129], off offset:256
	v_lshlrev_b32_e32 v116, 16, v148
	v_and_b32_e32 v117, 0xffff0000, v148
	v_lshlrev_b32_e32 v118, 16, v149
	v_and_b32_e32 v119, 0xffff0000, v149
	v_lshlrev_b32_e32 v130, 16, v150
	v_and_b32_e32 v131, 0xffff0000, v150
	v_lshlrev_b32_e32 v132, 16, v151
	v_and_b32_e32 v133, 0xffff0000, v151
	s_waitcnt vmcnt(0) lgkmcnt(0)
; __device__ __forceinline__ unsigned cvt_pk_bf16(float lo, float hi) { unsigned r; asm volatile("v_cvt_pk_bf16_f32 %0, %1, %2" : "=v"(r) : "v"(lo), "v"(hi)); return r; }
; __device__ __forceinline__ float bflo(unsigned u) { return __uint_as_float(u << 16); }
; __device__ __forceinline__ float bfhi(unsigned u) { return __uint_as_float(u & 0xffff0000u); }
;     __device__ __forceinline__ void operator()(const f32x4 (&acc)[2][2][4][2], const Unit& u, int wr, int wc, int fr, int fq) const {
;     ...
;             for (int m = 0; m < 4; ++m) { const size_t row = (size_t)(row0 + ai * HALF + m * 16);
; #pragma unroll
;                 for (int bj = 0; bj < 2; ++bj) { const int col = col0 + bj * HALF;
;                     const u32x4 gv = gall[m][bj];
;                     f32x4 v0 = acc[ai][bj][m][0], v1 = acc[ai][bj][m][1];
;                     v0[0] *= bflo(gv.x); v0[1] *= bfhi(gv.x); v0[2] *= bflo(gv.y); v0[3] *= bfhi(gv.y);
;                     v1[0] *= bflo(gv.z); v1[1] *= bfhi(gv.z); v1[2] *= bflo(gv.w); v1[3] *= bfhi(gv.w);
;                     bf16_t* op = O + row * ldc + col;
;                     if (MODE == 1) { const u32x4 ov = *(const u32x4*)op;
;                         v0[0] += bflo(ov.x); v0[1] += bfhi(ov.x); v0[2] += bflo(ov.y); v0[3] += bfhi(ov.y);
;                         v1[0] += bflo(ov.z); v1[1] += bfhi(ov.z); v1[2] += bflo(ov.w); v1[3] += bfhi(ov.w); }
;                     u32x4 w; w.x = cvt_pk_bf16(v0[0], v0[1]); w.y = cvt_pk_bf16(v0[2], v0[3]); w.z = cvt_pk_bf16(v1[0], v1[1]); w.w = cvt_pk_bf16(v1[2], v1[3]);
;                     *(u32x4*)op = w; } } }
	v_lshlrev_b32_e32 v134, 16, v112
	v_fmac_f32_e32 v134, v108, v116
	v_and_b32_e32 v108, 0xffff0000, v112
	v_fmac_f32_e32 v108, v109, v117
	v_lshlrev_b32_e32 v109, 16, v113
	v_fmac_f32_e32 v109, v110, v118
	v_and_b32_e32 v110, 0xffff0000, v113
	v_fmac_f32_e32 v110, v111, v119
	v_lshlrev_b32_e32 v111, 16, v114
	v_and_b32_e32 v112, 0xffff0000, v114
	v_fmac_f32_e32 v111, v104, v130
	v_fmac_f32_e32 v112, v105, v131
	v_lshlrev_b32_e32 v113, 16, v115
	v_and_b32_e32 v114, 0xffff0000, v115
	v_cvt_pk_bf16_f32 v104, v134, v108
	v_cvt_pk_bf16_f32 v105, v109, v110
	v_fmac_f32_e32 v113, v106, v132
	v_fmac_f32_e32 v114, v107, v133
	v_cvt_pk_bf16_f32 v106, v111, v112
	v_cvt_pk_bf16_f32 v107, v113, v114
	global_store_dwordx4 v[128:129], v[104:107], off offset:256
	v_lshlrev_b32_e32 v110, 16, v144
	v_and_b32_e32 v111, 0xffff0000, v144
	v_lshlrev_b64 v[104:105], 12, v[190:191]
	v_lshl_add_u64 v[104:105], s[40:41], 0, v[104:105]
	v_lshl_add_u64 v[104:105], v[104:105], 0, v[182:183]
	global_load_dwordx4 v[106:109], v[104:105], off
	v_lshlrev_b32_e32 v112, 16, v145
	v_and_b32_e32 v113, 0xffff0000, v145
	v_lshlrev_b32_e32 v114, 16, v146
	v_and_b32_e32 v115, 0xffff0000, v146
	v_lshlrev_b32_e32 v116, 16, v147
	v_and_b32_e32 v117, 0xffff0000, v147
	s_waitcnt vmcnt(0) lgkmcnt(0)
	v_lshlrev_b32_e32 v118, 16, v106
	v_fmac_f32_e32 v118, v96, v110
	v_and_b32_e32 v96, 0xffff0000, v106
	v_fmac_f32_e32 v96, v97, v111
	v_lshlrev_b32_e32 v97, 16, v107
	v_fmac_f32_e32 v97, v98, v112
	v_and_b32_e32 v98, 0xffff0000, v107
	v_fmac_f32_e32 v98, v99, v113
	v_lshlrev_b32_e32 v99, 16, v108
	v_and_b32_e32 v106, 0xffff0000, v108
	v_lshlrev_b32_e32 v107, 16, v109
	v_and_b32_e32 v108, 0xffff0000, v109
	v_fmac_f32_e32 v99, v92, v114
	v_fmac_f32_e32 v106, v93, v115
	v_fmac_f32_e32 v107, v94, v116
	v_fmac_f32_e32 v108, v95, v117
	v_cvt_pk_bf16_f32 v92, v118, v96
	v_cvt_pk_bf16_f32 v93, v97, v98
	v_cvt_pk_bf16_f32 v94, v99, v106
	v_cvt_pk_bf16_f32 v95, v107, v108
	global_store_dwordx4 v[104:105], v[92:95], off
	global_load_dwordx4 v[92:95], v[104:105], off offset:256
	v_lshlrev_b32_e32 v96, 16, v124
	v_and_b32_e32 v97, 0xffff0000, v124
	v_lshlrev_b32_e32 v98, 16, v125
	v_and_b32_e32 v99, 0xffff0000, v125
	v_lshlrev_b32_e32 v106, 16, v126
	v_and_b32_e32 v107, 0xffff0000, v126
	v_lshlrev_b32_e32 v108, 16, v127
	v_and_b32_e32 v109, 0xffff0000, v127
	s_waitcnt vmcnt(0) lgkmcnt(0)
	v_lshlrev_b32_e32 v110, 16, v92
	v_fmac_f32_e32 v110, v88, v96
	v_and_b32_e32 v88, 0xffff0000, v92
	v_fmac_f32_e32 v88, v89, v97
	v_lshlrev_b32_e32 v89, 16, v93
	v_fmac_f32_e32 v89, v90, v98
	v_and_b32_e32 v90, 0xffff0000, v93
	v_fmac_f32_e32 v90, v91, v99
	v_lshlrev_b32_e32 v91, 16, v94
	v_and_b32_e32 v92, 0xffff0000, v94
	v_fmac_f32_e32 v91, v84, v106
	v_fmac_f32_e32 v92, v85, v107
	v_lshlrev_b32_e32 v93, 16, v95
	v_and_b32_e32 v94, 0xffff0000, v95
	v_cvt_pk_bf16_f32 v84, v110, v88
	v_cvt_pk_bf16_f32 v85, v89, v90
	v_fmac_f32_e32 v93, v86, v108
	v_fmac_f32_e32 v94, v87, v109
	v_cvt_pk_bf16_f32 v86, v91, v92
	v_cvt_pk_bf16_f32 v87, v93, v94
	global_store_dwordx4 v[104:105], v[84:87], off offset:256
	v_lshlrev_b32_e32 v90, 16, v120
	v_and_b32_e32 v91, 0xffff0000, v120
	v_lshlrev_b64 v[84:85], 12, v[188:189]
	v_lshl_add_u64 v[84:85], s[40:41], 0, v[84:85]
	v_lshl_add_u64 v[84:85], v[84:85], 0, v[182:183]
	global_load_dwordx4 v[86:89], v[84:85], off
	v_lshlrev_b32_e32 v92, 16, v121
	v_and_b32_e32 v93, 0xffff0000, v121
	v_lshlrev_b32_e32 v94, 16, v122
	v_and_b32_e32 v95, 0xffff0000, v122
	v_lshlrev_b32_e32 v96, 16, v123
	v_and_b32_e32 v97, 0xffff0000, v123
	s_waitcnt vmcnt(0) lgkmcnt(0)
	v_lshlrev_b32_e32 v98, 16, v86
	v_fmac_f32_e32 v98, v80, v90
	v_and_b32_e32 v80, 0xffff0000, v86
	v_fmac_f32_e32 v80, v81, v91
	v_lshlrev_b32_e32 v81, 16, v87
	v_fmac_f32_e32 v81, v82, v92
	v_and_b32_e32 v82, 0xffff0000, v87
	v_fmac_f32_e32 v82, v83, v93
	v_lshlrev_b32_e32 v83, 16, v88
	v_and_b32_e32 v86, 0xffff0000, v88
	v_lshlrev_b32_e32 v87, 16, v89
	v_and_b32_e32 v88, 0xffff0000, v89
	v_fmac_f32_e32 v83, v76, v94
	v_fmac_f32_e32 v86, v77, v95
	v_fmac_f32_e32 v87, v78, v96
	v_fmac_f32_e32 v88, v79, v97
	v_cvt_pk_bf16_f32 v76, v98, v80
	v_cvt_pk_bf16_f32 v77, v81, v82
	v_cvt_pk_bf16_f32 v78, v83, v86
	v_cvt_pk_bf16_f32 v79, v87, v88
	global_store_dwordx4 v[84:85], v[76:79], off
	global_load_dwordx4 v[76:79], v[84:85], off offset:256
	v_lshlrev_b32_e32 v80, 16, v100
	v_and_b32_e32 v81, 0xffff0000, v100
	v_lshlrev_b32_e32 v82, 16, v101
	v_and_b32_e32 v83, 0xffff0000, v101
	v_lshlrev_b32_e32 v86, 16, v102
	v_and_b32_e32 v87, 0xffff0000, v102
	v_lshlrev_b32_e32 v88, 16, v103
	v_and_b32_e32 v89, 0xffff0000, v103
	v_add_u32_e32 v102, 0x80, v184
	v_ashrrev_i32_e32 v103, 31, v102
	v_add_u32_e32 v100, 0x90, v184
	v_add_u32_e32 v98, 0xa0, v184
	v_add_u32_e32 v96, 0xb0, v184
	v_ashrrev_i32_e32 v101, 31, v100
	v_ashrrev_i32_e32 v99, 31, v98
	v_ashrrev_i32_e32 v97, 31, v96
	s_waitcnt vmcnt(0) lgkmcnt(0)
	v_lshlrev_b32_e32 v90, 16, v76
	v_fmac_f32_e32 v90, v72, v80
	v_and_b32_e32 v72, 0xffff0000, v76
	v_fmac_f32_e32 v72, v73, v81
	v_lshlrev_b32_e32 v73, 16, v77
	v_fmac_f32_e32 v73, v74, v82
	v_and_b32_e32 v74, 0xffff0000, v77
	v_fmac_f32_e32 v74, v75, v83
	v_lshlrev_b32_e32 v75, 16, v78
	v_and_b32_e32 v76, 0xffff0000, v78
	v_fmac_f32_e32 v75, v68, v86
	v_fmac_f32_e32 v76, v69, v87
	v_lshlrev_b32_e32 v77, 16, v79
	v_and_b32_e32 v78, 0xffff0000, v79
	v_cvt_pk_bf16_f32 v68, v90, v72
	v_cvt_pk_bf16_f32 v69, v73, v74
	v_fmac_f32_e32 v77, v70, v88
	v_fmac_f32_e32 v78, v71, v89
	v_cvt_pk_bf16_f32 v70, v75, v76
	v_cvt_pk_bf16_f32 v71, v77, v78
	global_store_dwordx4 v[84:85], v[68:71], off offset:256
	s_nop 1
	v_mad_i64_i32 v[68:69], s[0:1], v102, s69, v[186:187]
	global_load_dwordx4 v[104:107], v[68:69], off
	global_load_dwordx4 v[92:95], v[68:69], off offset:256
	v_mad_i64_i32 v[68:69], s[0:1], v100, s69, v[186:187]
	v_lshlrev_b64 v[102:103], 12, v[102:103]
	global_load_dwordx4 v[88:91], v[68:69], off
	global_load_dwordx4 v[84:87], v[68:69], off offset:256
	v_mad_i64_i32 v[68:69], s[0:1], v98, s69, v[186:187]
	v_lshl_add_u64 v[102:103], s[40:41], 0, v[102:103]
	global_load_dwordx4 v[80:83], v[68:69], off
	global_load_dwordx4 v[76:79], v[68:69], off offset:256
	v_mad_i64_i32 v[68:69], s[0:1], v96, s69, v[186:187]
	global_load_dwordx4 v[72:75], v[68:69], off
	s_nop 0
	global_load_dwordx4 v[68:71], v[68:69], off offset:256
	s_mov_b64 s[0:1], -1
	s_waitcnt vmcnt(0) lgkmcnt(0)
; __device__ __forceinline__ unsigned cvt_pk_bf16(float lo, float hi) { unsigned r; asm volatile("v_cvt_pk_bf16_f32 %0, %1, %2" : "=v"(r) : "v"(lo), "v"(hi)); return r; }
; __device__ __forceinline__ float bflo(unsigned u) { return __uint_as_float(u << 16); }
; __device__ __forceinline__ float bfhi(unsigned u) { return __uint_as_float(u & 0xffff0000u); }
;     __device__ __forceinline__ void operator()(const f32x4 (&acc)[2][2][4][2], const Unit& u, int wr, int wc, int fr, int fq) const {
;     ...
;             for (int m = 0; m < 4; ++m) { const size_t row = (size_t)(row0 + ai * HALF + m * 16);
; #pragma unroll
;                 for (int bj = 0; bj < 2; ++bj) { const int col = col0 + bj * HALF;
;                     const u32x4 gv = gall[m][bj];
;                     f32x4 v0 = acc[ai][bj][m][0], v1 = acc[ai][bj][m][1];
;                     v0[0] *= bflo(gv.x); v0[1] *= bfhi(gv.x); v0[2] *= bflo(gv.y); v0[3] *= bfhi(gv.y);
;                     v1[0] *= bflo(gv.z); v1[1] *= bfhi(gv.z); v1[2] *= bflo(gv.w); v1[3] *= bfhi(gv.w);
;                     bf16_t* op = O + row * ldc + col;
;                     if (MODE == 1) { const u32x4 ov = *(const u32x4*)op;
;                         v0[0] += bflo(ov.x); v0[1] += bfhi(ov.x); v0[2] += bflo(ov.y); v0[3] += bfhi(ov.y);
;                         v1[0] += bflo(ov.z); v1[1] += bfhi(ov.z); v1[2] += bflo(ov.w); v1[3] += bfhi(ov.w); }
;                     u32x4 w; w.x = cvt_pk_bf16(v0[0], v0[1]); w.y = cvt_pk_bf16(v0[2], v0[3]); w.z = cvt_pk_bf16(v1[0], v1[1]); w.w = cvt_pk_bf16(v1[2], v1[3]);
;                     *(u32x4*)op = w; } } }
	v_lshlrev_b32_e32 v112, 16, v106
	v_and_b32_e32 v113, 0xffff0000, v106
	v_lshlrev_b32_e32 v114, 16, v107
	v_and_b32_e32 v115, 0xffff0000, v107
	v_lshl_add_u64 v[106:107], v[102:103], 0, v[182:183]
	v_lshlrev_b32_e32 v108, 16, v104
	v_and_b32_e32 v109, 0xffff0000, v104
	v_lshlrev_b32_e32 v110, 16, v105
	v_and_b32_e32 v111, 0xffff0000, v105
	global_load_dwordx4 v[102:105], v[106:107], off
	s_waitcnt vmcnt(0) lgkmcnt(0)
	v_lshlrev_b32_e32 v116, 16, v102
	v_fmac_f32_e32 v116, v64, v108
	v_and_b32_e32 v64, 0xffff0000, v102
	v_fmac_f32_e32 v64, v65, v109
	v_lshlrev_b32_e32 v65, 16, v103
	v_fmac_f32_e32 v65, v66, v110
	v_and_b32_e32 v66, 0xffff0000, v103
	v_fmac_f32_e32 v66, v67, v111
	v_lshlrev_b32_e32 v67, 16, v104
	v_and_b32_e32 v102, 0xffff0000, v104
	v_lshlrev_b32_e32 v103, 16, v105
	v_and_b32_e32 v104, 0xffff0000, v105
	v_fmac_f32_e32 v67, v60, v112
	v_fmac_f32_e32 v102, v61, v113
	v_fmac_f32_e32 v103, v62, v114
	v_fmac_f32_e32 v104, v63, v115
	v_cvt_pk_bf16_f32 v60, v116, v64
	v_cvt_pk_bf16_f32 v61, v65, v66
	v_cvt_pk_bf16_f32 v62, v67, v102
	v_cvt_pk_bf16_f32 v63, v103, v104
	global_store_dwordx4 v[106:107], v[60:63], off
	global_load_dwordx4 v[60:63], v[106:107], off offset:256
	v_lshlrev_b32_e32 v64, 16, v92
	v_and_b32_e32 v65, 0xffff0000, v92
	v_lshlrev_b32_e32 v66, 16, v93
	v_and_b32_e32 v67, 0xffff0000, v93
	v_lshlrev_b32_e32 v92, 16, v94
	v_and_b32_e32 v93, 0xffff0000, v94
	v_lshlrev_b32_e32 v94, 16, v95
	v_and_b32_e32 v95, 0xffff0000, v95
	s_waitcnt vmcnt(0) lgkmcnt(0)
	v_lshlrev_b32_e32 v102, 16, v60
	v_fmac_f32_e32 v102, v56, v64
	v_and_b32_e32 v56, 0xffff0000, v60
	v_fmac_f32_e32 v56, v57, v65
	v_lshlrev_b32_e32 v57, 16, v61
	v_fmac_f32_e32 v57, v58, v66
	v_and_b32_e32 v58, 0xffff0000, v61
	v_fmac_f32_e32 v58, v59, v67
	v_lshlrev_b32_e32 v59, 16, v62
	v_and_b32_e32 v60, 0xffff0000, v62
	v_fmac_f32_e32 v59, v52, v92
	v_fmac_f32_e32 v60, v53, v93
	v_lshlrev_b32_e32 v61, 16, v63
	v_and_b32_e32 v62, 0xffff0000, v63
	v_cvt_pk_bf16_f32 v52, v102, v56
	v_cvt_pk_bf16_f32 v53, v57, v58
	v_fmac_f32_e32 v61, v54, v94
	v_fmac_f32_e32 v62, v55, v95
	v_cvt_pk_bf16_f32 v54, v59, v60
	v_cvt_pk_bf16_f32 v55, v61, v62
	global_store_dwordx4 v[106:107], v[52:55], off offset:256
	v_lshlrev_b32_e32 v58, 16, v88
	v_and_b32_e32 v59, 0xffff0000, v88
	v_lshlrev_b64 v[52:53], 12, v[100:101]
	v_lshl_add_u64 v[52:53], s[40:41], 0, v[52:53]
	v_lshl_add_u64 v[52:53], v[52:53], 0, v[182:183]
	global_load_dwordx4 v[54:57], v[52:53], off
	v_lshlrev_b32_e32 v60, 16, v89
	v_and_b32_e32 v61, 0xffff0000, v89
	v_lshlrev_b32_e32 v62, 16, v90
	v_and_b32_e32 v63, 0xffff0000, v90
	v_lshlrev_b32_e32 v64, 16, v91
	v_and_b32_e32 v65, 0xffff0000, v91
	s_waitcnt vmcnt(0) lgkmcnt(0)
	v_lshlrev_b32_e32 v66, 16, v54
	v_fmac_f32_e32 v66, v48, v58
	v_and_b32_e32 v48, 0xffff0000, v54
	v_fmac_f32_e32 v48, v49, v59
	v_lshlrev_b32_e32 v49, 16, v55
	v_fmac_f32_e32 v49, v50, v60
	v_and_b32_e32 v50, 0xffff0000, v55
	v_fmac_f32_e32 v50, v51, v61
	v_lshlrev_b32_e32 v51, 16, v56
	v_and_b32_e32 v54, 0xffff0000, v56
	v_lshlrev_b32_e32 v55, 16, v57
	v_and_b32_e32 v56, 0xffff0000, v57
	v_fmac_f32_e32 v51, v44, v62
	v_fmac_f32_e32 v54, v45, v63
	v_fmac_f32_e32 v55, v46, v64
	v_fmac_f32_e32 v56, v47, v65
	v_cvt_pk_bf16_f32 v44, v66, v48
	v_cvt_pk_bf16_f32 v45, v49, v50
	v_cvt_pk_bf16_f32 v46, v51, v54
	v_cvt_pk_bf16_f32 v47, v55, v56
	global_store_dwordx4 v[52:53], v[44:47], off
	global_load_dwordx4 v[44:47], v[52:53], off offset:256
	v_lshlrev_b32_e32 v48, 16, v84
	v_and_b32_e32 v49, 0xffff0000, v84
	v_lshlrev_b32_e32 v50, 16, v85
	v_and_b32_e32 v51, 0xffff0000, v85
	v_lshlrev_b32_e32 v54, 16, v86
	v_and_b32_e32 v55, 0xffff0000, v86
	v_lshlrev_b32_e32 v56, 16, v87
	v_and_b32_e32 v57, 0xffff0000, v87
	s_waitcnt vmcnt(0) lgkmcnt(0)
	v_lshlrev_b32_e32 v58, 16, v44
	v_fmac_f32_e32 v58, v40, v48
	v_and_b32_e32 v40, 0xffff0000, v44
	v_fmac_f32_e32 v40, v41, v49
	v_lshlrev_b32_e32 v41, 16, v45
	v_fmac_f32_e32 v41, v42, v50
	v_and_b32_e32 v42, 0xffff0000, v45
	v_fmac_f32_e32 v42, v43, v51
	v_lshlrev_b32_e32 v43, 16, v46
	v_and_b32_e32 v44, 0xffff0000, v46
	v_fmac_f32_e32 v43, v36, v54
	v_fmac_f32_e32 v44, v37, v55
	v_lshlrev_b32_e32 v45, 16, v47
	v_and_b32_e32 v46, 0xffff0000, v47
	v_cvt_pk_bf16_f32 v36, v58, v40
	v_cvt_pk_bf16_f32 v37, v41, v42
	v_fmac_f32_e32 v45, v38, v56
	v_fmac_f32_e32 v46, v39, v57
	v_cvt_pk_bf16_f32 v38, v43, v44
	v_cvt_pk_bf16_f32 v39, v45, v46
	global_store_dwordx4 v[52:53], v[36:39], off offset:256
	v_lshlrev_b32_e32 v42, 16, v80
	v_and_b32_e32 v43, 0xffff0000, v80
	v_lshlrev_b64 v[36:37], 12, v[98:99]
	v_lshl_add_u64 v[36:37], s[40:41], 0, v[36:37]
	v_lshl_add_u64 v[36:37], v[36:37], 0, v[182:183]
	global_load_dwordx4 v[38:41], v[36:37], off
	v_lshlrev_b32_e32 v44, 16, v81
	v_and_b32_e32 v45, 0xffff0000, v81
	v_lshlrev_b32_e32 v46, 16, v82
	v_and_b32_e32 v47, 0xffff0000, v82
	v_lshlrev_b32_e32 v48, 16, v83
	v_and_b32_e32 v49, 0xffff0000, v83
	s_waitcnt vmcnt(0) lgkmcnt(0)
; __device__ __forceinline__ unsigned cvt_pk_bf16(float lo, float hi) { unsigned r; asm volatile("v_cvt_pk_bf16_f32 %0, %1, %2" : "=v"(r) : "v"(lo), "v"(hi)); return r; }
; __device__ __forceinline__ float bflo(unsigned u) { return __uint_as_float(u << 16); }
; __device__ __forceinline__ float bfhi(unsigned u) { return __uint_as_float(u & 0xffff0000u); }
; #define PG8_BAR __builtin_amdgcn_s_barrier()
;     __device__ __forceinline__ void operator()(const f32x4 (&acc)[2][2][4][2], const Unit& u, int wr, int wc, int fr, int fq) const {
;     ...
;             for (int m = 0; m < 4; ++m) { const size_t row = (size_t)(row0 + ai * HALF + m * 16);
; #pragma unroll
;                 for (int bj = 0; bj < 2; ++bj) { const int col = col0 + bj * HALF;
;                     const u32x4 gv = gall[m][bj];
;                     f32x4 v0 = acc[ai][bj][m][0], v1 = acc[ai][bj][m][1];
;                     v0[0] *= bflo(gv.x); v0[1] *= bfhi(gv.x); v0[2] *= bflo(gv.y); v0[3] *= bfhi(gv.y);
;                     v1[0] *= bflo(gv.z); v1[1] *= bfhi(gv.z); v1[2] *= bflo(gv.w); v1[3] *= bfhi(gv.w);
;                     bf16_t* op = O + row * ldc + col;
;                     if (MODE == 1) { const u32x4 ov = *(const u32x4*)op;
;                         v0[0] += bflo(ov.x); v0[1] += bfhi(ov.x); v0[2] += bflo(ov.y); v0[3] += bfhi(ov.y);
;                         v1[0] += bflo(ov.z); v1[1] += bfhi(ov.z); v1[2] += bflo(ov.w); v1[3] += bfhi(ov.w); }
;                     u32x4 w; w.x = cvt_pk_bf16(v0[0], v0[1]); w.y = cvt_pk_bf16(v0[2], v0[3]); w.z = cvt_pk_bf16(v1[0], v1[1]); w.w = cvt_pk_bf16(v1[2], v1[3]);
;                     *(u32x4*)op = w; } } }
; template <class Epi, class Sched, bool ALIGN_EPI = false, bool SP2 = false>
; __device__ __forceinline__ void gemm_phase(PG8_LAS unsigned char* lds, const Gemm g, const Sched& S, const Epi& E, int wave_s) {
;     ...
;         if (!has_next) break;
; #pragma unroll
;         for (int a = 0; a < 2; ++a)
; #pragma unroll
;             for (int b = 0; b < 2; ++b)
; #pragma unroll
;                 for (int m = 0; m < 4; ++m)
; #pragma unroll
;                     for (int n = 0; n < 2; ++n) acc[a][b][m][n] = (f32x4){0.f, 0.f, 0.f, 0.f};
;         cur = nxt; cA = nA; cB = nB; ++ui;
;         if constexpr (ALIGN_EPI) { if (wr == 1) PG8_BAR; }
	v_lshlrev_b32_e32 v50, 16, v38
	v_fmac_f32_e32 v50, v32, v42
	v_and_b32_e32 v32, 0xffff0000, v38
	v_fmac_f32_e32 v32, v33, v43
	v_lshlrev_b32_e32 v33, 16, v39
	v_fmac_f32_e32 v33, v34, v44
	v_and_b32_e32 v34, 0xffff0000, v39
	v_fmac_f32_e32 v34, v35, v45
	v_lshlrev_b32_e32 v35, 16, v40
	v_and_b32_e32 v38, 0xffff0000, v40
	v_lshlrev_b32_e32 v39, 16, v41
	v_and_b32_e32 v40, 0xffff0000, v41
	v_fmac_f32_e32 v35, v28, v46
	v_fmac_f32_e32 v38, v29, v47
	v_fmac_f32_e32 v39, v30, v48
	v_fmac_f32_e32 v40, v31, v49
	v_cvt_pk_bf16_f32 v28, v50, v32
	v_cvt_pk_bf16_f32 v29, v33, v34
	v_cvt_pk_bf16_f32 v30, v35, v38
	v_cvt_pk_bf16_f32 v31, v39, v40
	global_store_dwordx4 v[36:37], v[28:31], off
	global_load_dwordx4 v[28:31], v[36:37], off offset:256
	v_lshlrev_b32_e32 v32, 16, v76
	v_and_b32_e32 v33, 0xffff0000, v76
	v_lshlrev_b32_e32 v34, 16, v77
	v_and_b32_e32 v35, 0xffff0000, v77
	v_lshlrev_b32_e32 v38, 16, v78
	v_and_b32_e32 v39, 0xffff0000, v78
	v_lshlrev_b32_e32 v40, 16, v79
	v_and_b32_e32 v41, 0xffff0000, v79
	s_waitcnt vmcnt(0) lgkmcnt(0)
	v_lshlrev_b32_e32 v42, 16, v28
	v_fmac_f32_e32 v42, v24, v32
	v_and_b32_e32 v24, 0xffff0000, v28
	v_fmac_f32_e32 v24, v25, v33
	v_lshlrev_b32_e32 v25, 16, v29
	v_fmac_f32_e32 v25, v26, v34
	v_and_b32_e32 v26, 0xffff0000, v29
	v_fmac_f32_e32 v26, v27, v35
	v_lshlrev_b32_e32 v27, 16, v30
	v_and_b32_e32 v28, 0xffff0000, v30
	v_fmac_f32_e32 v27, v20, v38
	v_fmac_f32_e32 v28, v21, v39
	v_lshlrev_b32_e32 v29, 16, v31
	v_and_b32_e32 v30, 0xffff0000, v31
	v_cvt_pk_bf16_f32 v20, v42, v24
	v_cvt_pk_bf16_f32 v21, v25, v26
	v_fmac_f32_e32 v29, v22, v40
	v_fmac_f32_e32 v30, v23, v41
	v_cvt_pk_bf16_f32 v22, v27, v28
	v_cvt_pk_bf16_f32 v23, v29, v30
	global_store_dwordx4 v[36:37], v[20:23], off offset:256
	v_lshlrev_b32_e32 v26, 16, v72
	v_and_b32_e32 v27, 0xffff0000, v72
	v_lshlrev_b64 v[20:21], 12, v[96:97]
	v_lshl_add_u64 v[20:21], s[40:41], 0, v[20:21]
	v_lshl_add_u64 v[20:21], v[20:21], 0, v[182:183]
	global_load_dwordx4 v[22:25], v[20:21], off
	v_lshlrev_b32_e32 v28, 16, v73
	v_and_b32_e32 v29, 0xffff0000, v73
	v_lshlrev_b32_e32 v30, 16, v74
	v_and_b32_e32 v31, 0xffff0000, v74
	v_lshlrev_b32_e32 v32, 16, v75
	v_and_b32_e32 v33, 0xffff0000, v75
	s_waitcnt vmcnt(0) lgkmcnt(0)
	v_lshlrev_b32_e32 v34, 16, v22
	v_fmac_f32_e32 v34, v16, v26
	v_and_b32_e32 v16, 0xffff0000, v22
	v_fmac_f32_e32 v16, v17, v27
	v_lshlrev_b32_e32 v17, 16, v23
	v_fmac_f32_e32 v17, v18, v28
	v_and_b32_e32 v18, 0xffff0000, v23
	v_fmac_f32_e32 v18, v19, v29
	v_lshlrev_b32_e32 v19, 16, v24
	v_and_b32_e32 v22, 0xffff0000, v24
	v_lshlrev_b32_e32 v23, 16, v25
	v_and_b32_e32 v24, 0xffff0000, v25
	v_fmac_f32_e32 v19, v12, v30
	v_fmac_f32_e32 v22, v13, v31
	v_fmac_f32_e32 v23, v14, v32
	v_fmac_f32_e32 v24, v15, v33
	v_cvt_pk_bf16_f32 v12, v34, v16
	v_cvt_pk_bf16_f32 v13, v17, v18
	v_cvt_pk_bf16_f32 v14, v19, v22
	v_cvt_pk_bf16_f32 v15, v23, v24
	global_store_dwordx4 v[20:21], v[12:15], off
	global_load_dwordx4 v[12:15], v[20:21], off offset:256
	v_lshlrev_b32_e32 v16, 16, v68
	v_and_b32_e32 v17, 0xffff0000, v68
	v_lshlrev_b32_e32 v18, 16, v69
	v_and_b32_e32 v19, 0xffff0000, v69
	v_lshlrev_b32_e32 v22, 16, v70
	v_and_b32_e32 v23, 0xffff0000, v70
	v_lshlrev_b32_e32 v24, 16, v71
	v_and_b32_e32 v25, 0xffff0000, v71
	s_waitcnt vmcnt(0) lgkmcnt(0)
	v_lshlrev_b32_e32 v26, 16, v12
	v_fmac_f32_e32 v26, v8, v16
	v_and_b32_e32 v8, 0xffff0000, v12
	v_fmac_f32_e32 v8, v9, v17
	v_lshlrev_b32_e32 v9, 16, v13
	v_fmac_f32_e32 v9, v10, v18
	v_and_b32_e32 v10, 0xffff0000, v13
	v_fmac_f32_e32 v10, v11, v19
	v_lshlrev_b32_e32 v11, 16, v14
	v_and_b32_e32 v12, 0xffff0000, v14
	v_lshlrev_b32_e32 v13, 16, v15
	v_and_b32_e32 v14, 0xffff0000, v15
	v_fmac_f32_e32 v11, v4, v22
	v_fmac_f32_e32 v12, v5, v23
	v_fmac_f32_e32 v13, v6, v24
	v_fmac_f32_e32 v14, v7, v25
	v_cvt_pk_bf16_f32 v4, v26, v8
	v_cvt_pk_bf16_f32 v5, v9, v10
	v_cvt_pk_bf16_f32 v6, v11, v12
	v_cvt_pk_bf16_f32 v7, v13, v14
	global_store_dwordx4 v[20:21], v[4:7], off offset:256
	s_cbranch_vccnz .LBB0_580
	s_andn2_b64 vcc, exec, s[42:43]
	s_cbranch_vccnz .LBB0_579
	s_barrier
	s_branch .LBB0_579

; __device__ __forceinline__ unsigned cvt_pk_bf16(float lo, float hi) { unsigned r; asm volatile("v_cvt_pk_bf16_f32 %0, %1, %2" : "=v"(r) : "v"(lo), "v"(hi)); return r; }
;     __device__ __forceinline__ void operator()(const f32x4 (&acc)[2][2][4][2], const Unit& u, int wr, int wc, int fr, int fq) const {
;         const int row0 = u.pm * BM + wr * 64 + fr; const int col0 = u.pn * BM + wc * 32 + 8 * fq;
;         const float* gp = gate + (size_t)(u.pm >> 4) * gstride + col0;
;         f32x4 g0[2], g1[2];
; #pragma unroll
;         for (int bj = 0; bj < 2; ++bj) { g0[bj] = *(const f32x4*)(gp + bj * HALF); g1[bj] = *(const f32x4*)(gp + bj * HALF + 4); }
;         if (xin_f) {
; #pragma unroll
;             for (int ai = 0; ai < 2; ++ai)
; #pragma unroll
;                 for (int m = 0; m < 4; ++m) { const size_t off = (size_t)(row0 + ai * HALF + m * 16) * 2048 + col0;
; #pragma unroll
;                     for (int bj = 0; bj < 2; ++bj) { const f32x4 x0 = *(const f32x4*)(xin_f + off + bj * HALF), x1 = *(const f32x4*)(xin_f + off + bj * HALF + 4);
;                         const f32x4 v0 = x0 + g0[bj] * acc[ai][bj][m][0], v1 = x1 + g1[bj] * acc[ai][bj][m][1];
;                         u32x4 w; w.x = cvt_pk_bf16(v0[0], v0[1]); w.y = cvt_pk_bf16(v0[2], v0[3]); w.z = cvt_pk_bf16(v1[0], v1[1]); w.w = cvt_pk_bf16(v1[2], v1[3]);
;                         *(u32x4*)(out + off + bj * HALF) = w; } }
.LBB0_664:
	s_ashr_i32 s5, s33, 4
	s_mul_hi_i32 s7, s5, 0xc000
	s_mul_i32 s5, s5, 0xc000
	v_lshl_or_b32 v154, s56, 8, v212
	s_add_u32 s18, s52, s5
	s_addc_u32 s19, s53, s7
	v_ashrrev_i32_e32 v155, 31, v154
	v_lshl_add_u64 v[108:109], v[154:155], 2, s[18:19]
	global_load_dwordx4 v[120:123], v[108:109], off
	global_load_dwordx4 v[116:119], v[108:109], off offset:16
	global_load_dwordx4 v[112:115], v[108:109], off offset:512
	s_nop 0
	global_load_dwordx4 v[108:111], v[108:109], off offset:528
	v_lshl_add_u32 v160, s33, 8, v173
	v_or_b32_e32 v158, 16, v160
	v_or_b32_e32 v156, 32, v160
	v_or_b32_e32 v152, 48, v160
	v_readlane_b32 s66, v252, 18
	s_andn2_b64 vcc, exec, s[40:41]
	v_ashrrev_i32_e32 v161, 31, v160
	v_ashrrev_i32_e32 v159, 31, v158
	v_ashrrev_i32_e32 v157, 31, v156
	v_ashrrev_i32_e32 v153, 31, v152
	v_readlane_b32 s67, v252, 19
	s_cbranch_vccnz .LBB0_670
	v_lshlrev_b64 v[148:149], 11, v[160:161]
	v_lshl_add_u64 v[148:149], v[148:149], 0, v[154:155]
	v_lshl_add_u64 v[150:151], v[148:149], 2, s[24:25]
	v_mov_b32_e32 v228, v148
	v_mov_b32_e32 v229, v149
	v_lshl_add_u64 v[228:229], v[228:229], 2, s[24:25]
	global_load_dwordx4 v[232:235], v[228:229], off offset:16
	s_nop 0
	global_load_dwordx4 v[228:231], v[228:229], off
	v_mov_b32_e32 v236, v148
	v_mov_b32_e32 v237, v149
	v_lshl_add_u64 v[236:237], v[236:237], 2, s[24:25]
	global_load_dwordx4 v[240:243], v[236:237], off offset:528
	s_nop 0
	global_load_dwordx4 v[236:239], v[236:237], off offset:512
	v_add_co_u32_e32 v244, vcc, 0x8000, v148
	s_nop 1
	v_addc_co_u32_e32 v245, vcc, 0, v149, vcc
	v_lshl_add_u64 v[244:245], v[244:245], 2, s[24:25]
	global_load_dwordx4 v[248:251], v[244:245], off offset:16
	s_nop 0
	global_load_dwordx4 v[244:247], v[244:245], off
	s_mov_b64 s[18:19], 0x40000
	s_waitcnt vmcnt(4) lgkmcnt(0)
	v_pk_fma_f32 v[166:167], v[146:147], v[122:123], v[230:231]
	v_pk_fma_f32 v[190:191], v[144:145], v[120:121], v[228:229]
	v_pk_fma_f32 v[192:193], v[142:143], v[118:119], v[234:235]
	v_pk_fma_f32 v[164:165], v[140:141], v[116:117], v[232:233]
	v_add_co_u32_e32 v228, vcc, 0x8000, v148
	s_nop 1
	v_addc_co_u32_e32 v229, vcc, 0, v149, vcc
	v_lshl_add_u64 v[228:229], v[228:229], 2, s[24:25]
	global_load_dwordx4 v[232:235], v[228:229], off offset:528
	s_nop 0
	global_load_dwordx4 v[228:231], v[228:229], off offset:512
	v_cvt_pk_bf16_f32 v162, v190, v191
	v_cvt_pk_bf16_f32 v163, v166, v167
	v_lshl_add_u64 v[166:167], v[148:149], 1, s[20:21]
	v_cvt_pk_bf16_f32 v164, v164, v165
	v_cvt_pk_bf16_f32 v165, v192, v193
	global_store_dwordx4 v[166:167], v[162:165], off
	s_waitcnt vmcnt(5)
	v_pk_fma_f32 v[150:151], v[130:131], v[114:115], v[238:239]
	v_pk_fma_f32 v[190:191], v[128:129], v[112:113], v[236:237]
	v_pk_fma_f32 v[192:193], v[126:127], v[110:111], v[242:243]
	v_pk_fma_f32 v[164:165], v[124:125], v[108:109], v[240:241]
	v_add_co_u32_e32 v236, vcc, 0x10000, v148
	s_nop 1
	v_addc_co_u32_e32 v237, vcc, 0, v149, vcc
	v_lshl_add_u64 v[236:237], v[236:237], 2, s[24:25]
	global_load_dwordx4 v[240:243], v[236:237], off offset:16
	s_nop 0
	global_load_dwordx4 v[236:239], v[236:237], off
	v_cvt_pk_bf16_f32 v162, v190, v191
	v_cvt_pk_bf16_f32 v163, v150, v151
	v_lshlrev_b64 v[150:151], 11, v[158:159]
	v_lshl_add_u64 v[150:151], v[150:151], 0, v[154:155]
	v_cvt_pk_bf16_f32 v164, v164, v165
	v_cvt_pk_bf16_f32 v165, v192, v193
	global_store_dwordx4 v[166:167], v[162:165], off offset:256
	v_lshl_add_u64 v[166:167], v[150:151], 2, s[24:25]
	v_lshl_add_u64 v[150:151], v[150:151], 1, s[20:21]
	s_waitcnt vmcnt(6)
	v_pk_fma_f32 v[194:195], v[134:135], v[118:119], v[250:251]
	v_pk_fma_f32 v[164:165], v[132:133], v[116:117], v[248:249]
	v_pk_fma_f32 v[192:193], v[138:139], v[122:123], v[246:247]
	v_pk_fma_f32 v[190:191], v[136:137], v[120:121], v[244:245]
	v_add_co_u32_e32 v244, vcc, 0x10000, v148
	s_nop 1
	v_addc_co_u32_e32 v245, vcc, 0, v149, vcc
	v_lshl_add_u64 v[244:245], v[244:245], 2, s[24:25]
	global_load_dwordx4 v[248:251], v[244:245], off offset:528
	s_nop 0
	global_load_dwordx4 v[244:247], v[244:245], off offset:512
	s_nop 0
	v_cvt_pk_bf16_f32 v162, v190, v191
	v_cvt_pk_bf16_f32 v163, v192, v193
	v_cvt_pk_bf16_f32 v164, v164, v165
	v_cvt_pk_bf16_f32 v165, v194, v195
	global_store_dwordx4 v[150:151], v[162:165], off
	s_waitcnt vmcnt(7)
	v_pk_fma_f32 v[166:167], v[106:107], v[114:115], v[230:231]
	v_pk_fma_f32 v[192:193], v[102:103], v[110:111], v[234:235]
	v_pk_fma_f32 v[164:165], v[100:101], v[108:109], v[232:233]
	v_pk_fma_f32 v[190:191], v[104:105], v[112:113], v[228:229]
	v_add_co_u32_e32 v228, vcc, 0x18000, v148
	s_nop 1
	v_addc_co_u32_e32 v229, vcc, 0, v149, vcc
	v_lshl_add_u64 v[228:229], v[228:229], 2, s[24:25]
	global_load_dwordx4 v[232:235], v[228:229], off offset:16
	s_nop 0
	global_load_dwordx4 v[228:231], v[228:229], off
	s_nop 0
	v_cvt_pk_bf16_f32 v162, v190, v191
	v_cvt_pk_bf16_f32 v163, v166, v167
	v_cvt_pk_bf16_f32 v164, v164, v165
	v_cvt_pk_bf16_f32 v165, v192, v193
	global_store_dwordx4 v[150:151], v[162:165], off offset:256
	v_lshlrev_b64 v[150:151], 11, v[156:157]
	v_lshl_add_u64 v[150:151], v[150:151], 0, v[154:155]
	v_lshl_add_u64 v[166:167], v[150:151], 2, s[24:25]
	v_lshl_add_u64 v[150:151], v[150:151], 1, s[20:21]
	s_waitcnt vmcnt(7)
	v_pk_fma_f32 v[194:195], v[94:95], v[118:119], v[242:243]
	v_pk_fma_f32 v[164:165], v[92:93], v[116:117], v[240:241]
	v_pk_fma_f32 v[192:193], v[98:99], v[122:123], v[238:239]
	v_pk_fma_f32 v[190:191], v[96:97], v[120:121], v[236:237]
	v_add_co_u32_e32 v236, vcc, 0x18000, v148
	s_nop 1
	v_addc_co_u32_e32 v237, vcc, 0, v149, vcc
	v_lshl_add_u64 v[236:237], v[236:237], 2, s[24:25]
	global_load_dwordx4 v[240:243], v[236:237], off offset:528
	s_nop 0
	global_load_dwordx4 v[236:239], v[236:237], off offset:512
	s_nop 0
	v_cvt_pk_bf16_f32 v162, v190, v191
	v_cvt_pk_bf16_f32 v163, v192, v193
	v_cvt_pk_bf16_f32 v164, v164, v165
	v_cvt_pk_bf16_f32 v165, v194, v195
	global_store_dwordx4 v[150:151], v[162:165], off
	s_waitcnt vmcnt(7)
; __device__ __forceinline__ unsigned cvt_pk_bf16(float lo, float hi) { unsigned r; asm volatile("v_cvt_pk_bf16_f32 %0, %1, %2" : "=v"(r) : "v"(lo), "v"(hi)); return r; }
;     __device__ __forceinline__ void operator()(const f32x4 (&acc)[2][2][4][2], const Unit& u, int wr, int wc, int fr, int fq) const {
;     ...
;                 for (int m = 0; m < 4; ++m) { const size_t off = (size_t)(row0 + ai * HALF + m * 16) * 2048 + col0;
; #pragma unroll
;                     for (int bj = 0; bj < 2; ++bj) { const f32x4 x0 = *(const f32x4*)(xin_f + off + bj * HALF), x1 = *(const f32x4*)(xin_f + off + bj * HALF + 4);
;                         const f32x4 v0 = x0 + g0[bj] * acc[ai][bj][m][0], v1 = x1 + g1[bj] * acc[ai][bj][m][1];
;                         u32x4 w; w.x = cvt_pk_bf16(v0[0], v0[1]); w.y = cvt_pk_bf16(v0[2], v0[3]); w.z = cvt_pk_bf16(v1[0], v1[1]); w.w = cvt_pk_bf16(v1[2], v1[3]);
;                         *(u32x4*)(out + off + bj * HALF) = w; } }
	v_pk_fma_f32 v[166:167], v[90:91], v[114:115], v[246:247]
	v_pk_fma_f32 v[192:193], v[86:87], v[110:111], v[250:251]
	v_pk_fma_f32 v[164:165], v[84:85], v[108:109], v[248:249]
	v_pk_fma_f32 v[190:191], v[88:89], v[112:113], v[244:245]
	v_add_co_u32_e32 v244, vcc, 0x40000, v148
	s_nop 1
	v_addc_co_u32_e32 v245, vcc, 0, v149, vcc
	v_lshl_add_u64 v[244:245], v[244:245], 2, s[24:25]
	global_load_dwordx4 v[248:251], v[244:245], off offset:16
	s_nop 0
	global_load_dwordx4 v[244:247], v[244:245], off
	s_nop 0
	v_cvt_pk_bf16_f32 v162, v190, v191
	v_cvt_pk_bf16_f32 v163, v166, v167
	v_cvt_pk_bf16_f32 v164, v164, v165
	v_cvt_pk_bf16_f32 v165, v192, v193
	global_store_dwordx4 v[150:151], v[162:165], off offset:256
	v_lshlrev_b64 v[150:151], 11, v[152:153]
	v_lshl_add_u64 v[150:151], v[150:151], 0, v[154:155]
	v_lshl_add_u64 v[166:167], v[150:151], 2, s[24:25]
	v_lshl_add_u64 v[150:151], v[150:151], 1, s[20:21]
	s_waitcnt vmcnt(7)
	v_pk_fma_f32 v[194:195], v[78:79], v[118:119], v[234:235]
	v_pk_fma_f32 v[164:165], v[76:77], v[116:117], v[232:233]
	v_pk_fma_f32 v[192:193], v[82:83], v[122:123], v[230:231]
	v_pk_fma_f32 v[190:191], v[80:81], v[120:121], v[228:229]
	v_add_co_u32_e32 v228, vcc, 0x40000, v148
	s_nop 1
	v_addc_co_u32_e32 v229, vcc, 0, v149, vcc
	v_lshl_add_u64 v[228:229], v[228:229], 2, s[24:25]
	global_load_dwordx4 v[232:235], v[228:229], off offset:528
	s_nop 0
	global_load_dwordx4 v[228:231], v[228:229], off offset:512
	s_nop 0
	v_cvt_pk_bf16_f32 v162, v190, v191
	v_cvt_pk_bf16_f32 v163, v192, v193
	v_cvt_pk_bf16_f32 v164, v164, v165
	v_cvt_pk_bf16_f32 v165, v194, v195
	global_store_dwordx4 v[150:151], v[162:165], off
	s_waitcnt vmcnt(7)
	v_pk_fma_f32 v[166:167], v[74:75], v[114:115], v[238:239]
	v_pk_fma_f32 v[192:193], v[70:71], v[110:111], v[242:243]
	v_pk_fma_f32 v[164:165], v[68:69], v[108:109], v[240:241]
	v_pk_fma_f32 v[190:191], v[72:73], v[112:113], v[236:237]
	v_add_co_u32_e32 v236, vcc, 0x48000, v148
	s_nop 1
	v_addc_co_u32_e32 v237, vcc, 0, v149, vcc
	v_lshl_add_u64 v[236:237], v[236:237], 2, s[24:25]
	global_load_dwordx4 v[240:243], v[236:237], off offset:16
	s_nop 0
	global_load_dwordx4 v[236:239], v[236:237], off
	s_nop 0
	v_cvt_pk_bf16_f32 v162, v190, v191
	v_cvt_pk_bf16_f32 v163, v166, v167
	v_cvt_pk_bf16_f32 v164, v164, v165
	v_cvt_pk_bf16_f32 v165, v192, v193
	global_store_dwordx4 v[150:151], v[162:165], off offset:256
	v_lshl_add_u64 v[150:151], v[148:149], 0, s[18:19]
	v_lshl_add_u64 v[166:167], v[150:151], 2, s[24:25]
	v_lshl_add_u64 v[150:151], v[150:151], 1, s[20:21]
	s_mov_b64 s[18:19], 0x48000
	s_waitcnt vmcnt(7)
	v_pk_fma_f32 v[194:195], v[62:63], v[118:119], v[250:251]
	v_pk_fma_f32 v[164:165], v[60:61], v[116:117], v[248:249]
	v_pk_fma_f32 v[192:193], v[66:67], v[122:123], v[246:247]
	v_pk_fma_f32 v[190:191], v[64:65], v[120:121], v[244:245]
	v_add_co_u32_e32 v244, vcc, 0x48000, v148
	s_nop 1
	v_addc_co_u32_e32 v245, vcc, 0, v149, vcc
	v_lshl_add_u64 v[244:245], v[244:245], 2, s[24:25]
	global_load_dwordx4 v[248:251], v[244:245], off offset:528
	s_nop 0
	global_load_dwordx4 v[244:247], v[244:245], off offset:512
	s_nop 0
	v_cvt_pk_bf16_f32 v162, v190, v191
	v_cvt_pk_bf16_f32 v163, v192, v193
	v_cvt_pk_bf16_f32 v164, v164, v165
	v_cvt_pk_bf16_f32 v165, v194, v195
	global_store_dwordx4 v[150:151], v[162:165], off
	s_waitcnt vmcnt(7)
	v_pk_fma_f32 v[166:167], v[58:59], v[114:115], v[230:231]
	v_pk_fma_f32 v[192:193], v[54:55], v[110:111], v[234:235]
	v_pk_fma_f32 v[164:165], v[52:53], v[108:109], v[232:233]
	v_pk_fma_f32 v[190:191], v[56:57], v[112:113], v[228:229]
	v_add_co_u32_e32 v228, vcc, 0x50000, v148
	s_nop 1
	v_addc_co_u32_e32 v229, vcc, 0, v149, vcc
	v_lshl_add_u64 v[228:229], v[228:229], 2, s[24:25]
	global_load_dwordx4 v[232:235], v[228:229], off offset:16
	s_nop 0
	global_load_dwordx4 v[228:231], v[228:229], off
	s_nop 0
	v_cvt_pk_bf16_f32 v162, v190, v191
	v_cvt_pk_bf16_f32 v163, v166, v167
	v_cvt_pk_bf16_f32 v164, v164, v165
	v_cvt_pk_bf16_f32 v165, v192, v193
	global_store_dwordx4 v[150:151], v[162:165], off offset:256
	v_lshl_add_u64 v[150:151], v[148:149], 0, s[18:19]
	v_lshl_add_u64 v[166:167], v[150:151], 2, s[24:25]
	v_lshl_add_u64 v[150:151], v[150:151], 1, s[20:21]
	s_mov_b64 s[18:19], 0x50000
	s_waitcnt vmcnt(7)
	v_pk_fma_f32 v[194:195], v[46:47], v[118:119], v[242:243]
	v_pk_fma_f32 v[164:165], v[44:45], v[116:117], v[240:241]
	v_pk_fma_f32 v[192:193], v[50:51], v[122:123], v[238:239]
	v_pk_fma_f32 v[190:191], v[48:49], v[120:121], v[236:237]
	v_add_co_u32_e32 v236, vcc, 0x50000, v148
	s_nop 1
	v_addc_co_u32_e32 v237, vcc, 0, v149, vcc
	v_lshl_add_u64 v[236:237], v[236:237], 2, s[24:25]
	global_load_dwordx4 v[240:243], v[236:237], off offset:528
	s_nop 0
	global_load_dwordx4 v[236:239], v[236:237], off offset:512
	s_nop 0
	v_cvt_pk_bf16_f32 v162, v190, v191
	v_cvt_pk_bf16_f32 v163, v192, v193
	v_cvt_pk_bf16_f32 v164, v164, v165
	v_cvt_pk_bf16_f32 v165, v194, v195
	global_store_dwordx4 v[150:151], v[162:165], off
	s_waitcnt vmcnt(7)
	v_pk_fma_f32 v[166:167], v[42:43], v[114:115], v[246:247]
	v_pk_fma_f32 v[192:193], v[38:39], v[110:111], v[250:251]
	v_pk_fma_f32 v[164:165], v[36:37], v[108:109], v[248:249]
	v_pk_fma_f32 v[190:191], v[40:41], v[112:113], v[244:245]
	v_add_co_u32_e32 v244, vcc, 0x58000, v148
	s_nop 1
	v_addc_co_u32_e32 v245, vcc, 0, v149, vcc
	v_lshl_add_u64 v[244:245], v[244:245], 2, s[24:25]
	global_load_dwordx4 v[248:251], v[244:245], off offset:16
	s_nop 0
	global_load_dwordx4 v[244:247], v[244:245], off
	s_nop 0
	v_cvt_pk_bf16_f32 v162, v190, v191
	v_cvt_pk_bf16_f32 v163, v166, v167
	v_cvt_pk_bf16_f32 v164, v164, v165
	v_cvt_pk_bf16_f32 v165, v192, v193
	global_store_dwordx4 v[150:151], v[162:165], off offset:256
	v_lshl_add_u64 v[150:151], v[148:149], 0, s[18:19]
	v_lshl_add_u64 v[166:167], v[150:151], 2, s[24:25]
	v_lshl_add_u64 v[150:151], v[150:151], 1, s[20:21]
	s_mov_b64 s[18:19], 0x58000
	s_waitcnt vmcnt(7)
; __device__ __forceinline__ unsigned cvt_pk_bf16(float lo, float hi) { unsigned r; asm volatile("v_cvt_pk_bf16_f32 %0, %1, %2" : "=v"(r) : "v"(lo), "v"(hi)); return r; }
; __device__ __forceinline__ float bflo(unsigned u) { return __uint_as_float(u << 16); }
; __device__ __forceinline__ float bfhi(unsigned u) { return __uint_as_float(u & 0xffff0000u); }
;     __device__ __forceinline__ void operator()(const f32x4 (&acc)[2][2][4][2], const Unit& u, int wr, int wc, int fr, int fq) const {
;     ...
;                 for (int m = 0; m < 4; ++m) { const size_t off = (size_t)(row0 + ai * HALF + m * 16) * 2048 + col0;
; #pragma unroll
;                     for (int bj = 0; bj < 2; ++bj) { const f32x4 x0 = *(const f32x4*)(xin_f + off + bj * HALF), x1 = *(const f32x4*)(xin_f + off + bj * HALF + 4);
;                         const f32x4 v0 = x0 + g0[bj] * acc[ai][bj][m][0], v1 = x1 + g1[bj] * acc[ai][bj][m][1];
;                         u32x4 w; w.x = cvt_pk_bf16(v0[0], v0[1]); w.y = cvt_pk_bf16(v0[2], v0[3]); w.z = cvt_pk_bf16(v1[0], v1[1]); w.w = cvt_pk_bf16(v1[2], v1[3]);
;                         *(u32x4*)(out + off + bj * HALF) = w; } }
;     ...
;             for (int ai = 0; ai < 2; ++ai) { u32x4 xv[4][2];
; #pragma unroll
;                 for (int m = 0; m < 4; ++m)
; #pragma unroll
;                     for (int bj = 0; bj < 2; ++bj) xv[m][bj] = *(const u32x4*)(xin_b + (size_t)(row0 + ai * HALF + m * 16) * 2048 + col0 + bj * HALF);
; #pragma unroll
;                 for (int m = 0; m < 4; ++m) { const size_t off = (size_t)(row0 + ai * HALF + m * 16) * 2048 + col0;
; #pragma unroll
;                     for (int bj = 0; bj < 2; ++bj) { const u32x4 q = xv[m][bj];
;                         const f32x4 x0 = {bflo(q.x), bfhi(q.x), bflo(q.y), bfhi(q.y)}, x1 = {bflo(q.z), bfhi(q.z), bflo(q.w), bfhi(q.w)};
;                         const f32x4 v0 = x0 + g0[bj] * acc[ai][bj][m][0], v1 = x1 + g1[bj] * acc[ai][bj][m][1];
;                         u32x4 w; w.x = cvt_pk_bf16(v0[0], v0[1]); w.y = cvt_pk_bf16(v0[2], v0[3]); w.z = cvt_pk_bf16(v1[0], v1[1]); w.w = cvt_pk_bf16(v1[2], v1[3]);
;                         *(u32x4*)(out + off + bj * HALF) = w; } } }
	v_pk_fma_f32 v[194:195], v[30:31], v[118:119], v[234:235]
	v_pk_fma_f32 v[164:165], v[28:29], v[116:117], v[232:233]
	v_pk_fma_f32 v[192:193], v[34:35], v[122:123], v[230:231]
	v_pk_fma_f32 v[190:191], v[32:33], v[120:121], v[228:229]
	v_add_co_u32_e32 v228, vcc, 0x58000, v148
	s_nop 1
	v_addc_co_u32_e32 v229, vcc, 0, v149, vcc
	v_lshl_add_u64 v[228:229], v[228:229], 2, s[24:25]
	global_load_dwordx4 v[232:235], v[228:229], off offset:528
	s_nop 0
	global_load_dwordx4 v[228:231], v[228:229], off offset:512
	s_nop 0
	v_cvt_pk_bf16_f32 v162, v190, v191
	v_cvt_pk_bf16_f32 v163, v192, v193
	v_cvt_pk_bf16_f32 v164, v164, v165
	v_cvt_pk_bf16_f32 v165, v194, v195
	global_store_dwordx4 v[150:151], v[162:165], off
	s_waitcnt vmcnt(7)
	v_pk_fma_f32 v[166:167], v[26:27], v[114:115], v[238:239]
	v_pk_fma_f32 v[190:191], v[24:25], v[112:113], v[236:237]
	v_pk_fma_f32 v[192:193], v[22:23], v[110:111], v[242:243]
	v_pk_fma_f32 v[164:165], v[20:21], v[108:109], v[240:241]
	v_cvt_pk_bf16_f32 v162, v190, v191
	v_cvt_pk_bf16_f32 v163, v166, v167
	v_lshl_add_u64 v[166:167], v[148:149], 0, s[18:19]
	v_cvt_pk_bf16_f32 v164, v164, v165
	v_cvt_pk_bf16_f32 v165, v192, v193
	global_store_dwordx4 v[150:151], v[162:165], off offset:256
	v_lshl_add_u64 v[190:191], v[166:167], 2, s[24:25]
	s_waitcnt vmcnt(5)
	v_pk_fma_f32 v[192:193], v[14:15], v[118:119], v[250:251]
	v_pk_fma_f32 v[162:163], v[16:17], v[120:121], v[244:245]
	v_pk_fma_f32 v[150:151], v[12:13], v[116:117], v[248:249]
	v_cvt_pk_bf16_f32 v148, v162, v163
	v_lshl_add_u64 v[162:163], v[166:167], 1, s[20:21]
	v_pk_fma_f32 v[164:165], v[18:19], v[122:123], v[246:247]
	s_nop 0
	v_cvt_pk_bf16_f32 v149, v164, v165
	v_cvt_pk_bf16_f32 v150, v150, v151
	v_cvt_pk_bf16_f32 v151, v192, v193
	global_store_dwordx4 v[162:163], v[148:151], off
	s_waitcnt vmcnt(3)
	v_pk_fma_f32 v[190:191], v[6:7], v[110:111], v[234:235]
	v_pk_fma_f32 v[150:151], v[4:5], v[108:109], v[232:233]
	v_pk_fma_f32 v[166:167], v[10:11], v[114:115], v[230:231]
	v_pk_fma_f32 v[164:165], v[8:9], v[112:113], v[228:229]
	s_nop 0
	v_cvt_pk_bf16_f32 v148, v164, v165
	v_cvt_pk_bf16_f32 v149, v166, v167
	v_cvt_pk_bf16_f32 v150, v150, v151
	v_cvt_pk_bf16_f32 v151, v190, v191
	s_cbranch_execnz .LBB0_667
.LBB0_666:
	v_lshlrev_b64 v[190:191], 1, v[154:155]
	v_lshl_add_u64 v[192:193], s[20:21], 0, v[190:191]
	v_lshlrev_b64 v[194:195], 12, v[160:161]
	v_lshl_add_u64 v[148:149], v[192:193], 0, v[194:195]
	global_load_dwordx4 v[214:217], v[148:149], off
	global_load_dwordx4 v[218:221], v[148:149], off offset:256
	v_lshlrev_b64 v[200:201], 12, v[158:159]
	v_lshl_add_u64 v[148:149], v[192:193], 0, v[200:201]
	global_load_dwordx4 v[222:225], v[148:149], off
	global_load_dwordx4 v[164:167], v[148:149], off offset:256
	v_lshlrev_b64 v[198:199], 12, v[156:157]
	v_lshl_add_u64 v[148:149], v[192:193], 0, v[198:199]
	global_load_dwordx4 v[160:163], v[148:149], off
	global_load_dwordx4 v[156:159], v[148:149], off offset:256
	v_lshlrev_b64 v[196:197], 12, v[152:153]
	v_lshl_add_u64 v[148:149], v[192:193], 0, v[196:197]
	global_load_dwordx4 v[152:155], v[148:149], off
	s_nop 0
	global_load_dwordx4 v[148:151], v[148:149], off offset:256
	s_mov_b64 s[18:19], 0x80000
	s_waitcnt vmcnt(0) lgkmcnt(0)
	v_lshlrev_b32_e32 v226, 16, v214
	v_and_b32_e32 v227, 0xffff0000, v214
	v_lshlrev_b32_e32 v214, 16, v215
	v_and_b32_e32 v215, 0xffff0000, v215
	v_lshlrev_b32_e32 v228, 16, v216
	v_and_b32_e32 v229, 0xffff0000, v216
	v_lshlrev_b32_e32 v216, 16, v217
	v_and_b32_e32 v217, 0xffff0000, v217
	v_pk_fma_f32 v[144:145], v[144:145], v[120:121], v[226:227]
	v_pk_fma_f32 v[146:147], v[146:147], v[122:123], v[214:215]
	v_pk_fma_f32 v[214:215], v[142:143], v[118:119], v[216:217]
	v_pk_fma_f32 v[142:143], v[140:141], v[116:117], v[228:229]
	v_cvt_pk_bf16_f32 v140, v144, v145
	v_lshl_add_u64 v[144:145], s[20:21], 0, v[194:195]
	v_cvt_pk_bf16_f32 v141, v146, v147
	v_cvt_pk_bf16_f32 v142, v142, v143
	v_cvt_pk_bf16_f32 v143, v214, v215
	v_lshl_add_u64 v[144:145], v[144:145], 0, v[190:191]
	global_store_dwordx4 v[144:145], v[140:143], off
	v_lshlrev_b32_e32 v146, 16, v220
	v_and_b32_e32 v147, 0xffff0000, v220
	v_lshlrev_b32_e32 v140, 16, v218
	v_and_b32_e32 v141, 0xffff0000, v218
	v_lshlrev_b32_e32 v142, 16, v219
	v_and_b32_e32 v143, 0xffff0000, v219
	v_lshlrev_b32_e32 v214, 16, v221
	v_and_b32_e32 v215, 0xffff0000, v221
	v_pk_fma_f32 v[130:131], v[130:131], v[114:115], v[142:143]
	v_pk_fma_f32 v[128:129], v[128:129], v[112:113], v[140:141]
	v_pk_fma_f32 v[140:141], v[126:127], v[110:111], v[214:215]
	v_pk_fma_f32 v[126:127], v[124:125], v[108:109], v[146:147]
	v_cvt_pk_bf16_f32 v124, v128, v129
	v_cvt_pk_bf16_f32 v125, v130, v131
	v_lshlrev_b32_e32 v128, 16, v224
	v_cvt_pk_bf16_f32 v126, v126, v127
	v_cvt_pk_bf16_f32 v127, v140, v141
	global_store_dwordx4 v[144:145], v[124:127], off offset:256
	v_and_b32_e32 v129, 0xffff0000, v224
	v_lshlrev_b32_e32 v130, 16, v225
	v_lshlrev_b32_e32 v124, 16, v222
	v_and_b32_e32 v125, 0xffff0000, v222
	v_lshlrev_b32_e32 v126, 16, v223
	v_and_b32_e32 v127, 0xffff0000, v223
	v_pk_fma_f32 v[124:125], v[136:137], v[120:121], v[124:125]
	v_and_b32_e32 v131, 0xffff0000, v225
	v_pk_fma_f32 v[138:139], v[138:139], v[122:123], v[126:127]
	v_pk_fma_f32 v[128:129], v[132:133], v[116:117], v[128:129]
	v_cvt_pk_bf16_f32 v126, v124, v125
	v_lshl_add_u64 v[124:125], s[20:21], 0, v[200:201]
	v_pk_fma_f32 v[130:131], v[134:135], v[118:119], v[130:131]
	v_cvt_pk_bf16_f32 v127, v138, v139
	v_cvt_pk_bf16_f32 v128, v128, v129
	v_lshl_add_u64 v[124:125], v[124:125], 0, v[190:191]
	v_cvt_pk_bf16_f32 v129, v130, v131
	global_store_dwordx4 v[124:125], v[126:129], off
	v_lshlrev_b32_e32 v130, 16, v166
; __device__ __forceinline__ unsigned cvt_pk_bf16(float lo, float hi) { unsigned r; asm volatile("v_cvt_pk_bf16_f32 %0, %1, %2" : "=v"(r) : "v"(lo), "v"(hi)); return r; }
; __device__ __forceinline__ float bflo(unsigned u) { return __uint_as_float(u << 16); }
; __device__ __forceinline__ float bfhi(unsigned u) { return __uint_as_float(u & 0xffff0000u); }
;     __device__ __forceinline__ void operator()(const f32x4 (&acc)[2][2][4][2], const Unit& u, int wr, int wc, int fr, int fq) const {
;     ...
;             for (int ai = 0; ai < 2; ++ai) { u32x4 xv[4][2];
; #pragma unroll
;                 for (int m = 0; m < 4; ++m)
; #pragma unroll
;                     for (int bj = 0; bj < 2; ++bj) xv[m][bj] = *(const u32x4*)(xin_b + (size_t)(row0 + ai * HALF + m * 16) * 2048 + col0 + bj * HALF);
; #pragma unroll
;                 for (int m = 0; m < 4; ++m) { const size_t off = (size_t)(row0 + ai * HALF + m * 16) * 2048 + col0;
; #pragma unroll
;                     for (int bj = 0; bj < 2; ++bj) { const u32x4 q = xv[m][bj];
;                         const f32x4 x0 = {bflo(q.x), bfhi(q.x), bflo(q.y), bfhi(q.y)}, x1 = {bflo(q.z), bfhi(q.z), bflo(q.w), bfhi(q.w)};
;                         const f32x4 v0 = x0 + g0[bj] * acc[ai][bj][m][0], v1 = x1 + g1[bj] * acc[ai][bj][m][1];
;                         u32x4 w; w.x = cvt_pk_bf16(v0[0], v0[1]); w.y = cvt_pk_bf16(v0[2], v0[3]); w.z = cvt_pk_bf16(v1[0], v1[1]); w.w = cvt_pk_bf16(v1[2], v1[3]);
;                         *(u32x4*)(out + off + bj * HALF) = w; } } }
	v_and_b32_e32 v131, 0xffff0000, v166
	v_lshlrev_b32_e32 v126, 16, v164
	v_and_b32_e32 v127, 0xffff0000, v164
	v_lshlrev_b32_e32 v128, 16, v165
	v_and_b32_e32 v129, 0xffff0000, v165
	v_lshlrev_b32_e32 v132, 16, v167
	v_and_b32_e32 v133, 0xffff0000, v167
	v_pk_fma_f32 v[106:107], v[106:107], v[114:115], v[128:129]
	v_pk_fma_f32 v[104:105], v[104:105], v[112:113], v[126:127]
	v_pk_fma_f32 v[126:127], v[102:103], v[110:111], v[132:133]
	v_pk_fma_f32 v[102:103], v[100:101], v[108:109], v[130:131]
	v_cvt_pk_bf16_f32 v100, v104, v105
	v_cvt_pk_bf16_f32 v101, v106, v107
	v_lshlrev_b32_e32 v104, 16, v162
	v_cvt_pk_bf16_f32 v102, v102, v103
	v_cvt_pk_bf16_f32 v103, v126, v127
	global_store_dwordx4 v[124:125], v[100:103], off offset:256
	v_and_b32_e32 v105, 0xffff0000, v162
	v_lshlrev_b32_e32 v106, 16, v163
	v_lshlrev_b32_e32 v100, 16, v160
	v_and_b32_e32 v101, 0xffff0000, v160
	v_and_b32_e32 v107, 0xffff0000, v163
	v_pk_fma_f32 v[96:97], v[96:97], v[120:121], v[100:101]
	v_lshlrev_b32_e32 v102, 16, v161
	v_and_b32_e32 v103, 0xffff0000, v161
	v_pk_fma_f32 v[100:101], v[94:95], v[118:119], v[106:107]
	v_pk_fma_f32 v[94:95], v[92:93], v[116:117], v[104:105]
	v_cvt_pk_bf16_f32 v92, v96, v97
	v_lshl_add_u64 v[96:97], s[20:21], 0, v[198:199]
	v_pk_fma_f32 v[98:99], v[98:99], v[122:123], v[102:103]
	v_lshl_add_u64 v[96:97], v[96:97], 0, v[190:191]
	v_cvt_pk_bf16_f32 v93, v98, v99
	v_cvt_pk_bf16_f32 v94, v94, v95
	v_cvt_pk_bf16_f32 v95, v100, v101
	global_store_dwordx4 v[96:97], v[92:95], off
	v_lshlrev_b32_e32 v98, 16, v158
	v_and_b32_e32 v99, 0xffff0000, v158
	v_lshlrev_b32_e32 v92, 16, v156
	v_and_b32_e32 v93, 0xffff0000, v156
	v_lshlrev_b32_e32 v94, 16, v157
	v_and_b32_e32 v95, 0xffff0000, v157
	v_lshlrev_b32_e32 v100, 16, v159
	v_and_b32_e32 v101, 0xffff0000, v159
	v_pk_fma_f32 v[90:91], v[90:91], v[114:115], v[94:95]
	v_pk_fma_f32 v[88:89], v[88:89], v[112:113], v[92:93]
	v_pk_fma_f32 v[92:93], v[86:87], v[110:111], v[100:101]
	v_pk_fma_f32 v[86:87], v[84:85], v[108:109], v[98:99]
	v_cvt_pk_bf16_f32 v84, v88, v89
	v_cvt_pk_bf16_f32 v85, v90, v91
	v_lshlrev_b32_e32 v88, 16, v154
	v_cvt_pk_bf16_f32 v86, v86, v87
	v_cvt_pk_bf16_f32 v87, v92, v93
	global_store_dwordx4 v[96:97], v[84:87], off offset:256
	v_and_b32_e32 v89, 0xffff0000, v154
	v_lshlrev_b32_e32 v90, 16, v155
	v_lshlrev_b32_e32 v84, 16, v152
	v_and_b32_e32 v85, 0xffff0000, v152
	v_and_b32_e32 v91, 0xffff0000, v155
	v_pk_fma_f32 v[80:81], v[80:81], v[120:121], v[84:85]
	v_lshlrev_b32_e32 v86, 16, v153
	v_and_b32_e32 v87, 0xffff0000, v153
	v_pk_fma_f32 v[84:85], v[78:79], v[118:119], v[90:91]
	v_pk_fma_f32 v[78:79], v[76:77], v[116:117], v[88:89]
	v_cvt_pk_bf16_f32 v76, v80, v81
	v_lshl_add_u64 v[80:81], s[20:21], 0, v[196:197]
	v_pk_fma_f32 v[82:83], v[82:83], v[122:123], v[86:87]
	v_lshl_add_u64 v[80:81], v[80:81], 0, v[190:191]
	v_cvt_pk_bf16_f32 v77, v82, v83
	v_cvt_pk_bf16_f32 v78, v78, v79
	v_cvt_pk_bf16_f32 v79, v84, v85
	global_store_dwordx4 v[80:81], v[76:79], off
	v_lshlrev_b32_e32 v82, 16, v150
	v_and_b32_e32 v83, 0xffff0000, v150
	v_lshlrev_b32_e32 v76, 16, v148
	v_and_b32_e32 v77, 0xffff0000, v148
	v_lshlrev_b32_e32 v78, 16, v149
	v_and_b32_e32 v79, 0xffff0000, v149
	v_lshlrev_b32_e32 v84, 16, v151
	v_and_b32_e32 v85, 0xffff0000, v151
	v_pk_fma_f32 v[74:75], v[74:75], v[114:115], v[78:79]
	v_pk_fma_f32 v[72:73], v[72:73], v[112:113], v[76:77]
	v_pk_fma_f32 v[76:77], v[70:71], v[110:111], v[84:85]
	v_pk_fma_f32 v[70:71], v[68:69], v[108:109], v[82:83]
	v_cvt_pk_bf16_f32 v68, v72, v73
	v_cvt_pk_bf16_f32 v69, v74, v75
	v_lshl_add_u64 v[102:103], v[194:195], 0, s[18:19]
	v_cvt_pk_bf16_f32 v70, v70, v71
	v_cvt_pk_bf16_f32 v71, v76, v77
	global_store_dwordx4 v[80:81], v[68:71], off offset:256
	s_mov_b64 s[18:19], 0x90000
	v_lshl_add_u64 v[104:105], v[194:195], 0, s[18:19]
	v_lshl_add_u64 v[68:69], v[192:193], 0, v[102:103]
	global_load_dwordx4 v[78:81], v[68:69], off
	global_load_dwordx4 v[82:85], v[68:69], off offset:256
	v_lshl_add_u64 v[68:69], v[192:193], 0, v[104:105]
	global_load_dwordx4 v[86:89], v[68:69], off
	global_load_dwordx4 v[90:93], v[68:69], off offset:256
	s_mov_b64 s[18:19], 0xa0000
	v_lshl_add_u64 v[106:107], v[194:195], 0, s[18:19]
	v_lshl_add_u64 v[68:69], v[192:193], 0, v[106:107]
	global_load_dwordx4 v[94:97], v[68:69], off
	global_load_dwordx4 v[98:101], v[68:69], off offset:256
	s_mov_b64 s[18:19], 0xb0000
	v_lshl_add_u64 v[76:77], v[194:195], 0, s[18:19]
	v_lshl_add_u64 v[68:69], v[192:193], 0, v[76:77]
	global_load_dwordx4 v[72:75], v[68:69], off
	s_nop 0
	global_load_dwordx4 v[68:71], v[68:69], off offset:256
	s_waitcnt vmcnt(0) lgkmcnt(0)
; __device__ __forceinline__ unsigned cvt_pk_bf16(float lo, float hi) { unsigned r; asm volatile("v_cvt_pk_bf16_f32 %0, %1, %2" : "=v"(r) : "v"(lo), "v"(hi)); return r; }
; __device__ __forceinline__ float bflo(unsigned u) { return __uint_as_float(u << 16); }
; __device__ __forceinline__ float bfhi(unsigned u) { return __uint_as_float(u & 0xffff0000u); }
; #define PG8_BAR __builtin_amdgcn_s_barrier()
;     __device__ __forceinline__ void operator()(const f32x4 (&acc)[2][2][4][2], const Unit& u, int wr, int wc, int fr, int fq) const {
;     ...
;                 for (int m = 0; m < 4; ++m) { const size_t off = (size_t)(row0 + ai * HALF + m * 16) * 2048 + col0;
; #pragma unroll
;                     for (int bj = 0; bj < 2; ++bj) { const u32x4 q = xv[m][bj];
;                         const f32x4 x0 = {bflo(q.x), bfhi(q.x), bflo(q.y), bfhi(q.y)}, x1 = {bflo(q.z), bfhi(q.z), bflo(q.w), bfhi(q.w)};
;                         const f32x4 v0 = x0 + g0[bj] * acc[ai][bj][m][0], v1 = x1 + g1[bj] * acc[ai][bj][m][1];
;                         u32x4 w; w.x = cvt_pk_bf16(v0[0], v0[1]); w.y = cvt_pk_bf16(v0[2], v0[3]); w.z = cvt_pk_bf16(v1[0], v1[1]); w.w = cvt_pk_bf16(v1[2], v1[3]);
;                         *(u32x4*)(out + off + bj * HALF) = w; } } }
; template <class Epi, class Sched, bool ALIGN_EPI = false, bool SP2 = false>
; __device__ __forceinline__ void gemm_phase(PG8_LAS unsigned char* lds, const Gemm g, const Sched& S, const Epi& E, int wave_s) {
;     ...
;         if (!has_next) break;
; #pragma unroll
;         for (int a = 0; a < 2; ++a)
; #pragma unroll
;             for (int b = 0; b < 2; ++b)
; #pragma unroll
;                 for (int m = 0; m < 4; ++m)
; #pragma unroll
;                     for (int n = 0; n < 2; ++n) acc[a][b][m][n] = (f32x4){0.f, 0.f, 0.f, 0.f};
;         cur = nxt; cA = nA; cB = nB; ++ui;
;         if constexpr (ALIGN_EPI) { if (wr == 1) PG8_BAR; }
	v_lshlrev_b32_e32 v124, 16, v78
	v_and_b32_e32 v125, 0xffff0000, v78
	v_lshlrev_b32_e32 v78, 16, v79
	v_and_b32_e32 v79, 0xffff0000, v79
	v_lshlrev_b32_e32 v126, 16, v80
	v_and_b32_e32 v127, 0xffff0000, v80
	v_lshlrev_b32_e32 v80, 16, v81
	v_and_b32_e32 v81, 0xffff0000, v81
	v_pk_fma_f32 v[64:65], v[64:65], v[120:121], v[124:125]
	v_pk_fma_f32 v[66:67], v[66:67], v[122:123], v[78:79]
	v_pk_fma_f32 v[78:79], v[62:63], v[118:119], v[80:81]
	v_pk_fma_f32 v[62:63], v[60:61], v[116:117], v[126:127]
	v_cvt_pk_bf16_f32 v60, v64, v65
	v_lshl_add_u64 v[64:65], s[20:21], 0, v[102:103]
	v_cvt_pk_bf16_f32 v61, v66, v67
	v_cvt_pk_bf16_f32 v62, v62, v63
	v_cvt_pk_bf16_f32 v63, v78, v79
	v_lshl_add_u64 v[64:65], v[64:65], 0, v[190:191]
	global_store_dwordx4 v[64:65], v[60:63], off
	v_lshlrev_b32_e32 v66, 16, v84
	v_and_b32_e32 v67, 0xffff0000, v84
	v_lshlrev_b32_e32 v60, 16, v82
	v_and_b32_e32 v61, 0xffff0000, v82
	v_lshlrev_b32_e32 v62, 16, v83
	v_and_b32_e32 v63, 0xffff0000, v83
	v_lshlrev_b32_e32 v78, 16, v85
	v_and_b32_e32 v79, 0xffff0000, v85
	v_pk_fma_f32 v[58:59], v[58:59], v[114:115], v[62:63]
	v_pk_fma_f32 v[56:57], v[56:57], v[112:113], v[60:61]
	v_pk_fma_f32 v[60:61], v[54:55], v[110:111], v[78:79]
	v_pk_fma_f32 v[54:55], v[52:53], v[108:109], v[66:67]
	v_cvt_pk_bf16_f32 v52, v56, v57
	v_cvt_pk_bf16_f32 v53, v58, v59
	v_lshlrev_b32_e32 v56, 16, v88
	v_cvt_pk_bf16_f32 v54, v54, v55
	v_cvt_pk_bf16_f32 v55, v60, v61
	global_store_dwordx4 v[64:65], v[52:55], off offset:256
	v_and_b32_e32 v57, 0xffff0000, v88
	v_lshlrev_b32_e32 v58, 16, v89
	v_lshlrev_b32_e32 v52, 16, v86
	v_and_b32_e32 v53, 0xffff0000, v86
	v_and_b32_e32 v59, 0xffff0000, v89
	v_pk_fma_f32 v[48:49], v[48:49], v[120:121], v[52:53]
	v_lshlrev_b32_e32 v54, 16, v87
	v_and_b32_e32 v55, 0xffff0000, v87
	v_pk_fma_f32 v[52:53], v[46:47], v[118:119], v[58:59]
	v_pk_fma_f32 v[46:47], v[44:45], v[116:117], v[56:57]
	v_cvt_pk_bf16_f32 v44, v48, v49
	v_lshl_add_u64 v[48:49], s[20:21], 0, v[104:105]
	v_pk_fma_f32 v[50:51], v[50:51], v[122:123], v[54:55]
	v_lshl_add_u64 v[48:49], v[48:49], 0, v[190:191]
	v_cvt_pk_bf16_f32 v45, v50, v51
	v_cvt_pk_bf16_f32 v46, v46, v47
	v_cvt_pk_bf16_f32 v47, v52, v53
	global_store_dwordx4 v[48:49], v[44:47], off
	v_lshlrev_b32_e32 v50, 16, v92
	v_and_b32_e32 v51, 0xffff0000, v92
	v_lshlrev_b32_e32 v44, 16, v90
	v_and_b32_e32 v45, 0xffff0000, v90
	v_lshlrev_b32_e32 v46, 16, v91
	v_and_b32_e32 v47, 0xffff0000, v91
	v_lshlrev_b32_e32 v52, 16, v93
	v_and_b32_e32 v53, 0xffff0000, v93
	v_pk_fma_f32 v[42:43], v[42:43], v[114:115], v[46:47]
	v_pk_fma_f32 v[40:41], v[40:41], v[112:113], v[44:45]
	v_pk_fma_f32 v[44:45], v[38:39], v[110:111], v[52:53]
	v_pk_fma_f32 v[38:39], v[36:37], v[108:109], v[50:51]
	v_cvt_pk_bf16_f32 v36, v40, v41
	v_cvt_pk_bf16_f32 v37, v42, v43
	v_lshlrev_b32_e32 v40, 16, v96
	v_cvt_pk_bf16_f32 v38, v38, v39
	v_cvt_pk_bf16_f32 v39, v44, v45
	global_store_dwordx4 v[48:49], v[36:39], off offset:256
	v_and_b32_e32 v41, 0xffff0000, v96
	v_lshlrev_b32_e32 v42, 16, v97
	v_lshlrev_b32_e32 v36, 16, v94
	v_and_b32_e32 v37, 0xffff0000, v94
	v_and_b32_e32 v43, 0xffff0000, v97
	v_pk_fma_f32 v[32:33], v[32:33], v[120:121], v[36:37]
	v_lshlrev_b32_e32 v38, 16, v95
	v_and_b32_e32 v39, 0xffff0000, v95
	v_pk_fma_f32 v[36:37], v[30:31], v[118:119], v[42:43]
	v_pk_fma_f32 v[30:31], v[28:29], v[116:117], v[40:41]
	v_cvt_pk_bf16_f32 v28, v32, v33
	v_lshl_add_u64 v[32:33], s[20:21], 0, v[106:107]
	v_pk_fma_f32 v[34:35], v[34:35], v[122:123], v[38:39]
	v_lshl_add_u64 v[32:33], v[32:33], 0, v[190:191]
	v_cvt_pk_bf16_f32 v29, v34, v35
	v_cvt_pk_bf16_f32 v30, v30, v31
	v_cvt_pk_bf16_f32 v31, v36, v37
	global_store_dwordx4 v[32:33], v[28:31], off
	v_lshlrev_b32_e32 v34, 16, v100
	v_and_b32_e32 v35, 0xffff0000, v100
	v_lshlrev_b32_e32 v28, 16, v98
	v_and_b32_e32 v29, 0xffff0000, v98
	v_lshlrev_b32_e32 v30, 16, v99
	v_and_b32_e32 v31, 0xffff0000, v99
	v_lshlrev_b32_e32 v36, 16, v101
	v_and_b32_e32 v37, 0xffff0000, v101
	v_pk_fma_f32 v[26:27], v[26:27], v[114:115], v[30:31]
	v_pk_fma_f32 v[24:25], v[24:25], v[112:113], v[28:29]
	v_pk_fma_f32 v[28:29], v[22:23], v[110:111], v[36:37]
	v_pk_fma_f32 v[22:23], v[20:21], v[108:109], v[34:35]
	v_cvt_pk_bf16_f32 v20, v24, v25
	v_cvt_pk_bf16_f32 v21, v26, v27
	v_lshlrev_b32_e32 v24, 16, v74
	v_cvt_pk_bf16_f32 v22, v22, v23
	v_cvt_pk_bf16_f32 v23, v28, v29
	global_store_dwordx4 v[32:33], v[20:23], off offset:256
	v_and_b32_e32 v25, 0xffff0000, v74
	v_lshlrev_b32_e32 v26, 16, v75
	v_lshlrev_b32_e32 v20, 16, v72
	v_and_b32_e32 v21, 0xffff0000, v72
	v_and_b32_e32 v27, 0xffff0000, v75
	v_pk_fma_f32 v[16:17], v[16:17], v[120:121], v[20:21]
	v_lshlrev_b32_e32 v22, 16, v73
	v_and_b32_e32 v23, 0xffff0000, v73
	v_pk_fma_f32 v[20:21], v[14:15], v[118:119], v[26:27]
	v_pk_fma_f32 v[14:15], v[12:13], v[116:117], v[24:25]
	v_cvt_pk_bf16_f32 v12, v16, v17
	v_lshl_add_u64 v[16:17], s[20:21], 0, v[76:77]
	v_pk_fma_f32 v[18:19], v[18:19], v[122:123], v[22:23]
	v_lshl_add_u64 v[162:163], v[16:17], 0, v[190:191]
	v_cvt_pk_bf16_f32 v13, v18, v19
	v_cvt_pk_bf16_f32 v14, v14, v15
	v_cvt_pk_bf16_f32 v15, v20, v21
	global_store_dwordx4 v[162:163], v[12:15], off
	v_lshlrev_b32_e32 v16, 16, v70
	v_and_b32_e32 v17, 0xffff0000, v70
	v_lshlrev_b32_e32 v12, 16, v68
	v_and_b32_e32 v13, 0xffff0000, v68
	v_lshlrev_b32_e32 v14, 16, v69
	v_and_b32_e32 v15, 0xffff0000, v69
	v_lshlrev_b32_e32 v18, 16, v71
	v_and_b32_e32 v19, 0xffff0000, v71
	v_pk_fma_f32 v[10:11], v[10:11], v[114:115], v[14:15]
	v_pk_fma_f32 v[8:9], v[8:9], v[112:113], v[12:13]
	v_pk_fma_f32 v[6:7], v[6:7], v[110:111], v[18:19]
	v_pk_fma_f32 v[4:5], v[4:5], v[108:109], v[16:17]
	v_cvt_pk_bf16_f32 v148, v8, v9
	v_cvt_pk_bf16_f32 v149, v10, v11
	s_nop 0
	v_cvt_pk_bf16_f32 v150, v4, v5
	v_cvt_pk_bf16_f32 v151, v6, v7
.LBB0_667:
	s_andn2_b64 vcc, exec, s[36:37]
	s_mov_b64 s[18:19], -1
	global_store_dwordx4 v[162:163], v[148:151], off offset:256
	s_cbranch_vccnz .LBB0_653
	s_andn2_b64 vcc, exec, s[0:1]
	s_cbranch_vccnz .LBB0_652
	s_barrier
	s_branch .LBB0_652

; __device__ __forceinline__ unsigned cvt_pk_bf16(float lo, float hi) { unsigned r; asm volatile("v_cvt_pk_bf16_f32 %0, %1, %2" : "=v"(r) : "v"(lo), "v"(hi)); return r; }
; __device__ __forceinline__ float siluf_(float x) { return x * __builtin_amdgcn_rcpf(1.f + __expf(-x)); }
;     __device__ __forceinline__ void operator()(const f32x4 (&acc)[2][2][4][2], const Unit& u, int wr, int wc, int fr, int fq) const {
;         const int row0 = u.pm * BM + wr * 64 + fr; const int col0 = u.pn * HALF + wc * 32 + 8 * fq;
; #pragma unroll
;         for (int ai = 0; ai < 2; ++ai)
; #pragma unroll
;             for (int m = 0; m < 4; ++m) { bf16_t* op = O + (size_t)(row0 + ai * HALF + m * 16) * ldc + col0;
;                 f32x4 v0, v1;
; #pragma unroll
;                 for (int j = 0; j < 4; ++j) { v0[j] = siluf_(acc[ai][0][m][0][j]) * acc[ai][1][m][0][j]; v1[j] = siluf_(acc[ai][0][m][1][j]) * acc[ai][1][m][1][j]; }
;                 u32x4 w; w.x = cvt_pk_bf16(v0[0], v0[1]); w.y = cvt_pk_bf16(v0[2], v0[3]); w.z = cvt_pk_bf16(v1[0], v1[1]); w.w = cvt_pk_bf16(v1[2], v1[3]);
;                 *(u32x4*)op = w; }
.LBB0_793:
	v_mul_f32_e32 v147, 0xbfb8aa3b, v128
	v_exp_f32_e32 v147, v147
	v_lshl_or_b32 v148, s33, 7, v144
	v_lshl_add_u32 v146, s50, 8, v142
	v_ashrrev_i32_e32 v149, 31, v148
	v_add_f32_e32 v147, 1.0, v147
	v_rcp_f32_e32 v147, v147
	v_mov_b64_e32 v[140:141], s[4:5]
	s_movk_i32 s17, 0x2c00
	v_mad_i64_i32 v[150:151], s[18:19], v146, s17, v[140:141]
	v_mul_f32_e32 v128, v128, v147
	v_mul_f32_e32 v124, v128, v124
	v_mul_f32_e32 v128, 0xbfb8aa3b, v120
	v_exp_f32_e32 v128, v128
	s_andn2_b64 vcc, exec, s[36:37]
	v_add_f32_e32 v128, 1.0, v128
	v_rcp_f32_e32 v128, v128
	s_nop 0
	v_mul_f32_e32 v120, v120, v128
	v_mul_f32_e32 v120, v120, v116
	v_mul_f32_e32 v116, 0xbfb8aa3b, v129
	v_exp_f32_e32 v116, v116
	s_nop 0
	v_add_f32_e32 v116, 1.0, v116
	v_rcp_f32_e32 v116, v116
	s_nop 0
	v_mul_f32_e32 v116, v129, v116
	v_mul_f32_e32 v125, v116, v125
	v_mul_f32_e32 v116, 0xbfb8aa3b, v121
	v_exp_f32_e32 v116, v116
	s_nop 0
	v_add_f32_e32 v116, 1.0, v116
	v_rcp_f32_e32 v116, v116
	s_nop 0
	v_mul_f32_e32 v116, v121, v116
	v_mul_f32_e32 v121, v116, v117
	v_mul_f32_e32 v116, 0xbfb8aa3b, v130
	v_exp_f32_e32 v116, v116
	s_nop 0
	v_add_f32_e32 v116, 1.0, v116
	v_rcp_f32_e32 v116, v116
	s_nop 0
	v_mul_f32_e32 v116, v130, v116
	v_mul_f32_e32 v126, v116, v126
	v_mul_f32_e32 v116, 0xbfb8aa3b, v122
	v_exp_f32_e32 v116, v116
	s_nop 0
	v_add_f32_e32 v116, 1.0, v116
	v_rcp_f32_e32 v116, v116
	s_nop 0
	v_mul_f32_e32 v116, v122, v116
	v_mul_f32_e32 v128, v116, v118
	v_mul_f32_e32 v116, 0xbfb8aa3b, v131
	v_exp_f32_e32 v116, v116
	v_cvt_pk_bf16_f32 v118, v124, v125
	s_nop 0
	v_add_f32_e32 v116, 1.0, v116
	v_rcp_f32_e32 v116, v116
	s_nop 0
	v_mul_f32_e32 v116, v131, v116
	v_mul_f32_e32 v127, v116, v127
	v_mul_f32_e32 v116, 0xbfb8aa3b, v123
	v_exp_f32_e32 v116, v116
	s_nop 0
	v_add_f32_e32 v116, 1.0, v116
	v_rcp_f32_e32 v116, v116
	s_nop 0
	v_mul_f32_e32 v116, v123, v116
	v_mul_f32_e32 v129, v116, v119
	v_lshlrev_b64 v[116:117], 1, v[148:149]
	v_lshl_add_u64 v[122:123], v[150:151], 0, v[116:117]
	v_cvt_pk_bf16_f32 v119, v126, v127
	v_cvt_pk_bf16_f32 v120, v120, v121
	v_cvt_pk_bf16_f32 v121, v128, v129
	global_store_dwordx4 v[122:123], v[118:121], off
	s_nop 1
	v_mul_f32_e32 v120, 0xbfb8aa3b, v112
	v_exp_f32_e32 v120, v120
	v_or_b32_e32 v118, 16, v146
	v_mad_i64_i32 v[118:119], s[18:19], v118, s17, v[140:141]
	v_add_f32_e32 v120, 1.0, v120
	v_rcp_f32_e32 v120, v120
	s_nop 0
	v_mul_f32_e32 v112, v112, v120
	v_mul_f32_e32 v108, v112, v108
	v_mul_f32_e32 v112, 0xbfb8aa3b, v104
	v_exp_f32_e32 v112, v112
	s_nop 0
	v_add_f32_e32 v112, 1.0, v112
	v_rcp_f32_e32 v112, v112
	s_nop 0
	v_mul_f32_e32 v104, v104, v112
	v_mul_f32_e32 v112, v104, v100
	v_mul_f32_e32 v100, 0xbfb8aa3b, v113
	v_mul_f32_e32 v104, 0xbfb8aa3b, v105
	v_exp_f32_e32 v100, v100
	v_exp_f32_e32 v104, v104
	v_add_f32_e32 v100, 1.0, v100
	v_add_f32_e32 v104, 1.0, v104
	v_rcp_f32_e32 v100, v100
	v_rcp_f32_e32 v104, v104
	v_mul_f32_e32 v100, v113, v100
	v_mul_f32_e32 v104, v105, v104
	v_mul_f32_e32 v100, v100, v109
	v_mul_f32_e32 v109, v104, v101
	v_mul_f32_e32 v104, 0xbfb8aa3b, v106
	v_exp_f32_e32 v104, v104
	v_mul_f32_e32 v101, 0xbfb8aa3b, v114
	v_exp_f32_e32 v101, v101
	v_cvt_pk_bf16_f32 v100, v108, v100
	v_add_f32_e32 v104, 1.0, v104
	v_rcp_f32_e32 v104, v104
	v_add_f32_e32 v101, 1.0, v101
	v_rcp_f32_e32 v101, v101
	v_mul_f32_e32 v104, v106, v104
	v_mul_f32_e32 v106, v104, v102
	v_mul_f32_e32 v102, 0xbfb8aa3b, v115
	v_exp_f32_e32 v102, v102
	v_mul_f32_e32 v104, 0xbfb8aa3b, v107
	v_exp_f32_e32 v104, v104
	v_mul_f32_e32 v101, v114, v101
	v_add_f32_e32 v102, 1.0, v102
	v_rcp_f32_e32 v102, v102
	v_add_f32_e32 v104, 1.0, v104
	v_rcp_f32_e32 v104, v104
	v_mul_f32_e32 v101, v101, v110
	v_mul_f32_e32 v102, v115, v102
	v_mul_f32_e32 v102, v102, v111
	v_mul_f32_e32 v104, v107, v104
	v_mul_f32_e32 v103, v104, v103
	v_lshl_add_u64 v[104:105], v[118:119], 0, v[116:117]
	v_cvt_pk_bf16_f32 v101, v101, v102
	v_cvt_pk_bf16_f32 v102, v112, v109
	v_cvt_pk_bf16_f32 v103, v106, v103
	global_store_dwordx4 v[104:105], v[100:103], off
	s_nop 1
	v_mul_f32_e32 v102, 0xbfb8aa3b, v96
	v_exp_f32_e32 v102, v102
	v_or_b32_e32 v100, 32, v146
	v_mad_i64_i32 v[100:101], s[18:19], v100, s17, v[140:141]
	v_add_f32_e32 v102, 1.0, v102
	v_rcp_f32_e32 v102, v102
	s_nop 0
	v_mul_f32_e32 v96, v96, v102
	v_mul_f32_e32 v92, v96, v92
	v_mul_f32_e32 v96, 0xbfb8aa3b, v88
	v_exp_f32_e32 v96, v96
	s_nop 0
	v_add_f32_e32 v96, 1.0, v96
	v_rcp_f32_e32 v96, v96
	s_nop 0
	v_mul_f32_e32 v88, v88, v96
	v_mul_f32_e32 v96, v88, v84
	v_mul_f32_e32 v84, 0xbfb8aa3b, v97
	v_mul_f32_e32 v88, 0xbfb8aa3b, v89
	v_exp_f32_e32 v84, v84
	v_exp_f32_e32 v88, v88
	v_add_f32_e32 v84, 1.0, v84
	v_add_f32_e32 v88, 1.0, v88
	v_rcp_f32_e32 v84, v84
	v_rcp_f32_e32 v88, v88
	v_mul_f32_e32 v84, v97, v84
	v_mul_f32_e32 v88, v89, v88
	v_mul_f32_e32 v84, v84, v93
	v_mul_f32_e32 v93, v88, v85
	v_mul_f32_e32 v88, 0xbfb8aa3b, v90
	v_exp_f32_e32 v88, v88
	v_mul_f32_e32 v85, 0xbfb8aa3b, v98
	v_exp_f32_e32 v85, v85
	v_cvt_pk_bf16_f32 v84, v92, v84
	v_add_f32_e32 v88, 1.0, v88
	v_rcp_f32_e32 v88, v88
	v_add_f32_e32 v85, 1.0, v85
	v_rcp_f32_e32 v85, v85
	v_mul_f32_e32 v88, v90, v88
	v_mul_f32_e32 v90, v88, v86
	v_mul_f32_e32 v86, 0xbfb8aa3b, v99
	v_exp_f32_e32 v86, v86
	v_mul_f32_e32 v88, 0xbfb8aa3b, v91
	v_exp_f32_e32 v88, v88
	v_mul_f32_e32 v85, v98, v85
	v_add_f32_e32 v86, 1.0, v86
	v_rcp_f32_e32 v86, v86
	v_add_f32_e32 v88, 1.0, v88
	v_rcp_f32_e32 v88, v88
	v_mul_f32_e32 v85, v85, v94
	v_mul_f32_e32 v86, v99, v86
	v_mul_f32_e32 v86, v86, v95
	v_mul_f32_e32 v88, v91, v88
	v_mul_f32_e32 v87, v88, v87
	v_lshl_add_u64 v[88:89], v[100:101], 0, v[116:117]
	v_cvt_pk_bf16_f32 v85, v85, v86
	v_cvt_pk_bf16_f32 v86, v96, v93
; __device__ __forceinline__ unsigned cvt_pk_bf16(float lo, float hi) { unsigned r; asm volatile("v_cvt_pk_bf16_f32 %0, %1, %2" : "=v"(r) : "v"(lo), "v"(hi)); return r; }
; __device__ __forceinline__ float siluf_(float x) { return x * __builtin_amdgcn_rcpf(1.f + __expf(-x)); }
;     __device__ __forceinline__ void operator()(const f32x4 (&acc)[2][2][4][2], const Unit& u, int wr, int wc, int fr, int fq) const {
;     ...
;         for (int ai = 0; ai < 2; ++ai)
; #pragma unroll
;             for (int m = 0; m < 4; ++m) { bf16_t* op = O + (size_t)(row0 + ai * HALF + m * 16) * ldc + col0;
;                 f32x4 v0, v1;
; #pragma unroll
;                 for (int j = 0; j < 4; ++j) { v0[j] = siluf_(acc[ai][0][m][0][j]) * acc[ai][1][m][0][j]; v1[j] = siluf_(acc[ai][0][m][1][j]) * acc[ai][1][m][1][j]; }
;                 u32x4 w; w.x = cvt_pk_bf16(v0[0], v0[1]); w.y = cvt_pk_bf16(v0[2], v0[3]); w.z = cvt_pk_bf16(v1[0], v1[1]); w.w = cvt_pk_bf16(v1[2], v1[3]);
;                 *(u32x4*)op = w; }
	v_cvt_pk_bf16_f32 v87, v90, v87
	global_store_dwordx4 v[88:89], v[84:87], off
	s_nop 1
	v_mul_f32_e32 v86, 0xbfb8aa3b, v80
	v_exp_f32_e32 v86, v86
	v_or_b32_e32 v84, 48, v146
	v_mad_i64_i32 v[84:85], s[18:19], v84, s17, v[140:141]
	v_add_f32_e32 v86, 1.0, v86
	v_rcp_f32_e32 v86, v86
	s_nop 0
	v_mul_f32_e32 v80, v80, v86
	v_mul_f32_e32 v76, v80, v76
	v_mul_f32_e32 v80, 0xbfb8aa3b, v72
	v_exp_f32_e32 v80, v80
	s_nop 0
	v_add_f32_e32 v80, 1.0, v80
	v_rcp_f32_e32 v80, v80
	s_nop 0
	v_mul_f32_e32 v72, v72, v80
	v_mul_f32_e32 v80, v72, v68
	v_mul_f32_e32 v68, 0xbfb8aa3b, v81
	v_mul_f32_e32 v72, 0xbfb8aa3b, v73
	v_exp_f32_e32 v68, v68
	v_exp_f32_e32 v72, v72
	v_add_f32_e32 v68, 1.0, v68
	v_add_f32_e32 v72, 1.0, v72
	v_rcp_f32_e32 v68, v68
	v_rcp_f32_e32 v72, v72
	v_mul_f32_e32 v68, v81, v68
	v_mul_f32_e32 v72, v73, v72
	v_mul_f32_e32 v68, v68, v77
	v_mul_f32_e32 v77, v72, v69
	v_mul_f32_e32 v72, 0xbfb8aa3b, v74
	v_exp_f32_e32 v72, v72
	v_mul_f32_e32 v69, 0xbfb8aa3b, v82
	v_exp_f32_e32 v69, v69
	v_cvt_pk_bf16_f32 v68, v76, v68
	v_add_f32_e32 v72, 1.0, v72
	v_rcp_f32_e32 v72, v72
	v_add_f32_e32 v69, 1.0, v69
	v_rcp_f32_e32 v69, v69
	v_mul_f32_e32 v72, v74, v72
	v_mul_f32_e32 v74, v72, v70
	v_mul_f32_e32 v70, 0xbfb8aa3b, v83
	v_exp_f32_e32 v70, v70
	v_mul_f32_e32 v72, 0xbfb8aa3b, v75
	v_exp_f32_e32 v72, v72
	v_mul_f32_e32 v69, v82, v69
	v_add_f32_e32 v70, 1.0, v70
	v_rcp_f32_e32 v70, v70
	v_add_f32_e32 v72, 1.0, v72
	v_rcp_f32_e32 v72, v72
	v_mul_f32_e32 v69, v69, v78
	v_mul_f32_e32 v70, v83, v70
	v_mul_f32_e32 v70, v70, v79
	v_mul_f32_e32 v72, v75, v72
	v_mul_f32_e32 v71, v72, v71
	v_lshl_add_u64 v[72:73], v[84:85], 0, v[116:117]
	v_cvt_pk_bf16_f32 v69, v69, v70
	v_cvt_pk_bf16_f32 v70, v80, v77
	v_cvt_pk_bf16_f32 v71, v74, v71
	global_store_dwordx4 v[72:73], v[68:71], off
	s_nop 1
	v_mul_f32_e32 v70, 0xbfb8aa3b, v64
	v_exp_f32_e32 v70, v70
	v_add_u32_e32 v68, 0x80, v146
	v_mad_i64_i32 v[68:69], s[18:19], v68, s17, v[140:141]
	v_add_f32_e32 v70, 1.0, v70
	v_rcp_f32_e32 v70, v70
	s_nop 0
	v_mul_f32_e32 v64, v64, v70
	v_mul_f32_e32 v60, v64, v60
	v_mul_f32_e32 v64, 0xbfb8aa3b, v56
	v_exp_f32_e32 v64, v64
	s_nop 0
	v_add_f32_e32 v64, 1.0, v64
	v_rcp_f32_e32 v64, v64
	s_nop 0
	v_mul_f32_e32 v56, v56, v64
	v_mul_f32_e32 v64, v56, v52
	v_mul_f32_e32 v52, 0xbfb8aa3b, v65
	v_mul_f32_e32 v56, 0xbfb8aa3b, v57
	v_exp_f32_e32 v52, v52
	v_exp_f32_e32 v56, v56
	v_add_f32_e32 v52, 1.0, v52
	v_add_f32_e32 v56, 1.0, v56
	v_rcp_f32_e32 v52, v52
	v_rcp_f32_e32 v56, v56
	v_mul_f32_e32 v52, v65, v52
	v_mul_f32_e32 v56, v57, v56
	v_mul_f32_e32 v52, v52, v61
	v_mul_f32_e32 v61, v56, v53
	v_mul_f32_e32 v56, 0xbfb8aa3b, v58
	v_exp_f32_e32 v56, v56
	v_mul_f32_e32 v53, 0xbfb8aa3b, v66
	v_exp_f32_e32 v53, v53
	v_cvt_pk_bf16_f32 v52, v60, v52
	v_add_f32_e32 v56, 1.0, v56
	v_rcp_f32_e32 v56, v56
	v_add_f32_e32 v53, 1.0, v53
	v_rcp_f32_e32 v53, v53
	v_mul_f32_e32 v56, v58, v56
	v_mul_f32_e32 v58, v56, v54
	v_mul_f32_e32 v54, 0xbfb8aa3b, v67
	v_exp_f32_e32 v54, v54
	v_mul_f32_e32 v56, 0xbfb8aa3b, v59
	v_exp_f32_e32 v56, v56
	v_mul_f32_e32 v53, v66, v53
	v_add_f32_e32 v54, 1.0, v54
	v_rcp_f32_e32 v54, v54
	v_add_f32_e32 v56, 1.0, v56
	v_rcp_f32_e32 v56, v56
	v_mul_f32_e32 v53, v53, v62
	v_mul_f32_e32 v54, v67, v54
	v_mul_f32_e32 v54, v54, v63
	v_mul_f32_e32 v56, v59, v56
	v_mul_f32_e32 v55, v56, v55
	v_lshl_add_u64 v[56:57], v[68:69], 0, v[116:117]
	v_cvt_pk_bf16_f32 v53, v53, v54
	v_cvt_pk_bf16_f32 v54, v64, v61
	v_cvt_pk_bf16_f32 v55, v58, v55
	global_store_dwordx4 v[56:57], v[52:55], off
	s_nop 1
	v_mul_f32_e32 v54, 0xbfb8aa3b, v48
	v_exp_f32_e32 v54, v54
	v_add_u32_e32 v52, 0x90, v146
	v_mad_i64_i32 v[52:53], s[18:19], v52, s17, v[140:141]
	v_add_f32_e32 v54, 1.0, v54
	v_rcp_f32_e32 v54, v54
	s_nop 0
	v_mul_f32_e32 v48, v48, v54
	v_mul_f32_e32 v44, v48, v44
	v_mul_f32_e32 v48, 0xbfb8aa3b, v40
	v_exp_f32_e32 v48, v48
	s_nop 0
	v_add_f32_e32 v48, 1.0, v48
	v_rcp_f32_e32 v48, v48
	s_nop 0
	v_mul_f32_e32 v40, v40, v48
	v_mul_f32_e32 v48, v40, v36
	v_mul_f32_e32 v36, 0xbfb8aa3b, v49
	v_mul_f32_e32 v40, 0xbfb8aa3b, v41
	v_exp_f32_e32 v36, v36
	v_exp_f32_e32 v40, v40
	v_add_f32_e32 v36, 1.0, v36
	v_add_f32_e32 v40, 1.0, v40
	v_rcp_f32_e32 v36, v36
	v_rcp_f32_e32 v40, v40
	v_mul_f32_e32 v36, v49, v36
	v_mul_f32_e32 v40, v41, v40
	v_mul_f32_e32 v36, v36, v45
	v_mul_f32_e32 v45, v40, v37
	v_mul_f32_e32 v40, 0xbfb8aa3b, v42
; __device__ __forceinline__ unsigned cvt_pk_bf16(float lo, float hi) { unsigned r; asm volatile("v_cvt_pk_bf16_f32 %0, %1, %2" : "=v"(r) : "v"(lo), "v"(hi)); return r; }
; __device__ __forceinline__ float siluf_(float x) { return x * __builtin_amdgcn_rcpf(1.f + __expf(-x)); }
; #define PG8_BAR __builtin_amdgcn_s_barrier()
;     __device__ __forceinline__ void operator()(const f32x4 (&acc)[2][2][4][2], const Unit& u, int wr, int wc, int fr, int fq) const {
;     ...
;         for (int ai = 0; ai < 2; ++ai)
; #pragma unroll
;             for (int m = 0; m < 4; ++m) { bf16_t* op = O + (size_t)(row0 + ai * HALF + m * 16) * ldc + col0;
;                 f32x4 v0, v1;
; #pragma unroll
;                 for (int j = 0; j < 4; ++j) { v0[j] = siluf_(acc[ai][0][m][0][j]) * acc[ai][1][m][0][j]; v1[j] = siluf_(acc[ai][0][m][1][j]) * acc[ai][1][m][1][j]; }
;                 u32x4 w; w.x = cvt_pk_bf16(v0[0], v0[1]); w.y = cvt_pk_bf16(v0[2], v0[3]); w.z = cvt_pk_bf16(v1[0], v1[1]); w.w = cvt_pk_bf16(v1[2], v1[3]);
;                 *(u32x4*)op = w; }
; template <class Epi, class Sched, bool ALIGN_EPI = false, bool SP2 = false>
; __device__ __forceinline__ void gemm_phase(PG8_LAS unsigned char* lds, const Gemm g, const Sched& S, const Epi& E, int wave_s) {
;     ...
;         if (!has_next) break;
; #pragma unroll
;         for (int a = 0; a < 2; ++a)
; #pragma unroll
;             for (int b = 0; b < 2; ++b)
; #pragma unroll
;                 for (int m = 0; m < 4; ++m)
; #pragma unroll
;                     for (int n = 0; n < 2; ++n) acc[a][b][m][n] = (f32x4){0.f, 0.f, 0.f, 0.f};
;         cur = nxt; cA = nA; cB = nB; ++ui;
;         if constexpr (ALIGN_EPI) { if (wr == 1) PG8_BAR; }
	v_exp_f32_e32 v40, v40
	v_mul_f32_e32 v37, 0xbfb8aa3b, v50
	v_exp_f32_e32 v37, v37
	v_cvt_pk_bf16_f32 v36, v44, v36
	v_add_f32_e32 v40, 1.0, v40
	v_rcp_f32_e32 v40, v40
	v_add_f32_e32 v37, 1.0, v37
	v_rcp_f32_e32 v37, v37
	v_mul_f32_e32 v40, v42, v40
	v_mul_f32_e32 v42, v40, v38
	v_mul_f32_e32 v38, 0xbfb8aa3b, v51
	v_exp_f32_e32 v38, v38
	v_mul_f32_e32 v40, 0xbfb8aa3b, v43
	v_exp_f32_e32 v40, v40
	v_mul_f32_e32 v37, v50, v37
	v_add_f32_e32 v38, 1.0, v38
	v_rcp_f32_e32 v38, v38
	v_add_f32_e32 v40, 1.0, v40
	v_rcp_f32_e32 v40, v40
	v_mul_f32_e32 v37, v37, v46
	v_mul_f32_e32 v38, v51, v38
	v_mul_f32_e32 v38, v38, v47
	v_mul_f32_e32 v40, v43, v40
	v_mul_f32_e32 v39, v40, v39
	v_lshl_add_u64 v[40:41], v[52:53], 0, v[116:117]
	v_cvt_pk_bf16_f32 v37, v37, v38
	v_cvt_pk_bf16_f32 v38, v48, v45
	v_cvt_pk_bf16_f32 v39, v42, v39
	global_store_dwordx4 v[40:41], v[36:39], off
	s_nop 1
	v_mul_f32_e32 v38, 0xbfb8aa3b, v32
	v_exp_f32_e32 v38, v38
	v_add_u32_e32 v36, 0xa0, v146
	v_mad_i64_i32 v[36:37], s[18:19], v36, s17, v[140:141]
	v_add_f32_e32 v38, 1.0, v38
	v_rcp_f32_e32 v38, v38
	s_nop 0
	v_mul_f32_e32 v32, v32, v38
	v_mul_f32_e32 v28, v32, v28
	v_mul_f32_e32 v32, 0xbfb8aa3b, v24
	v_exp_f32_e32 v32, v32
	s_nop 0
	v_add_f32_e32 v32, 1.0, v32
	v_rcp_f32_e32 v32, v32
	s_nop 0
	v_mul_f32_e32 v24, v24, v32
	v_mul_f32_e32 v32, v24, v20
	v_mul_f32_e32 v20, 0xbfb8aa3b, v33
	v_mul_f32_e32 v24, 0xbfb8aa3b, v25
	v_exp_f32_e32 v20, v20
	v_exp_f32_e32 v24, v24
	v_add_f32_e32 v20, 1.0, v20
	v_add_f32_e32 v24, 1.0, v24
	v_rcp_f32_e32 v20, v20
	v_rcp_f32_e32 v24, v24
	v_mul_f32_e32 v20, v33, v20
	v_mul_f32_e32 v24, v25, v24
	v_mul_f32_e32 v20, v20, v29
	v_mul_f32_e32 v29, v24, v21
	v_mul_f32_e32 v24, 0xbfb8aa3b, v26
	v_exp_f32_e32 v24, v24
	v_mul_f32_e32 v21, 0xbfb8aa3b, v34
	v_exp_f32_e32 v21, v21
	v_cvt_pk_bf16_f32 v20, v28, v20
	v_add_f32_e32 v24, 1.0, v24
	v_rcp_f32_e32 v24, v24
	v_add_f32_e32 v21, 1.0, v21
	v_rcp_f32_e32 v21, v21
	v_mul_f32_e32 v24, v26, v24
	v_mul_f32_e32 v26, v24, v22
	v_mul_f32_e32 v22, 0xbfb8aa3b, v35
	v_exp_f32_e32 v22, v22
	v_mul_f32_e32 v24, 0xbfb8aa3b, v27
	v_exp_f32_e32 v24, v24
	v_mul_f32_e32 v21, v34, v21
	v_add_f32_e32 v22, 1.0, v22
	v_rcp_f32_e32 v22, v22
	v_add_f32_e32 v24, 1.0, v24
	v_rcp_f32_e32 v24, v24
	v_mul_f32_e32 v21, v21, v30
	v_mul_f32_e32 v22, v35, v22
	v_mul_f32_e32 v22, v22, v31
	v_mul_f32_e32 v24, v27, v24
	v_mul_f32_e32 v23, v24, v23
	v_lshl_add_u64 v[24:25], v[36:37], 0, v[116:117]
	v_cvt_pk_bf16_f32 v21, v21, v22
	v_cvt_pk_bf16_f32 v22, v32, v29
	v_cvt_pk_bf16_f32 v23, v26, v23
	global_store_dwordx4 v[24:25], v[20:23], off
	s_nop 1
	v_mul_f32_e32 v22, 0xbfb8aa3b, v16
	v_exp_f32_e32 v22, v22
	v_add_u32_e32 v20, 0xb0, v146
	v_mad_i64_i32 v[20:21], s[18:19], v20, s17, v[140:141]
	v_add_f32_e32 v22, 1.0, v22
	v_rcp_f32_e32 v22, v22
	s_mov_b64 s[18:19], -1
	v_mul_f32_e32 v16, v16, v22
	v_mul_f32_e32 v12, v16, v12
	v_mul_f32_e32 v16, 0xbfb8aa3b, v8
	v_exp_f32_e32 v16, v16
	s_nop 0
	v_add_f32_e32 v16, 1.0, v16
	v_rcp_f32_e32 v16, v16
	s_nop 0
	v_mul_f32_e32 v8, v8, v16
	v_mul_f32_e32 v16, v8, v4
	v_mul_f32_e32 v4, 0xbfb8aa3b, v17
	v_mul_f32_e32 v8, 0xbfb8aa3b, v9
	v_exp_f32_e32 v4, v4
	v_exp_f32_e32 v8, v8
	v_add_f32_e32 v4, 1.0, v4
	v_add_f32_e32 v8, 1.0, v8
	v_rcp_f32_e32 v4, v4
	v_rcp_f32_e32 v8, v8
	v_mul_f32_e32 v4, v17, v4
	v_mul_f32_e32 v8, v9, v8
	v_mul_f32_e32 v4, v4, v13
	v_mul_f32_e32 v13, v8, v5
	v_mul_f32_e32 v8, 0xbfb8aa3b, v10
	v_exp_f32_e32 v8, v8
	v_mul_f32_e32 v5, 0xbfb8aa3b, v18
	v_exp_f32_e32 v5, v5
	v_cvt_pk_bf16_f32 v4, v12, v4
	v_add_f32_e32 v8, 1.0, v8
	v_rcp_f32_e32 v8, v8
	v_add_f32_e32 v5, 1.0, v5
	v_rcp_f32_e32 v5, v5
	v_mul_f32_e32 v8, v10, v8
	v_mul_f32_e32 v10, v8, v6
	v_mul_f32_e32 v6, 0xbfb8aa3b, v19
	v_mul_f32_e32 v8, 0xbfb8aa3b, v11
	v_exp_f32_e32 v6, v6
	v_exp_f32_e32 v8, v8
	v_mul_f32_e32 v5, v18, v5
	v_mul_f32_e32 v5, v5, v14
	v_add_f32_e32 v6, 1.0, v6
	v_add_f32_e32 v8, 1.0, v8
	v_rcp_f32_e32 v6, v6
	v_rcp_f32_e32 v8, v8
	v_mul_f32_e32 v6, v19, v6
	v_mul_f32_e32 v8, v11, v8
	v_mul_f32_e32 v6, v6, v15
	v_mul_f32_e32 v7, v8, v7
	v_lshl_add_u64 v[8:9], v[20:21], 0, v[116:117]
	v_cvt_pk_bf16_f32 v5, v5, v6
	v_cvt_pk_bf16_f32 v6, v16, v13
	v_cvt_pk_bf16_f32 v7, v10, v7
	global_store_dwordx4 v[8:9], v[4:7], off
	s_cbranch_vccnz .LBB0_786
	s_andn2_b64 vcc, exec, s[0:1]
	s_cbranch_vccnz .LBB0_785
	s_barrier
	s_branch .LBB0_785

; __device__ __forceinline__ unsigned cvt_pk_bf16(float lo, float hi) { unsigned r; asm volatile("v_cvt_pk_bf16_f32 %0, %1, %2" : "=v"(r) : "v"(lo), "v"(hi)); return r; }
;     __device__ __forceinline__ void operator()(const f32x4 (&acc)[2][2][4][2], const Unit& u, int wr, int wc, int fr, int fq) const {
;     ...
;         const float* gp = gate + (size_t)(u.pm >> 4) * gstride + col0;
;         f32x4 g0[2], g1[2];
; #pragma unroll
;         for (int bj = 0; bj < 2; ++bj) { g0[bj] = *(const f32x4*)(gp + bj * HALF); g1[bj] = *(const f32x4*)(gp + bj * HALF + 4); }
;         if (xin_f) {
; #pragma unroll
;             for (int ai = 0; ai < 2; ++ai)
; #pragma unroll
;                 for (int m = 0; m < 4; ++m) { const size_t off = (size_t)(row0 + ai * HALF + m * 16) * 2048 + col0;
; #pragma unroll
;                     for (int bj = 0; bj < 2; ++bj) { const f32x4 x0 = *(const f32x4*)(xin_f + off + bj * HALF), x1 = *(const f32x4*)(xin_f + off + bj * HALF + 4);
;                         const f32x4 v0 = x0 + g0[bj] * acc[ai][bj][m][0], v1 = x1 + g1[bj] * acc[ai][bj][m][1];
;                         u32x4 w; w.x = cvt_pk_bf16(v0[0], v0[1]); w.y = cvt_pk_bf16(v0[2], v0[3]); w.z = cvt_pk_bf16(v1[0], v1[1]); w.w = cvt_pk_bf16(v1[2], v1[3]);
;                         *(u32x4*)(out + off + bj * HALF) = w; } }
;         } else {
; #pragma unroll
;             for (int ai = 0; ai < 2; ++ai) { u32x4 xv[4][2];
; #pragma unroll
;                 for (int m = 0; m < 4; ++m)
; #pragma unroll
;                     for (int bj = 0; bj < 2; ++bj) xv[m][bj] = *(const u32x4*)(xin_b + (size_t)(row0 + ai * HALF + m * 16) * 2048 + col0 + bj * HALF);
; #pragma unroll
;                 for (int m = 0; m < 4; ++m) { const size_t off = (size_t)(row0 + ai * HALF + m * 16) * 2048 + col0;
; #pragma unroll
;                     for (int bj = 0; bj < 2; ++bj) { const u32x4 q = xv[m][bj];
;                         const f32x4 x0 = {bflo(q.x), bfhi(q.x), bflo(q.y), bfhi(q.y)}, x1 = {bflo(q.z), bfhi(q.z), bflo(q.w), bfhi(q.w)};
;                         const f32x4 v0 = x0 + g0[bj] * acc[ai][bj][m][0], v1 = x1 + g1[bj] * acc[ai][bj][m][1];
;                         u32x4 w; w.x = cvt_pk_bf16(v0[0], v0[1]); w.y = cvt_pk_bf16(v0[2], v0[3]); w.z = cvt_pk_bf16(v1[0], v1[1]); w.w = cvt_pk_bf16(v1[2], v1[3]);
;                         *(u32x4*)(out + off + bj * HALF) = w; } } }
.LBB0_866:
	v_lshl_or_b32 v132, s52, 8, v185
	v_ashrrev_i32_e32 v133, 31, v132
	v_lshl_add_u32 v148, s51, 8, v173
	v_lshlrev_b64 v[160:161], 1, v[132:133]
	v_ashrrev_i32_e32 v149, 31, v148
	v_lshl_add_u64 v[162:163], s[4:5], 0, v[160:161]
	v_lshlrev_b64 v[164:165], 12, v[148:149]
	v_lshl_add_u64 v[134:135], v[162:163], 0, v[164:165]
	s_ashr_i32 s20, s51, 4
	global_load_dwordx4 v[188:191], v[134:135], off
	global_load_dwordx4 v[192:195], v[134:135], off offset:256
	v_or_b32_e32 v134, 16, v148
	s_mul_hi_i32 s21, s20, 0xc000
	s_mul_i32 s20, s20, 0xc000
	v_ashrrev_i32_e32 v135, 31, v134
	s_add_u32 s20, s45, s20
	v_lshlrev_b64 v[200:201], 12, v[134:135]
	s_addc_u32 s21, s46, s21
	v_lshl_add_u64 v[150:151], v[162:163], 0, v[200:201]
	v_lshl_add_u64 v[132:133], v[132:133], 2, s[20:21]
	global_load_dwordx4 v[196:199], v[150:151], off
	global_load_dwordx4 v[144:147], v[132:133], off
	global_load_dwordx4 v[140:143], v[132:133], off offset:16
	global_load_dwordx4 v[136:139], v[132:133], off offset:512
	s_nop 0
	global_load_dwordx4 v[132:135], v[132:133], off offset:528
	s_nop 0
	global_load_dwordx4 v[212:215], v[150:151], off offset:256
	v_or_b32_e32 v150, 32, v148
	v_ashrrev_i32_e32 v151, 31, v150
	v_lshlrev_b64 v[182:183], 12, v[150:151]
	v_lshl_add_u64 v[150:151], v[162:163], 0, v[182:183]
	global_load_dwordx4 v[216:219], v[150:151], off
	v_or_b32_e32 v148, 48, v148
	v_ashrrev_i32_e32 v149, 31, v148
	v_lshlrev_b64 v[166:167], 12, v[148:149]
	v_lshl_add_u64 v[148:149], s[4:5], 0, v[164:165]
	v_lshl_add_u64 v[228:229], v[162:163], 0, v[166:167]
	v_lshl_add_u64 v[230:231], v[148:149], 0, v[160:161]
	global_load_dwordx4 v[220:223], v[150:151], off offset:256
	global_load_dwordx4 v[224:227], v[228:229], off
	s_nop 0
	global_load_dwordx4 v[148:151], v[228:229], off offset:256
	s_mov_b64 s[20:21], 0x80000
	s_and_b64 vcc, exec, s[34:35]
	s_waitcnt vmcnt(0) lgkmcnt(0)
	v_lshlrev_b32_e32 v228, 16, v188
	v_and_b32_e32 v229, 0xffff0000, v188
	v_lshlrev_b32_e32 v188, 16, v189
	v_and_b32_e32 v189, 0xffff0000, v189
	v_lshlrev_b32_e32 v232, 16, v190
	v_and_b32_e32 v233, 0xffff0000, v190
	v_lshlrev_b32_e32 v190, 16, v191
	v_and_b32_e32 v191, 0xffff0000, v191
	v_lshlrev_b32_e32 v234, 16, v192
	v_and_b32_e32 v235, 0xffff0000, v192
	v_lshlrev_b32_e32 v236, 16, v194
	v_and_b32_e32 v237, 0xffff0000, v194
	v_lshlrev_b32_e32 v194, 16, v195
	v_and_b32_e32 v195, 0xffff0000, v195
	v_lshlrev_b32_e32 v192, 16, v193
	v_and_b32_e32 v193, 0xffff0000, v193
	v_pk_fma_f32 v[130:131], v[130:131], v[146:147], v[188:189]
	v_pk_fma_f32 v[128:129], v[128:129], v[144:145], v[228:229]
	v_pk_fma_f32 v[126:127], v[126:127], v[142:143], v[190:191]
	v_pk_fma_f32 v[124:125], v[124:125], v[140:141], v[232:233]
	v_pk_fma_f32 v[112:113], v[112:113], v[136:137], v[234:235]
	v_pk_fma_f32 v[188:189], v[110:111], v[134:135], v[194:195]
	v_pk_fma_f32 v[190:191], v[108:109], v[132:133], v[236:237]
	v_cvt_pk_bf16_f32 v108, v128, v129
	v_cvt_pk_bf16_f32 v109, v130, v131
	v_cvt_pk_bf16_f32 v110, v124, v125
	v_cvt_pk_bf16_f32 v111, v126, v127
	v_lshlrev_b32_e32 v238, 16, v196
	v_and_b32_e32 v239, 0xffff0000, v196
	v_lshlrev_b32_e32 v196, 16, v197
	v_and_b32_e32 v197, 0xffff0000, v197
	v_lshlrev_b32_e32 v240, 16, v198
	v_and_b32_e32 v241, 0xffff0000, v198
	v_lshlrev_b32_e32 v198, 16, v199
	v_and_b32_e32 v199, 0xffff0000, v199
	v_pk_fma_f32 v[114:115], v[114:115], v[138:139], v[192:193]
	global_store_dwordx4 v[230:231], v[108:111], off
	v_pk_fma_f32 v[122:123], v[122:123], v[146:147], v[196:197]
	v_pk_fma_f32 v[120:121], v[120:121], v[144:145], v[238:239]
	v_cvt_pk_bf16_f32 v108, v112, v113
	v_cvt_pk_bf16_f32 v109, v114, v115
	v_cvt_pk_bf16_f32 v110, v190, v191
	v_cvt_pk_bf16_f32 v111, v188, v189
	v_lshl_add_u64 v[112:113], s[4:5], 0, v[200:201]
	v_pk_fma_f32 v[118:119], v[118:119], v[142:143], v[198:199]
	v_pk_fma_f32 v[116:117], v[116:117], v[140:141], v[240:241]
	global_store_dwordx4 v[230:231], v[108:111], off offset:256
	v_lshl_add_u64 v[112:113], v[112:113], 0, v[160:161]
	v_lshlrev_b32_e32 v114, 16, v214
	v_cvt_pk_bf16_f32 v108, v120, v121
	v_cvt_pk_bf16_f32 v109, v122, v123
	v_cvt_pk_bf16_f32 v110, v116, v117
	v_cvt_pk_bf16_f32 v111, v118, v119
	global_store_dwordx4 v[112:113], v[108:111], off
	v_and_b32_e32 v115, 0xffff0000, v214
	v_lshlrev_b32_e32 v116, 16, v215
	v_lshlrev_b32_e32 v108, 16, v212
	v_and_b32_e32 v109, 0xffff0000, v212
	v_lshlrev_b32_e32 v110, 16, v213
	v_and_b32_e32 v111, 0xffff0000, v213
	v_and_b32_e32 v117, 0xffff0000, v215
	v_pk_fma_f32 v[106:107], v[106:107], v[138:139], v[110:111]
	v_pk_fma_f32 v[104:105], v[104:105], v[136:137], v[108:109]
	v_pk_fma_f32 v[108:109], v[102:103], v[134:135], v[116:117]
	v_pk_fma_f32 v[102:103], v[100:101], v[132:133], v[114:115]
	v_cvt_pk_bf16_f32 v100, v104, v105
	v_cvt_pk_bf16_f32 v101, v106, v107
	v_lshlrev_b32_e32 v104, 16, v218
	v_cvt_pk_bf16_f32 v102, v102, v103
	v_cvt_pk_bf16_f32 v103, v108, v109
	global_store_dwordx4 v[112:113], v[100:103], off offset:256
	v_and_b32_e32 v105, 0xffff0000, v218
	v_lshlrev_b32_e32 v106, 16, v219
	v_lshlrev_b32_e32 v100, 16, v216
	v_and_b32_e32 v101, 0xffff0000, v216
	v_and_b32_e32 v107, 0xffff0000, v219
	v_pk_fma_f32 v[96:97], v[96:97], v[144:145], v[100:101]
	v_lshlrev_b32_e32 v102, 16, v217
	v_and_b32_e32 v103, 0xffff0000, v217
	v_pk_fma_f32 v[100:101], v[94:95], v[142:143], v[106:107]
	v_pk_fma_f32 v[94:95], v[92:93], v[140:141], v[104:105]
	v_cvt_pk_bf16_f32 v92, v96, v97
	v_lshl_add_u64 v[96:97], s[4:5], 0, v[182:183]
	v_pk_fma_f32 v[98:99], v[98:99], v[146:147], v[102:103]
	v_lshl_add_u64 v[96:97], v[96:97], 0, v[160:161]
	v_cvt_pk_bf16_f32 v93, v98, v99
	v_cvt_pk_bf16_f32 v94, v94, v95
; __device__ __forceinline__ unsigned cvt_pk_bf16(float lo, float hi) { unsigned r; asm volatile("v_cvt_pk_bf16_f32 %0, %1, %2" : "=v"(r) : "v"(lo), "v"(hi)); return r; }
; __device__ __forceinline__ float bflo(unsigned u) { return __uint_as_float(u << 16); }
; __device__ __forceinline__ float bfhi(unsigned u) { return __uint_as_float(u & 0xffff0000u); }
;     __device__ __forceinline__ void operator()(const f32x4 (&acc)[2][2][4][2], const Unit& u, int wr, int wc, int fr, int fq) const {
;     ...
;             for (int ai = 0; ai < 2; ++ai) { u32x4 xv[4][2];
; #pragma unroll
;                 for (int m = 0; m < 4; ++m)
; #pragma unroll
;                     for (int bj = 0; bj < 2; ++bj) xv[m][bj] = *(const u32x4*)(xin_b + (size_t)(row0 + ai * HALF + m * 16) * 2048 + col0 + bj * HALF);
; #pragma unroll
;                 for (int m = 0; m < 4; ++m) { const size_t off = (size_t)(row0 + ai * HALF + m * 16) * 2048 + col0;
; #pragma unroll
;                     for (int bj = 0; bj < 2; ++bj) { const u32x4 q = xv[m][bj];
;                         const f32x4 x0 = {bflo(q.x), bfhi(q.x), bflo(q.y), bfhi(q.y)}, x1 = {bflo(q.z), bfhi(q.z), bflo(q.w), bfhi(q.w)};
;                         const f32x4 v0 = x0 + g0[bj] * acc[ai][bj][m][0], v1 = x1 + g1[bj] * acc[ai][bj][m][1];
;                         u32x4 w; w.x = cvt_pk_bf16(v0[0], v0[1]); w.y = cvt_pk_bf16(v0[2], v0[3]); w.z = cvt_pk_bf16(v1[0], v1[1]); w.w = cvt_pk_bf16(v1[2], v1[3]);
;                         *(u32x4*)(out + off + bj * HALF) = w; } } }
	v_cvt_pk_bf16_f32 v95, v100, v101
	global_store_dwordx4 v[96:97], v[92:95], off
	v_lshlrev_b32_e32 v98, 16, v222
	v_and_b32_e32 v99, 0xffff0000, v222
	v_lshlrev_b32_e32 v92, 16, v220
	v_and_b32_e32 v93, 0xffff0000, v220
	v_lshlrev_b32_e32 v94, 16, v221
	v_and_b32_e32 v95, 0xffff0000, v221
	v_lshlrev_b32_e32 v100, 16, v223
	v_and_b32_e32 v101, 0xffff0000, v223
	v_pk_fma_f32 v[90:91], v[90:91], v[138:139], v[94:95]
	v_pk_fma_f32 v[88:89], v[88:89], v[136:137], v[92:93]
	v_pk_fma_f32 v[92:93], v[86:87], v[134:135], v[100:101]
	v_pk_fma_f32 v[86:87], v[84:85], v[132:133], v[98:99]
	v_cvt_pk_bf16_f32 v84, v88, v89
	v_cvt_pk_bf16_f32 v85, v90, v91
	v_lshlrev_b32_e32 v88, 16, v226
	v_cvt_pk_bf16_f32 v86, v86, v87
	v_cvt_pk_bf16_f32 v87, v92, v93
	global_store_dwordx4 v[96:97], v[84:87], off offset:256
	v_and_b32_e32 v89, 0xffff0000, v226
	v_lshlrev_b32_e32 v90, 16, v227
	v_lshlrev_b32_e32 v84, 16, v224
	v_and_b32_e32 v85, 0xffff0000, v224
	v_and_b32_e32 v91, 0xffff0000, v227
	v_pk_fma_f32 v[80:81], v[80:81], v[144:145], v[84:85]
	v_lshlrev_b32_e32 v86, 16, v225
	v_and_b32_e32 v87, 0xffff0000, v225
	v_pk_fma_f32 v[84:85], v[78:79], v[142:143], v[90:91]
	v_pk_fma_f32 v[78:79], v[76:77], v[140:141], v[88:89]
	v_cvt_pk_bf16_f32 v76, v80, v81
	v_lshl_add_u64 v[80:81], s[4:5], 0, v[166:167]
	v_pk_fma_f32 v[82:83], v[82:83], v[146:147], v[86:87]
	v_lshl_add_u64 v[98:99], v[80:81], 0, v[160:161]
	v_cvt_pk_bf16_f32 v77, v82, v83
	v_cvt_pk_bf16_f32 v78, v78, v79
	v_cvt_pk_bf16_f32 v79, v84, v85
	global_store_dwordx4 v[98:99], v[76:79], off
	v_lshlrev_b32_e32 v80, 16, v150
	v_and_b32_e32 v81, 0xffff0000, v150
	v_lshlrev_b32_e32 v76, 16, v148
	v_and_b32_e32 v77, 0xffff0000, v148
	v_lshlrev_b32_e32 v82, 16, v151
	v_and_b32_e32 v83, 0xffff0000, v151
	v_pk_fma_f32 v[72:73], v[72:73], v[136:137], v[76:77]
	v_lshl_add_u64 v[102:103], v[164:165], 0, s[20:21]
	v_lshlrev_b32_e32 v78, 16, v149
	v_and_b32_e32 v79, 0xffff0000, v149
	v_pk_fma_f32 v[76:77], v[70:71], v[134:135], v[82:83]
	v_pk_fma_f32 v[70:71], v[68:69], v[132:133], v[80:81]
	v_cvt_pk_bf16_f32 v68, v72, v73
	v_lshl_add_u64 v[72:73], v[162:163], 0, v[102:103]
	v_pk_fma_f32 v[74:75], v[74:75], v[138:139], v[78:79]
	s_mov_b64 s[20:21], 0x90000
	v_cvt_pk_bf16_f32 v69, v74, v75
	v_cvt_pk_bf16_f32 v70, v70, v71
	v_cvt_pk_bf16_f32 v71, v76, v77
	global_load_dwordx4 v[78:81], v[72:73], off
	global_load_dwordx4 v[82:85], v[72:73], off offset:256
	v_lshl_add_u64 v[104:105], v[164:165], 0, s[20:21]
	v_lshl_add_u64 v[72:73], v[162:163], 0, v[104:105]
	global_load_dwordx4 v[86:89], v[72:73], off
	global_load_dwordx4 v[90:93], v[72:73], off offset:256
	s_mov_b64 s[20:21], 0xa0000
	v_lshl_add_u64 v[106:107], v[164:165], 0, s[20:21]
	v_lshl_add_u64 v[72:73], v[162:163], 0, v[106:107]
	global_load_dwordx4 v[94:97], v[72:73], off
	s_mov_b64 s[20:21], 0xb0000
	global_store_dwordx4 v[98:99], v[68:71], off offset:256
	global_load_dwordx4 v[98:101], v[72:73], off offset:256
	v_lshl_add_u64 v[76:77], v[164:165], 0, s[20:21]
	v_lshl_add_u64 v[68:69], v[162:163], 0, v[76:77]
	global_load_dwordx4 v[72:75], v[68:69], off
	s_nop 0
	global_load_dwordx4 v[68:71], v[68:69], off offset:256
	s_mov_b64 s[20:21], -1
	s_waitcnt vmcnt(0) lgkmcnt(0)
; __device__ __forceinline__ unsigned cvt_pk_bf16(float lo, float hi) { unsigned r; asm volatile("v_cvt_pk_bf16_f32 %0, %1, %2" : "=v"(r) : "v"(lo), "v"(hi)); return r; }
; __device__ __forceinline__ float bflo(unsigned u) { return __uint_as_float(u << 16); }
; __device__ __forceinline__ float bfhi(unsigned u) { return __uint_as_float(u & 0xffff0000u); }
;     __device__ __forceinline__ void operator()(const f32x4 (&acc)[2][2][4][2], const Unit& u, int wr, int wc, int fr, int fq) const {
;     ...
;                 for (int m = 0; m < 4; ++m) { const size_t off = (size_t)(row0 + ai * HALF + m * 16) * 2048 + col0;
; #pragma unroll
;                     for (int bj = 0; bj < 2; ++bj) { const u32x4 q = xv[m][bj];
;                         const f32x4 x0 = {bflo(q.x), bfhi(q.x), bflo(q.y), bfhi(q.y)}, x1 = {bflo(q.z), bfhi(q.z), bflo(q.w), bfhi(q.w)};
;                         const f32x4 v0 = x0 + g0[bj] * acc[ai][bj][m][0], v1 = x1 + g1[bj] * acc[ai][bj][m][1];
;                         u32x4 w; w.x = cvt_pk_bf16(v0[0], v0[1]); w.y = cvt_pk_bf16(v0[2], v0[3]); w.z = cvt_pk_bf16(v1[0], v1[1]); w.w = cvt_pk_bf16(v1[2], v1[3]);
;                         *(u32x4*)(out + off + bj * HALF) = w; } } }
	v_lshlrev_b32_e32 v108, 16, v78
	v_and_b32_e32 v109, 0xffff0000, v78
	v_lshlrev_b32_e32 v78, 16, v79
	v_and_b32_e32 v79, 0xffff0000, v79
	v_lshlrev_b32_e32 v110, 16, v80
	v_and_b32_e32 v111, 0xffff0000, v80
	v_lshlrev_b32_e32 v80, 16, v81
	v_and_b32_e32 v81, 0xffff0000, v81
	v_pk_fma_f32 v[64:65], v[64:65], v[144:145], v[108:109]
	v_pk_fma_f32 v[66:67], v[66:67], v[146:147], v[78:79]
	v_pk_fma_f32 v[78:79], v[62:63], v[142:143], v[80:81]
	v_pk_fma_f32 v[62:63], v[60:61], v[140:141], v[110:111]
	v_cvt_pk_bf16_f32 v60, v64, v65
	v_lshl_add_u64 v[64:65], s[4:5], 0, v[102:103]
	v_cvt_pk_bf16_f32 v61, v66, v67
	v_cvt_pk_bf16_f32 v62, v62, v63
	v_cvt_pk_bf16_f32 v63, v78, v79
	v_lshl_add_u64 v[64:65], v[64:65], 0, v[160:161]
	global_store_dwordx4 v[64:65], v[60:63], off
	v_lshlrev_b32_e32 v66, 16, v84
	v_and_b32_e32 v67, 0xffff0000, v84
	v_lshlrev_b32_e32 v60, 16, v82
	v_and_b32_e32 v61, 0xffff0000, v82
	v_lshlrev_b32_e32 v62, 16, v83
	v_and_b32_e32 v63, 0xffff0000, v83
	v_lshlrev_b32_e32 v78, 16, v85
	v_and_b32_e32 v79, 0xffff0000, v85
	v_pk_fma_f32 v[58:59], v[58:59], v[138:139], v[62:63]
	v_pk_fma_f32 v[56:57], v[56:57], v[136:137], v[60:61]
	v_pk_fma_f32 v[60:61], v[54:55], v[134:135], v[78:79]
	v_pk_fma_f32 v[54:55], v[52:53], v[132:133], v[66:67]
	v_cvt_pk_bf16_f32 v52, v56, v57
	v_cvt_pk_bf16_f32 v53, v58, v59
	v_lshlrev_b32_e32 v56, 16, v88
	v_cvt_pk_bf16_f32 v54, v54, v55
	v_cvt_pk_bf16_f32 v55, v60, v61
	global_store_dwordx4 v[64:65], v[52:55], off offset:256
	v_and_b32_e32 v57, 0xffff0000, v88
	v_lshlrev_b32_e32 v58, 16, v89
	v_lshlrev_b32_e32 v52, 16, v86
	v_and_b32_e32 v53, 0xffff0000, v86
	v_and_b32_e32 v59, 0xffff0000, v89
	v_pk_fma_f32 v[48:49], v[48:49], v[144:145], v[52:53]
	v_lshlrev_b32_e32 v54, 16, v87
	v_and_b32_e32 v55, 0xffff0000, v87
	v_pk_fma_f32 v[52:53], v[46:47], v[142:143], v[58:59]
	v_pk_fma_f32 v[46:47], v[44:45], v[140:141], v[56:57]
	v_cvt_pk_bf16_f32 v44, v48, v49
	v_lshl_add_u64 v[48:49], s[4:5], 0, v[104:105]
	v_pk_fma_f32 v[50:51], v[50:51], v[146:147], v[54:55]
	v_lshl_add_u64 v[48:49], v[48:49], 0, v[160:161]
	v_cvt_pk_bf16_f32 v45, v50, v51
	v_cvt_pk_bf16_f32 v46, v46, v47
	v_cvt_pk_bf16_f32 v47, v52, v53
	global_store_dwordx4 v[48:49], v[44:47], off
	v_lshlrev_b32_e32 v50, 16, v92
	v_and_b32_e32 v51, 0xffff0000, v92
	v_lshlrev_b32_e32 v44, 16, v90
	v_and_b32_e32 v45, 0xffff0000, v90
	v_lshlrev_b32_e32 v46, 16, v91
	v_and_b32_e32 v47, 0xffff0000, v91
	v_lshlrev_b32_e32 v52, 16, v93
	v_and_b32_e32 v53, 0xffff0000, v93
	v_pk_fma_f32 v[42:43], v[42:43], v[138:139], v[46:47]
	v_pk_fma_f32 v[40:41], v[40:41], v[136:137], v[44:45]
	v_pk_fma_f32 v[44:45], v[38:39], v[134:135], v[52:53]
	v_pk_fma_f32 v[38:39], v[36:37], v[132:133], v[50:51]
	v_cvt_pk_bf16_f32 v36, v40, v41
	v_cvt_pk_bf16_f32 v37, v42, v43
	v_lshlrev_b32_e32 v40, 16, v96
	v_cvt_pk_bf16_f32 v38, v38, v39
	v_cvt_pk_bf16_f32 v39, v44, v45
	global_store_dwordx4 v[48:49], v[36:39], off offset:256
	v_and_b32_e32 v41, 0xffff0000, v96
	v_lshlrev_b32_e32 v42, 16, v97
	v_lshlrev_b32_e32 v36, 16, v94
	v_and_b32_e32 v37, 0xffff0000, v94
	v_and_b32_e32 v43, 0xffff0000, v97
	v_pk_fma_f32 v[32:33], v[32:33], v[144:145], v[36:37]
	v_lshlrev_b32_e32 v38, 16, v95
	v_and_b32_e32 v39, 0xffff0000, v95
	v_pk_fma_f32 v[36:37], v[30:31], v[142:143], v[42:43]
	v_pk_fma_f32 v[30:31], v[28:29], v[140:141], v[40:41]
	v_cvt_pk_bf16_f32 v28, v32, v33
	v_lshl_add_u64 v[32:33], s[4:5], 0, v[106:107]
	v_pk_fma_f32 v[34:35], v[34:35], v[146:147], v[38:39]
	v_lshl_add_u64 v[32:33], v[32:33], 0, v[160:161]
	v_cvt_pk_bf16_f32 v29, v34, v35
	v_cvt_pk_bf16_f32 v30, v30, v31
	v_cvt_pk_bf16_f32 v31, v36, v37
	global_store_dwordx4 v[32:33], v[28:31], off
	v_lshlrev_b32_e32 v34, 16, v100
	v_and_b32_e32 v35, 0xffff0000, v100
	v_lshlrev_b32_e32 v28, 16, v98
	v_and_b32_e32 v29, 0xffff0000, v98
	v_lshlrev_b32_e32 v30, 16, v99
	v_and_b32_e32 v31, 0xffff0000, v99
	v_lshlrev_b32_e32 v36, 16, v101
	v_and_b32_e32 v37, 0xffff0000, v101
	v_pk_fma_f32 v[26:27], v[26:27], v[138:139], v[30:31]
	v_pk_fma_f32 v[24:25], v[24:25], v[136:137], v[28:29]
	v_pk_fma_f32 v[28:29], v[22:23], v[134:135], v[36:37]
	v_pk_fma_f32 v[22:23], v[20:21], v[132:133], v[34:35]
	v_cvt_pk_bf16_f32 v20, v24, v25
	v_cvt_pk_bf16_f32 v21, v26, v27
	v_lshlrev_b32_e32 v24, 16, v74
	v_cvt_pk_bf16_f32 v22, v22, v23
	v_cvt_pk_bf16_f32 v23, v28, v29
	global_store_dwordx4 v[32:33], v[20:23], off offset:256
	v_and_b32_e32 v25, 0xffff0000, v74
	v_lshlrev_b32_e32 v26, 16, v75
	v_lshlrev_b32_e32 v20, 16, v72
	v_and_b32_e32 v21, 0xffff0000, v72
	v_and_b32_e32 v27, 0xffff0000, v75
	v_pk_fma_f32 v[16:17], v[16:17], v[144:145], v[20:21]
	v_lshlrev_b32_e32 v22, 16, v73
	v_and_b32_e32 v23, 0xffff0000, v73
	v_pk_fma_f32 v[20:21], v[14:15], v[142:143], v[26:27]
	v_pk_fma_f32 v[14:15], v[12:13], v[140:141], v[24:25]
	v_cvt_pk_bf16_f32 v12, v16, v17
	v_lshl_add_u64 v[16:17], s[4:5], 0, v[76:77]
	v_pk_fma_f32 v[18:19], v[18:19], v[146:147], v[22:23]
	v_lshl_add_u64 v[16:17], v[16:17], 0, v[160:161]
	v_cvt_pk_bf16_f32 v13, v18, v19
	v_cvt_pk_bf16_f32 v14, v14, v15
	v_cvt_pk_bf16_f32 v15, v20, v21
	global_store_dwordx4 v[16:17], v[12:15], off
	v_lshlrev_b32_e32 v18, 16, v70
	v_and_b32_e32 v19, 0xffff0000, v70
	v_lshlrev_b32_e32 v12, 16, v68
	v_and_b32_e32 v13, 0xffff0000, v68
	v_lshlrev_b32_e32 v20, 16, v71
	v_and_b32_e32 v21, 0xffff0000, v71
	v_lshlrev_b32_e32 v14, 16, v69
	v_and_b32_e32 v15, 0xffff0000, v69
	v_pk_fma_f32 v[8:9], v[8:9], v[136:137], v[12:13]
	v_pk_fma_f32 v[12:13], v[6:7], v[134:135], v[20:21]
	v_pk_fma_f32 v[6:7], v[4:5], v[132:133], v[18:19]
	v_pk_fma_f32 v[10:11], v[10:11], v[138:139], v[14:15]
	v_cvt_pk_bf16_f32 v4, v8, v9
	s_nop 0
	v_cvt_pk_bf16_f32 v5, v10, v11
	v_cvt_pk_bf16_f32 v6, v6, v7
	v_cvt_pk_bf16_f32 v7, v12, v13
	global_store_dwordx4 v[16:17], v[4:7], off offset:256
	s_cbranch_vccnz .LBB0_851
	s_andn2_b64 vcc, exec, s[0:1]
	s_cbranch_vccnz .LBB0_850
	s_barrier
	s_branch .LBB0_850
